# hoisted residual-row loads in w_o/w_down epilogues (renamed regs, counted vmcnt) + split packed f32 ops there
# speedup vs baseline: 1.3761x; 1.3761x over previous
; #define LAS __attribute__((address_space(3)))
; __device__ __forceinline__ void row_stats_to_lds(const float* SP, int pm, LAS f2v* T, int tid) {
;     if (tid < 256) { const f32x4* p = (const f32x4*)(SP + (size_t)(pm * 256 + tid) * 32); float s1 = 0.f, s2 = 0.f;
; #pragma unroll
;         for (int k = 0; k < 8; ++k) { const f32x4 v = p[k]; s1 += v.x + v.z; s2 += v.y + v.w; }
;         const float mu = s1 * (1.f / DM), var = s2 * (1.f / DM) - mu * mu;
;         T[tid] = (f2v){mu, 1.f / sqrtf(var + LN_EPS)}; }
;     asm volatile("s_waitcnt lgkmcnt(0)" ::: "memory"); __builtin_amdgcn_s_barrier(); asm volatile("" ::: "memory");
; }
;     __device__ __forceinline__ void operator()(pg8::f32x4 (&acc)[2][2][4][2], const pg8::Unit& u, int wr, int wc, int fr, int fq) const {
;     ...
;         row_stats_to_lds(SPin, u.pm, T, (wr * 4 + wc) * 64 + fq * 16 + fr);
;         const int cb = u.pn * 256 + wc * 32 + 8 * fq;
;         f4 gv[2][2], bv[2][2];
; #pragma unroll
;         for (int bj = 0; bj < 2; ++bj)
; #pragma unroll
;             for (int n = 0; n < 2; ++n) { gv[bj][n] = *(const f4*)(g + cb + 128 * bj + 4 * n); bv[bj][n] = *(const f4*)(b + cb + 128 * bj + 4 * n); }
; #pragma unroll
;         for (int ai = 0; ai < 2; ++ai)
; #pragma unroll
;             for (int m = 0; m < 4; ++m) { const int rl = ai * 128 + wr * 64 + m * 16 + fr; const f2v st = T[rl]; const float r = st.y, rm = -st.x * st.y;
;                 const size_t off = (size_t)(u.pm * 256 + rl) * DM + cb; float s1 = 0.f, s2 = 0.f;
; #pragma unroll
;                 for (int bj = 0; bj < 2; ++bj) { f4 pre[2]; float xin[8]; unpack8(*(const u32x4*)(XB + off + 128 * bj), xin);
.LBB0_580:
	s_lshl_b32 s0, s48, 8
	s_and_saveexec_b64 s[36:37], s[42:43]
	s_cbranch_execz .LBB0_582
	v_add_u32_e32 v36, s0, v182
	v_ashrrev_i32_e32 v37, 31, v36
	v_lshlrev_b64 v[36:37], 7, v[36:37]
	v_lshl_add_u64 v[68:69], s[22:23], 0, v[36:37]
	global_load_dwordx4 v[36:39], v[68:69], off
	global_load_dwordx4 v[40:43], v[68:69], off offset:16
	global_load_dwordx4 v[44:47], v[68:69], off offset:32
	global_load_dwordx4 v[48:51], v[68:69], off offset:48
	global_load_dwordx4 v[56:59], v[68:69], off offset:64
	global_load_dwordx4 v[60:63], v[68:69], off offset:80
	global_load_dwordx4 v[64:67], v[68:69], off offset:96
	s_nop 0
	global_load_dwordx4 v[68:71], v[68:69], off offset:112
	s_mov_b32 s4, 0x3a800000
	s_waitcnt vmcnt(0)
	v_add_f32_e64 v36, v36, v38
	v_add_f32_e64 v37, v37, v39
	v_add_f32_e64 v38, v40, v42
	v_add_f32_e64 v39, v41, v43
	v_add_f32_e64 v36, v36, 0
	v_add_f32_e64 v37, v37, 0
	v_add_f32_e64 v40, v44, v46
	v_add_f32_e64 v41, v45, v47
	v_add_f32_e64 v36, v36, v38
	v_add_f32_e64 v37, v37, v39
	v_add_f32_e64 v42, v48, v50
	v_add_f32_e64 v43, v49, v51
	v_add_f32_e64 v36, v36, v40
	v_add_f32_e64 v37, v37, v41
	v_add_f32_e64 v44, v56, v58
	v_add_f32_e64 v45, v57, v59
	v_add_f32_e64 v36, v36, v42
	v_add_f32_e64 v37, v37, v43
	v_add_f32_e64 v46, v60, v62
	v_add_f32_e64 v47, v61, v63
	v_add_f32_e64 v36, v36, v44
	v_add_f32_e64 v37, v37, v45
	v_add_f32_e64 v48, v64, v66
	v_add_f32_e64 v49, v65, v67
	v_add_f32_e64 v36, v36, v46
	v_add_f32_e64 v37, v37, v47
	v_add_f32_e64 v50, v68, v70
	v_add_f32_e64 v51, v69, v71
	v_add_f32_e64 v36, v36, v48
	v_add_f32_e64 v37, v37, v49
	s_nop 0
	v_add_f32_e64 v36, v36, v50
	v_add_f32_e64 v37, v37, v51
	s_nop 0
	v_mul_f32_e64 v36, v36, s4
	v_mul_f32_e64 v37, v37, s4
	s_nop 0
	v_fma_f32 v37, -v36, v36, v37
	v_add_f32_e32 v37, 0x358637bd, v37
	v_mul_f32_e32 v38, 0x4f800000, v37
	v_cmp_gt_f32_e32 vcc, s11, v37
	s_nop 1
	v_cndmask_b32_e32 v37, v37, v38, vcc
	v_sqrt_f32_e32 v38, v37
	s_nop 0
	v_add_u32_e32 v39, -1, v38
	v_add_u32_e32 v40, 1, v38
	v_fma_f32 v41, -v39, v38, v37
	v_fma_f32 v42, -v40, v38, v37
	v_cmp_ge_f32_e64 s[48:49], 0, v41
	s_nop 1
	v_cndmask_b32_e64 v38, v38, v39, s[48:49]
	v_cmp_lt_f32_e64 s[48:49], 0, v42
	s_nop 1
	v_cndmask_b32_e64 v38, v38, v40, s[48:49]
	v_mul_f32_e32 v39, 0x37800000, v38
	v_cndmask_b32_e32 v38, v38, v39, vcc
	v_cmp_class_f32_e32 vcc, v37, v231
	s_nop 1
	v_cndmask_b32_e32 v37, v38, v37, vcc
	v_div_scale_f32 v38, s[4:5], v37, v37, 1.0
	v_rcp_f32_e32 v39, v38
	v_div_scale_f32 v40, vcc, 1.0, v37, 1.0
	v_fma_f32 v41, -v38, v39, 1.0
	v_fmac_f32_e32 v39, v41, v39
	v_mul_f32_e32 v41, v40, v39
	v_fma_f32 v42, -v38, v41, v40
	v_fmac_f32_e32 v41, v42, v39
	v_fma_f32 v38, -v38, v41, v40
	v_div_fmas_f32 v38, v38, v39, v41
	v_div_fixup_f32 v37, v38, v37, 1.0
	ds_write_b64 v196, v[36:37]
.LBB0_582:
	s_or_b64 exec, exec, s[36:37]
	v_add_u32_e32 v172, s0, v179
	v_lshl_or_b32 v170, s68, 8, v181
	v_ashrrev_i32_e32 v173, 31, v172
	v_ashrrev_i32_e32 v171, 31, v170
	v_lshlrev_b64 v[174:175], 11, v[172:173]
	v_lshlrev_b64 v[36:37], 2, v[170:171]
	v_lshl_add_u64 v[174:175], s[18:19], 0, v[174:175]
	s_waitcnt lgkmcnt(0)
	s_barrier
	v_lshl_add_u64 v[40:41], s[12:13], 0, v[36:37]
	v_lshl_add_u64 v[48:49], s[14:15], 0, v[36:37]
	v_lshl_add_u64 v[174:175], v[170:171], 1, v[174:175]
	global_load_dwordx4 v[56:59], v[40:41], off offset:16
	global_load_dwordx4 v[64:67], v[40:41], off
	global_load_dwordx4 v[60:63], v[48:49], off offset:16
	global_load_dwordx4 v[68:71], v[48:49], off
	global_load_dwordx4 v[36:39], v[40:41], off offset:528
	global_load_dwordx4 v[44:47], v[40:41], off offset:512
	s_nop 0
	global_load_dwordx4 v[40:43], v[48:49], off offset:528
	s_nop 0
	global_load_dwordx4 v[48:51], v[48:49], off offset:512
	ds_read_b64 v[176:177], v197
	v_add_u32_e32 v218, s0, v179
	v_ashrrev_i32_e32 v219, 31, v218
	v_lshlrev_b64 v[220:221], 11, v[218:219]
	v_lshl_add_u64 v[220:221], s[18:19], 0, v[220:221]
	v_lshl_add_u64 v[220:221], v[170:171], 1, v[220:221]
	global_load_dwordx4 v[214:217], v[220:221], off
	global_load_dwordx4 v[218:221], v[220:221], off offset:256
	v_add_u32_e32 v226, s0, v183
	v_ashrrev_i32_e32 v227, 31, v226
	v_lshlrev_b64 v[228:229], 11, v[226:227]
	v_lshl_add_u64 v[228:229], s[18:19], 0, v[228:229]
	v_lshl_add_u64 v[228:229], v[170:171], 1, v[228:229]
	global_load_dwordx4 v[222:225], v[228:229], off
	global_load_dwordx4 v[226:229], v[228:229], off offset:256
	v_add_u32_e32 v242, s0, v184
	v_ashrrev_i32_e32 v243, 31, v242
	v_lshlrev_b64 v[244:245], 11, v[242:243]
	v_lshl_add_u64 v[244:245], s[18:19], 0, v[244:245]
	v_lshl_add_u64 v[244:245], v[170:171], 1, v[244:245]
	global_load_dwordx4 v[238:241], v[244:245], off
	global_load_dwordx4 v[242:245], v[244:245], off offset:256
	s_lshl_b32 s1, s68, 3
	s_or_b32 s36, s1, s64
	s_ashr_i32 s37, s36, 31
	s_waitcnt lgkmcnt(0)
	v_mul_f32_e64 v178, v177, -v176
	s_waitcnt vmcnt(0)
; __device__ __forceinline__ unsigned pk(float lo, float hi) { return pg8::cvt_pk_bf16(lo, hi); }
; template <int O> __device__ __forceinline__ float swz_xor(float v) { return __int_as_float(__builtin_amdgcn_ds_swizzle(__float_as_int(v), (O << 10) | 0x1f)); }
;     __device__ __forceinline__ void operator()(pg8::f32x4 (&acc)[2][2][4][2], const pg8::Unit& u, int wr, int wc, int fr, int fq) const {
;     ...
;             for (int m = 0; m < 4; ++m) { const int rl = ai * 128 + wr * 64 + m * 16 + fr; const f2v st = T[rl]; const float r = st.y, rm = -st.x * st.y;
;                 const size_t off = (size_t)(u.pm * 256 + rl) * DM + cb; float s1 = 0.f, s2 = 0.f;
; #pragma unroll
;                 for (int bj = 0; bj < 2; ++bj) { f4 pre[2]; float xin[8]; unpack8(*(const u32x4*)(XB + off + 128 * bj), xin);
; #pragma unroll
;                     for (int n = 0; n < 2; ++n) { const f4 v = {xin[4 * n], xin[4 * n + 1], xin[4 * n + 2], xin[4 * n + 3]}; const f4 xr = (v * r + rm) * gv[bj][n] + bv[bj][n];
;                         pre[n] = xr * alpha + acc[ai][bj][m][n]; if (X) *(f4*)(X + off + 128 * bj + 4 * n) = pre[n];
;                         s1 += (pre[n][0] + pre[n][1]) + (pre[n][2] + pre[n][3]); s2 += (pre[n][0] * pre[n][0] + pre[n][1] * pre[n][1]) + (pre[n][2] * pre[n][2] + pre[n][3] * pre[n][3]); }
;                     u32x4 w; w.x = pk(pre[0][0], pre[0][1]); w.y = pk(pre[0][2], pre[0][3]); w.z = pk(pre[1][0], pre[1][1]); w.w = pk(pre[1][2], pre[1][3]);
;                     if (!X) *(u32x4*)(XB + off + 128 * bj) = w; }
;                 s1 += swz_xor<16>(s1); s2 += swz_xor<16>(s2);
;                 { auto r1 = __builtin_amdgcn_permlane32_swap(__float_as_uint(s1), __float_as_uint(s1), false, false); s1 = __uint_as_float(r1[0]) + __uint_as_float(r1[1]);
;                   auto r2 = __builtin_amdgcn_permlane32_swap(__float_as_uint(s2), __float_as_uint(s2), false, false); s2 = __uint_as_float(r2[0]) + __uint_as_float(r2[1]); }
;                 if (fq == 0) *(f2v*)(SPout + (size_t)(u.pm * 256 + rl) * 32 + (u.pn * 4 + wc) * 2) = (f2v){s1, s2};
	v_lshlrev_b32_e32 v210, 16, v214
	v_and_b32_e32 v211, 0xffff0000, v214
	v_lshlrev_b32_e32 v206, 16, v215
	v_and_b32_e32 v207, 0xffff0000, v215
	v_fma_f32 v210, v177, v210, v178
	v_fma_f32 v211, v177, v211, v178
	v_fma_f32 v206, v177, v206, v178
	v_fma_f32 v207, v177, v207, v178
	v_fma_f32 v210, v64, v210, v68
	v_fma_f32 v211, v65, v211, v69
	v_fma_f32 v206, v66, v206, v70
	v_fma_f32 v207, v67, v207, v71
	v_fma_f32 v156, v210, s10, v156
	v_fma_f32 v157, v211, s10, v157
	v_fma_f32 v158, v206, s10, v158
	v_fma_f32 v159, v207, s10, v159
	v_add_f32_e32 v206, v156, v157
	v_add_f32_e32 v207, v159, v158
	v_add_f32_e32 v206, v206, v207
	v_add_f32_e32 v210, 0, v206
	v_mul_f32_e32 v206, v157, v157
	v_mul_f32_e32 v207, v158, v158
	v_lshlrev_b32_e32 v212, 16, v216
	v_and_b32_e32 v213, 0xffff0000, v216
	v_lshlrev_b32_e32 v208, 16, v217
	v_and_b32_e32 v209, 0xffff0000, v217
	v_fmac_f32_e32 v206, v156, v156
	v_fmac_f32_e32 v207, v159, v159
	v_add_f32_e32 v211, v206, v207
	v_fma_f32 v206, v177, v212, v178
	v_fma_f32 v207, v177, v213, v178
	v_fma_f32 v208, v177, v208, v178
	v_fma_f32 v209, v177, v209, v178
	v_fma_f32 v206, v56, v206, v60
	v_fma_f32 v207, v57, v207, v61
	v_fma_f32 v208, v58, v208, v62
	v_fma_f32 v209, v59, v209, v63
	s_nop 0
	v_fma_f32 v208, v208, s10, v154
	v_fma_f32 v209, v209, s10, v155
	v_fma_f32 v154, v206, s10, v152
	v_fma_f32 v155, v207, s10, v153
	v_add_f32_e32 v153, v209, v208
	v_add_f32_e32 v152, v154, v155
	v_add_f32_e32 v152, v152, v153
	v_add_f32_e32 v206, v152, v210
	v_mul_f32_e32 v152, v155, v155
	v_mul_f32_e32 v153, v208, v208
	v_fmac_f32_e32 v152, v154, v154
	v_fmac_f32_e32 v153, v209, v209
	v_add_f32_e32 v152, v152, v153
	v_add_f32_e32 v207, v211, v152
	v_cvt_pk_bf16_f32 v152, v156, v157
	v_cvt_pk_bf16_f32 v153, v158, v159
	v_cvt_pk_bf16_f32 v154, v154, v155
	v_cvt_pk_bf16_f32 v155, v208, v209
	global_store_dwordx4 v[174:175], v[152:155], off
	s_waitcnt vmcnt(5)
	v_lshlrev_b32_e32 v156, 16, v218
	v_and_b32_e32 v157, 0xffff0000, v218
	v_lshlrev_b32_e32 v152, 16, v219
	v_and_b32_e32 v153, 0xffff0000, v219
	v_fma_f32 v156, v177, v156, v178
	v_fma_f32 v157, v177, v157, v178
	v_fma_f32 v152, v177, v152, v178
	v_fma_f32 v153, v177, v153, v178
	v_fma_f32 v156, v44, v156, v48
	v_fma_f32 v157, v45, v157, v49
	v_fma_f32 v152, v46, v152, v50
	v_fma_f32 v153, v47, v153, v51
	v_fma_f32 v148, v156, s10, v148
	v_fma_f32 v149, v157, s10, v149
	v_fma_f32 v150, v152, s10, v150
	v_fma_f32 v151, v153, s10, v151
	v_add_f32_e32 v152, v148, v149
	v_add_f32_e32 v153, v151, v150
	v_add_f32_e32 v152, v152, v153
	v_add_f32_e32 v156, v206, v152
	v_mul_f32_e32 v152, v149, v149
	v_mul_f32_e32 v153, v150, v150
	v_fmac_f32_e32 v152, v148, v148
	v_fmac_f32_e32 v153, v151, v151
	v_lshlrev_b32_e32 v158, 16, v220
	v_and_b32_e32 v159, 0xffff0000, v220
	v_lshlrev_b32_e32 v154, 16, v221
	v_and_b32_e32 v155, 0xffff0000, v221
	v_add_u32_e32 v218, s0, v185
	v_ashrrev_i32_e32 v219, 31, v218
	v_lshlrev_b64 v[220:221], 11, v[218:219]
	v_lshl_add_u64 v[220:221], s[18:19], 0, v[220:221]
	v_lshl_add_u64 v[220:221], v[170:171], 1, v[220:221]
	global_load_dwordx4 v[214:217], v[220:221], off
	global_load_dwordx4 v[218:221], v[220:221], off offset:256
	v_add_f32_e32 v152, v152, v153
	v_add_f32_e32 v157, v207, v152
	v_fma_f32 v152, v177, v158, v178
	v_fma_f32 v153, v177, v159, v178
	v_fma_f32 v154, v177, v154, v178
	v_fma_f32 v155, v177, v155, v178
	v_fma_f32 v152, v36, v152, v40
	v_fma_f32 v153, v37, v153, v41
	v_fma_f32 v154, v38, v154, v42
	v_fma_f32 v155, v39, v155, v43
	s_nop 0
	v_fma_f32 v154, v154, s10, v146
	v_fma_f32 v155, v155, s10, v147
	v_fma_f32 v146, v152, s10, v144
	v_fma_f32 v147, v153, s10, v145
	v_add_f32_e32 v145, v155, v154
	v_add_f32_e32 v144, v146, v147
	v_add_f32_e32 v144, v144, v145
	v_add_f32_e32 v152, v144, v156
	v_mul_f32_e32 v144, v147, v147
	v_mul_f32_e32 v145, v154, v154
	v_fmac_f32_e32 v144, v146, v146
	v_fmac_f32_e32 v145, v155, v155
	v_add_f32_e32 v144, v144, v145
	v_add_f32_e32 v153, v144, v157
	v_cvt_pk_bf16_f32 v144, v148, v149
	v_cvt_pk_bf16_f32 v145, v150, v151
	v_cvt_pk_bf16_f32 v146, v146, v147
	v_cvt_pk_bf16_f32 v147, v154, v155
	global_store_dwordx4 v[174:175], v[144:147], off offset:256
	ds_swizzle_b32 v144, v152 offset:swizzle(SWAP,16)
	ds_swizzle_b32 v145, v153 offset:swizzle(SWAP,16)
	s_waitcnt lgkmcnt(1)
	v_add_f32_e32 v144, v152, v144
	s_waitcnt lgkmcnt(0)
	v_add_f32_e32 v145, v153, v145
	v_mov_b32_e32 v146, v144
	v_mov_b32_e32 v147, v145
	s_nop 0
	v_permlane32_swap_b32_e32 v144, v146
	v_permlane32_swap_b32_e32 v145, v147
	s_and_saveexec_b64 s[4:5], s[44:45]
	s_cbranch_execz .LBB0_584
	v_add_f32_e64 v144, v144, v146
	v_add_f32_e64 v145, v145, v147
	v_lshlrev_b64 v[146:147], 7, v[172:173]
	v_lshl_add_u64 v[146:147], s[20:21], 0, v[146:147]
	v_lshl_add_u64 v[146:147], s[36:37], 2, v[146:147]
	global_store_dwordx2 v[146:147], v[144:145], off
; __device__ __forceinline__ unsigned pk(float lo, float hi) { return pg8::cvt_pk_bf16(lo, hi); }
; template <int O> __device__ __forceinline__ float swz_xor(float v) { return __int_as_float(__builtin_amdgcn_ds_swizzle(__float_as_int(v), (O << 10) | 0x1f)); }
;     __device__ __forceinline__ void operator()(pg8::f32x4 (&acc)[2][2][4][2], const pg8::Unit& u, int wr, int wc, int fr, int fq) const {
;     ...
;             for (int m = 0; m < 4; ++m) { const int rl = ai * 128 + wr * 64 + m * 16 + fr; const f2v st = T[rl]; const float r = st.y, rm = -st.x * st.y;
;                 const size_t off = (size_t)(u.pm * 256 + rl) * DM + cb; float s1 = 0.f, s2 = 0.f;
; #pragma unroll
;                 for (int bj = 0; bj < 2; ++bj) { f4 pre[2]; float xin[8]; unpack8(*(const u32x4*)(XB + off + 128 * bj), xin);
; #pragma unroll
;                     for (int n = 0; n < 2; ++n) { const f4 v = {xin[4 * n], xin[4 * n + 1], xin[4 * n + 2], xin[4 * n + 3]}; const f4 xr = (v * r + rm) * gv[bj][n] + bv[bj][n];
;                         pre[n] = xr * alpha + acc[ai][bj][m][n]; if (X) *(f4*)(X + off + 128 * bj + 4 * n) = pre[n];
;                         s1 += (pre[n][0] + pre[n][1]) + (pre[n][2] + pre[n][3]); s2 += (pre[n][0] * pre[n][0] + pre[n][1] * pre[n][1]) + (pre[n][2] * pre[n][2] + pre[n][3] * pre[n][3]); }
;                     u32x4 w; w.x = pk(pre[0][0], pre[0][1]); w.y = pk(pre[0][2], pre[0][3]); w.z = pk(pre[1][0], pre[1][1]); w.w = pk(pre[1][2], pre[1][3]);
;                     if (!X) *(u32x4*)(XB + off + 128 * bj) = w; }
;                 s1 += swz_xor<16>(s1); s2 += swz_xor<16>(s2);
;                 { auto r1 = __builtin_amdgcn_permlane32_swap(__float_as_uint(s1), __float_as_uint(s1), false, false); s1 = __uint_as_float(r1[0]) + __uint_as_float(r1[1]);
;                   auto r2 = __builtin_amdgcn_permlane32_swap(__float_as_uint(s2), __float_as_uint(s2), false, false); s2 = __uint_as_float(r2[0]) + __uint_as_float(r2[1]); }
;                 if (fq == 0) *(f2v*)(SPout + (size_t)(u.pm * 256 + rl) * 32 + (u.pn * 4 + wc) * 2) = (f2v){s1, s2};
.LBB0_584:
	s_or_b64 exec, exec, s[4:5]
	v_add_u32_e32 v144, s0, v183
	v_ashrrev_i32_e32 v145, 31, v144
	v_lshlrev_b64 v[146:147], 11, v[144:145]
	v_lshl_add_u64 v[146:147], s[18:19], 0, v[146:147]
	v_lshl_add_u64 v[146:147], v[170:171], 1, v[146:147]
	ds_read_b64 v[148:149], v198
	s_waitcnt lgkmcnt(0)
	v_mul_f32_e64 v150, v149, -v148
	s_waitcnt vmcnt(7)
	v_lshlrev_b32_e32 v156, 16, v222
	v_and_b32_e32 v157, 0xffff0000, v222
	v_lshlrev_b32_e32 v152, 16, v223
	v_and_b32_e32 v153, 0xffff0000, v223
	v_fma_f32 v152, v149, v152, v150
	v_fma_f32 v153, v149, v153, v150
	v_fma_f32 v156, v149, v156, v150
	v_fma_f32 v157, v149, v157, v150
	v_fma_f32 v152, v66, v152, v70
	v_fma_f32 v153, v67, v153, v71
	v_fma_f32 v156, v64, v156, v68
	v_fma_f32 v157, v65, v157, v69
	v_fma_f32 v142, v152, s10, v142
	v_fma_f32 v143, v153, s10, v143
	v_fma_f32 v140, v156, s10, v140
	v_fma_f32 v141, v157, s10, v141
	v_add_f32_e32 v152, v143, v142
	v_add_f32_e32 v151, v140, v141
	v_add_f32_e32 v151, v151, v152
	v_mul_f32_e32 v152, v141, v141
	v_mul_f32_e32 v153, v142, v142
	v_lshlrev_b32_e32 v158, 16, v224
	v_and_b32_e32 v159, 0xffff0000, v224
	v_lshlrev_b32_e32 v154, 16, v225
	v_and_b32_e32 v155, 0xffff0000, v225
	v_add_f32_e32 v151, 0, v151
	v_fmac_f32_e32 v152, v140, v140
	v_fmac_f32_e32 v153, v143, v143
	v_add_f32_e32 v156, v152, v153
	v_fma_f32 v152, v149, v154, v150
	v_fma_f32 v153, v149, v155, v150
	v_fma_f32 v154, v149, v158, v150
	v_fma_f32 v155, v149, v159, v150
	v_fma_f32 v152, v58, v152, v62
	v_fma_f32 v153, v59, v153, v63
	v_fma_f32 v154, v56, v154, v60
	v_fma_f32 v155, v57, v155, v61
	v_fma_f32 v152, v152, s10, v138
	v_fma_f32 v153, v153, s10, v139
	v_fma_f32 v138, v154, s10, v136
	v_fma_f32 v139, v155, s10, v137
	v_add_f32_e32 v137, v153, v152
	v_add_f32_e32 v136, v138, v139
	v_add_f32_e32 v136, v136, v137
	v_add_f32_e32 v151, v136, v151
	v_mul_f32_e32 v136, v139, v139
	v_mul_f32_e32 v137, v152, v152
	v_fmac_f32_e32 v136, v138, v138
	v_fmac_f32_e32 v137, v153, v153
	v_add_f32_e32 v136, v136, v137
	v_add_f32_e32 v154, v156, v136
	v_cvt_pk_bf16_f32 v136, v140, v141
	v_cvt_pk_bf16_f32 v137, v142, v143
	v_cvt_pk_bf16_f32 v138, v138, v139
	v_cvt_pk_bf16_f32 v139, v152, v153
	global_store_dwordx4 v[146:147], v[136:139], off
	s_waitcnt vmcnt(7)
	v_lshlrev_b32_e32 v140, 16, v226
	v_and_b32_e32 v141, 0xffff0000, v226
	v_lshlrev_b32_e32 v136, 16, v227
	v_and_b32_e32 v137, 0xffff0000, v227
	v_fma_f32 v136, v149, v136, v150
	v_fma_f32 v137, v149, v137, v150
	v_fma_f32 v140, v149, v140, v150
	v_fma_f32 v141, v149, v141, v150
	v_fma_f32 v136, v46, v136, v50
	v_fma_f32 v137, v47, v137, v51
	v_fma_f32 v140, v44, v140, v48
	v_fma_f32 v141, v45, v141, v49
	v_fma_f32 v134, v136, s10, v134
	v_fma_f32 v135, v137, s10, v135
	v_fma_f32 v132, v140, s10, v132
	v_fma_f32 v133, v141, s10, v133
	v_add_f32_e32 v137, v135, v134
	v_add_f32_e32 v136, v132, v133
	v_add_f32_e32 v136, v136, v137
	v_add_f32_e32 v140, v151, v136
	v_mul_f32_e32 v136, v133, v133
	v_mul_f32_e32 v137, v134, v134
	v_fmac_f32_e32 v136, v132, v132
	v_fmac_f32_e32 v137, v135, v135
	v_lshlrev_b32_e32 v142, 16, v228
	v_and_b32_e32 v143, 0xffff0000, v228
	v_lshlrev_b32_e32 v138, 16, v229
	v_and_b32_e32 v139, 0xffff0000, v229
	v_add_u32_e32 v226, s0, v186
	v_ashrrev_i32_e32 v227, 31, v226
	v_lshlrev_b64 v[228:229], 11, v[226:227]
	v_lshl_add_u64 v[228:229], s[18:19], 0, v[228:229]
	v_lshl_add_u64 v[228:229], v[170:171], 1, v[228:229]
	global_load_dwordx4 v[222:225], v[228:229], off
	global_load_dwordx4 v[226:229], v[228:229], off offset:256
	v_add_f32_e32 v136, v136, v137
	v_add_f32_e32 v141, v154, v136
	v_fma_f32 v136, v149, v138, v150
	v_fma_f32 v137, v149, v139, v150
	v_fma_f32 v138, v149, v142, v150
	v_fma_f32 v139, v149, v143, v150
	v_fma_f32 v136, v38, v136, v42
	v_fma_f32 v137, v39, v137, v43
	v_fma_f32 v138, v36, v138, v40
	v_fma_f32 v139, v37, v139, v41
	v_fma_f32 v136, v136, s10, v130
	v_fma_f32 v137, v137, s10, v131
	v_fma_f32 v130, v138, s10, v128
	v_fma_f32 v131, v139, s10, v129
	v_add_f32_e32 v129, v137, v136
	v_add_f32_e32 v128, v130, v131
	v_add_f32_e32 v128, v128, v129
	v_add_f32_e32 v138, v128, v140
	v_mul_f32_e32 v128, v131, v131
	v_mul_f32_e32 v129, v136, v136
	v_fmac_f32_e32 v128, v130, v130
	v_fmac_f32_e32 v129, v137, v137
	v_add_f32_e32 v128, v128, v129
	v_add_f32_e32 v139, v128, v141
	v_cvt_pk_bf16_f32 v128, v132, v133
	v_cvt_pk_bf16_f32 v129, v134, v135
	v_cvt_pk_bf16_f32 v130, v130, v131
	v_cvt_pk_bf16_f32 v131, v136, v137
	global_store_dwordx4 v[146:147], v[128:131], off offset:256
	ds_swizzle_b32 v128, v138 offset:swizzle(SWAP,16)
	ds_swizzle_b32 v129, v139 offset:swizzle(SWAP,16)
	s_waitcnt lgkmcnt(1)
	v_add_f32_e32 v128, v138, v128
	s_waitcnt lgkmcnt(0)
	v_add_f32_e32 v129, v139, v129
	v_mov_b32_e32 v130, v128
	v_mov_b32_e32 v131, v129
	s_nop 0
	v_permlane32_swap_b32_e32 v128, v130
	v_permlane32_swap_b32_e32 v129, v131
	s_and_saveexec_b64 s[4:5], s[44:45]
	s_cbranch_execz .LBB0_586
	v_add_f32_e64 v128, v128, v130
	v_add_f32_e64 v129, v129, v131
	v_lshlrev_b64 v[130:131], 7, v[144:145]
	v_lshl_add_u64 v[130:131], s[20:21], 0, v[130:131]
	v_lshl_add_u64 v[130:131], s[36:37], 2, v[130:131]
	global_store_dwordx2 v[130:131], v[128:129], off
; __device__ __forceinline__ unsigned pk(float lo, float hi) { return pg8::cvt_pk_bf16(lo, hi); }
; template <int O> __device__ __forceinline__ float swz_xor(float v) { return __int_as_float(__builtin_amdgcn_ds_swizzle(__float_as_int(v), (O << 10) | 0x1f)); }
;     __device__ __forceinline__ void operator()(pg8::f32x4 (&acc)[2][2][4][2], const pg8::Unit& u, int wr, int wc, int fr, int fq) const {
;     ...
;             for (int m = 0; m < 4; ++m) { const int rl = ai * 128 + wr * 64 + m * 16 + fr; const f2v st = T[rl]; const float r = st.y, rm = -st.x * st.y;
;                 const size_t off = (size_t)(u.pm * 256 + rl) * DM + cb; float s1 = 0.f, s2 = 0.f;
; #pragma unroll
;                 for (int bj = 0; bj < 2; ++bj) { f4 pre[2]; float xin[8]; unpack8(*(const u32x4*)(XB + off + 128 * bj), xin);
; #pragma unroll
;                     for (int n = 0; n < 2; ++n) { const f4 v = {xin[4 * n], xin[4 * n + 1], xin[4 * n + 2], xin[4 * n + 3]}; const f4 xr = (v * r + rm) * gv[bj][n] + bv[bj][n];
;                         pre[n] = xr * alpha + acc[ai][bj][m][n]; if (X) *(f4*)(X + off + 128 * bj + 4 * n) = pre[n];
;                         s1 += (pre[n][0] + pre[n][1]) + (pre[n][2] + pre[n][3]); s2 += (pre[n][0] * pre[n][0] + pre[n][1] * pre[n][1]) + (pre[n][2] * pre[n][2] + pre[n][3] * pre[n][3]); }
;                     u32x4 w; w.x = pk(pre[0][0], pre[0][1]); w.y = pk(pre[0][2], pre[0][3]); w.z = pk(pre[1][0], pre[1][1]); w.w = pk(pre[1][2], pre[1][3]);
;                     if (!X) *(u32x4*)(XB + off + 128 * bj) = w; }
;                 s1 += swz_xor<16>(s1); s2 += swz_xor<16>(s2);
;                 { auto r1 = __builtin_amdgcn_permlane32_swap(__float_as_uint(s1), __float_as_uint(s1), false, false); s1 = __uint_as_float(r1[0]) + __uint_as_float(r1[1]);
;                   auto r2 = __builtin_amdgcn_permlane32_swap(__float_as_uint(s2), __float_as_uint(s2), false, false); s2 = __uint_as_float(r2[0]) + __uint_as_float(r2[1]); }
;                 if (fq == 0) *(f2v*)(SPout + (size_t)(u.pm * 256 + rl) * 32 + (u.pn * 4 + wc) * 2) = (f2v){s1, s2};
.LBB0_586:
	s_or_b64 exec, exec, s[4:5]
	v_add_u32_e32 v128, s0, v184
	v_ashrrev_i32_e32 v129, 31, v128
	v_lshlrev_b64 v[130:131], 11, v[128:129]
	v_lshl_add_u64 v[130:131], s[18:19], 0, v[130:131]
	v_lshl_add_u64 v[130:131], v[170:171], 1, v[130:131]
	ds_read_b64 v[132:133], v199
	s_waitcnt lgkmcnt(0)
	v_mul_f32_e64 v134, v133, -v132
	s_waitcnt vmcnt(9)
	v_lshlrev_b32_e32 v140, 16, v238
	v_and_b32_e32 v141, 0xffff0000, v238
	v_lshlrev_b32_e32 v136, 16, v239
	v_and_b32_e32 v137, 0xffff0000, v239
	v_fma_f32 v136, v133, v136, v134
	v_fma_f32 v137, v133, v137, v134
	v_fma_f32 v140, v133, v140, v134
	v_fma_f32 v141, v133, v141, v134
	v_fma_f32 v136, v66, v136, v70
	v_fma_f32 v137, v67, v137, v71
	v_fma_f32 v140, v64, v140, v68
	v_fma_f32 v141, v65, v141, v69
	v_fma_f32 v126, v136, s10, v126
	v_fma_f32 v127, v137, s10, v127
	v_fma_f32 v124, v140, s10, v124
	v_fma_f32 v125, v141, s10, v125
	v_add_f32_e32 v136, v127, v126
	v_add_f32_e32 v135, v124, v125
	v_add_f32_e32 v135, v135, v136
	v_mul_f32_e32 v136, v125, v125
	v_mul_f32_e32 v137, v126, v126
	v_lshlrev_b32_e32 v142, 16, v240
	v_and_b32_e32 v143, 0xffff0000, v240
	v_lshlrev_b32_e32 v138, 16, v241
	v_and_b32_e32 v139, 0xffff0000, v241
	v_add_f32_e32 v135, 0, v135
	v_fmac_f32_e32 v136, v124, v124
	v_fmac_f32_e32 v137, v127, v127
	v_add_f32_e32 v140, v136, v137
	v_fma_f32 v136, v133, v138, v134
	v_fma_f32 v137, v133, v139, v134
	v_fma_f32 v138, v133, v142, v134
	v_fma_f32 v139, v133, v143, v134
	v_fma_f32 v136, v58, v136, v62
	v_fma_f32 v137, v59, v137, v63
	v_fma_f32 v138, v56, v138, v60
	v_fma_f32 v139, v57, v139, v61
	v_fma_f32 v136, v136, s10, v122
	v_fma_f32 v137, v137, s10, v123
	v_fma_f32 v122, v138, s10, v120
	v_fma_f32 v123, v139, s10, v121
	v_add_f32_e32 v121, v137, v136
	v_add_f32_e32 v120, v122, v123
	v_add_f32_e32 v120, v120, v121
	v_add_f32_e32 v135, v120, v135
	v_mul_f32_e32 v120, v123, v123
	v_mul_f32_e32 v121, v136, v136
	v_fmac_f32_e32 v120, v122, v122
	v_fmac_f32_e32 v121, v137, v137
	v_add_f32_e32 v120, v120, v121
	v_add_f32_e32 v138, v140, v120
	v_cvt_pk_bf16_f32 v120, v124, v125
	v_cvt_pk_bf16_f32 v121, v126, v127
	v_cvt_pk_bf16_f32 v122, v122, v123
	v_cvt_pk_bf16_f32 v123, v136, v137
	global_store_dwordx4 v[130:131], v[120:123], off
	s_waitcnt vmcnt(9)
	v_lshlrev_b32_e32 v124, 16, v242
	v_and_b32_e32 v125, 0xffff0000, v242
	v_lshlrev_b32_e32 v120, 16, v243
	v_and_b32_e32 v121, 0xffff0000, v243
	v_fma_f32 v120, v133, v120, v134
	v_fma_f32 v121, v133, v121, v134
	v_fma_f32 v124, v133, v124, v134
	v_fma_f32 v125, v133, v125, v134
	v_fma_f32 v120, v46, v120, v50
	v_fma_f32 v121, v47, v121, v51
	v_fma_f32 v124, v44, v124, v48
	v_fma_f32 v125, v45, v125, v49
	v_fma_f32 v118, v120, s10, v118
	v_fma_f32 v119, v121, s10, v119
	v_fma_f32 v116, v124, s10, v116
	v_fma_f32 v117, v125, s10, v117
	v_add_f32_e32 v121, v119, v118
	v_add_f32_e32 v120, v116, v117
	v_add_f32_e32 v120, v120, v121
	v_add_f32_e32 v124, v135, v120
	v_mul_f32_e32 v120, v117, v117
	v_mul_f32_e32 v121, v118, v118
	v_fmac_f32_e32 v120, v116, v116
	v_fmac_f32_e32 v121, v119, v119
	v_lshlrev_b32_e32 v126, 16, v244
	v_and_b32_e32 v127, 0xffff0000, v244
	v_lshlrev_b32_e32 v122, 16, v245
	v_and_b32_e32 v123, 0xffff0000, v245
	v_add_u32_e32 v242, s0, v187
	v_ashrrev_i32_e32 v243, 31, v242
	v_lshlrev_b64 v[244:245], 11, v[242:243]
	v_lshl_add_u64 v[244:245], s[18:19], 0, v[244:245]
	v_lshl_add_u64 v[244:245], v[170:171], 1, v[244:245]
	global_load_dwordx4 v[238:241], v[244:245], off
	global_load_dwordx4 v[242:245], v[244:245], off offset:256
	v_add_f32_e32 v120, v120, v121
	v_add_f32_e32 v125, v138, v120
	v_fma_f32 v120, v133, v122, v134
	v_fma_f32 v121, v133, v123, v134
	v_fma_f32 v122, v133, v126, v134
	v_fma_f32 v123, v133, v127, v134
	v_fma_f32 v120, v38, v120, v42
	v_fma_f32 v121, v39, v121, v43
	v_fma_f32 v122, v36, v122, v40
	v_fma_f32 v123, v37, v123, v41
	v_fma_f32 v120, v120, s10, v114
	v_fma_f32 v121, v121, s10, v115
	v_fma_f32 v114, v122, s10, v112
	v_fma_f32 v115, v123, s10, v113
	v_add_f32_e32 v113, v121, v120
	v_add_f32_e32 v112, v114, v115
	v_add_f32_e32 v112, v112, v113
	v_add_f32_e32 v122, v112, v124
	v_mul_f32_e32 v112, v115, v115
	v_mul_f32_e32 v113, v120, v120
	v_fmac_f32_e32 v112, v114, v114
	v_fmac_f32_e32 v113, v121, v121
	v_add_f32_e32 v112, v112, v113
	v_add_f32_e32 v123, v112, v125
	v_cvt_pk_bf16_f32 v112, v116, v117
	v_cvt_pk_bf16_f32 v113, v118, v119
	v_cvt_pk_bf16_f32 v114, v114, v115
	v_cvt_pk_bf16_f32 v115, v120, v121
	global_store_dwordx4 v[130:131], v[112:115], off offset:256
	ds_swizzle_b32 v112, v122 offset:swizzle(SWAP,16)
	ds_swizzle_b32 v113, v123 offset:swizzle(SWAP,16)
	s_waitcnt lgkmcnt(1)
	v_add_f32_e32 v112, v122, v112
	s_waitcnt lgkmcnt(0)
	v_add_f32_e32 v113, v123, v113
	v_mov_b32_e32 v114, v112
	v_mov_b32_e32 v115, v113
	s_nop 0
	v_permlane32_swap_b32_e32 v112, v114
	v_permlane32_swap_b32_e32 v113, v115
	s_and_saveexec_b64 s[4:5], s[44:45]
	s_cbranch_execz .LBB0_588
	v_add_f32_e64 v112, v112, v114
	v_add_f32_e64 v113, v113, v115
	v_lshlrev_b64 v[114:115], 7, v[128:129]
	v_lshl_add_u64 v[114:115], s[20:21], 0, v[114:115]
	v_lshl_add_u64 v[114:115], s[36:37], 2, v[114:115]
	global_store_dwordx2 v[114:115], v[112:113], off
; __device__ __forceinline__ unsigned pk(float lo, float hi) { return pg8::cvt_pk_bf16(lo, hi); }
; template <int O> __device__ __forceinline__ float swz_xor(float v) { return __int_as_float(__builtin_amdgcn_ds_swizzle(__float_as_int(v), (O << 10) | 0x1f)); }
;     __device__ __forceinline__ void operator()(pg8::f32x4 (&acc)[2][2][4][2], const pg8::Unit& u, int wr, int wc, int fr, int fq) const {
;     ...
;             for (int m = 0; m < 4; ++m) { const int rl = ai * 128 + wr * 64 + m * 16 + fr; const f2v st = T[rl]; const float r = st.y, rm = -st.x * st.y;
;                 const size_t off = (size_t)(u.pm * 256 + rl) * DM + cb; float s1 = 0.f, s2 = 0.f;
; #pragma unroll
;                 for (int bj = 0; bj < 2; ++bj) { f4 pre[2]; float xin[8]; unpack8(*(const u32x4*)(XB + off + 128 * bj), xin);
; #pragma unroll
;                     for (int n = 0; n < 2; ++n) { const f4 v = {xin[4 * n], xin[4 * n + 1], xin[4 * n + 2], xin[4 * n + 3]}; const f4 xr = (v * r + rm) * gv[bj][n] + bv[bj][n];
;                         pre[n] = xr * alpha + acc[ai][bj][m][n]; if (X) *(f4*)(X + off + 128 * bj + 4 * n) = pre[n];
;                         s1 += (pre[n][0] + pre[n][1]) + (pre[n][2] + pre[n][3]); s2 += (pre[n][0] * pre[n][0] + pre[n][1] * pre[n][1]) + (pre[n][2] * pre[n][2] + pre[n][3] * pre[n][3]); }
;                     u32x4 w; w.x = pk(pre[0][0], pre[0][1]); w.y = pk(pre[0][2], pre[0][3]); w.z = pk(pre[1][0], pre[1][1]); w.w = pk(pre[1][2], pre[1][3]);
;                     if (!X) *(u32x4*)(XB + off + 128 * bj) = w; }
;                 s1 += swz_xor<16>(s1); s2 += swz_xor<16>(s2);
;                 { auto r1 = __builtin_amdgcn_permlane32_swap(__float_as_uint(s1), __float_as_uint(s1), false, false); s1 = __uint_as_float(r1[0]) + __uint_as_float(r1[1]);
;                   auto r2 = __builtin_amdgcn_permlane32_swap(__float_as_uint(s2), __float_as_uint(s2), false, false); s2 = __uint_as_float(r2[0]) + __uint_as_float(r2[1]); }
;                 if (fq == 0) *(f2v*)(SPout + (size_t)(u.pm * 256 + rl) * 32 + (u.pn * 4 + wc) * 2) = (f2v){s1, s2};
.LBB0_588:
	s_or_b64 exec, exec, s[4:5]
	v_add_u32_e32 v112, s0, v185
	v_ashrrev_i32_e32 v113, 31, v112
	v_lshlrev_b64 v[114:115], 11, v[112:113]
	v_lshl_add_u64 v[114:115], s[18:19], 0, v[114:115]
	v_lshl_add_u64 v[114:115], v[170:171], 1, v[114:115]
	ds_read_b64 v[116:117], v200
	s_waitcnt lgkmcnt(0)
	v_mul_f32_e64 v118, v117, -v116
	s_waitcnt vmcnt(10)
	v_lshlrev_b32_e32 v124, 16, v214
	v_and_b32_e32 v125, 0xffff0000, v214
	v_lshlrev_b32_e32 v120, 16, v215
	v_and_b32_e32 v121, 0xffff0000, v215
	v_fma_f32 v120, v117, v120, v118
	v_fma_f32 v121, v117, v121, v118
	v_fma_f32 v124, v117, v124, v118
	v_fma_f32 v125, v117, v125, v118
	v_fma_f32 v120, v66, v120, v70
	v_fma_f32 v121, v67, v121, v71
	v_fma_f32 v124, v64, v124, v68
	v_fma_f32 v125, v65, v125, v69
	v_fma_f32 v110, v120, s10, v110
	v_fma_f32 v111, v121, s10, v111
	v_fma_f32 v108, v124, s10, v108
	v_fma_f32 v109, v125, s10, v109
	v_add_f32_e32 v120, v111, v110
	v_add_f32_e32 v119, v108, v109
	v_add_f32_e32 v119, v119, v120
	v_mul_f32_e32 v120, v109, v109
	v_mul_f32_e32 v121, v110, v110
	v_lshlrev_b32_e32 v126, 16, v216
	v_and_b32_e32 v127, 0xffff0000, v216
	v_lshlrev_b32_e32 v122, 16, v217
	v_and_b32_e32 v123, 0xffff0000, v217
	v_add_f32_e32 v119, 0, v119
	v_fmac_f32_e32 v120, v108, v108
	v_fmac_f32_e32 v121, v111, v111
	v_add_f32_e32 v124, v120, v121
	v_fma_f32 v120, v117, v122, v118
	v_fma_f32 v121, v117, v123, v118
	v_fma_f32 v122, v117, v126, v118
	v_fma_f32 v123, v117, v127, v118
	v_fma_f32 v120, v58, v120, v62
	v_fma_f32 v121, v59, v121, v63
	v_fma_f32 v122, v56, v122, v60
	v_fma_f32 v123, v57, v123, v61
	v_fma_f32 v120, v120, s10, v106
	v_fma_f32 v121, v121, s10, v107
	v_fma_f32 v106, v122, s10, v104
	v_fma_f32 v107, v123, s10, v105
	v_add_f32_e32 v105, v121, v120
	v_add_f32_e32 v104, v106, v107
	v_add_f32_e32 v104, v104, v105
	v_add_f32_e32 v119, v104, v119
	v_mul_f32_e32 v104, v107, v107
	v_mul_f32_e32 v105, v120, v120
	v_fmac_f32_e32 v104, v106, v106
	v_fmac_f32_e32 v105, v121, v121
	v_add_f32_e32 v104, v104, v105
	v_add_f32_e32 v122, v124, v104
	v_cvt_pk_bf16_f32 v104, v108, v109
	v_cvt_pk_bf16_f32 v105, v110, v111
	v_cvt_pk_bf16_f32 v106, v106, v107
	v_cvt_pk_bf16_f32 v107, v120, v121
	global_store_dwordx4 v[114:115], v[104:107], off
	s_waitcnt vmcnt(10)
	v_lshlrev_b32_e32 v108, 16, v218
	v_and_b32_e32 v109, 0xffff0000, v218
	v_lshlrev_b32_e32 v104, 16, v219
	v_and_b32_e32 v105, 0xffff0000, v219
	v_fma_f32 v104, v117, v104, v118
	v_fma_f32 v105, v117, v105, v118
	v_fma_f32 v108, v117, v108, v118
	v_fma_f32 v109, v117, v109, v118
	v_fma_f32 v104, v46, v104, v50
	v_fma_f32 v105, v47, v105, v51
	v_fma_f32 v108, v44, v108, v48
	v_fma_f32 v109, v45, v109, v49
	v_fma_f32 v102, v104, s10, v102
	v_fma_f32 v103, v105, s10, v103
	v_fma_f32 v100, v108, s10, v100
	v_fma_f32 v101, v109, s10, v101
	v_add_f32_e32 v105, v103, v102
	v_add_f32_e32 v104, v100, v101
	v_add_f32_e32 v104, v104, v105
	v_add_f32_e32 v108, v119, v104
	v_mul_f32_e32 v104, v101, v101
	v_mul_f32_e32 v105, v102, v102
	v_fmac_f32_e32 v104, v100, v100
	v_fmac_f32_e32 v105, v103, v103
	v_lshlrev_b32_e32 v110, 16, v220
	v_and_b32_e32 v111, 0xffff0000, v220
	v_lshlrev_b32_e32 v106, 16, v221
	v_and_b32_e32 v107, 0xffff0000, v221
	v_add_u32_e32 v218, s0, v194
	v_ashrrev_i32_e32 v219, 31, v218
	v_lshlrev_b64 v[220:221], 11, v[218:219]
	v_lshl_add_u64 v[220:221], s[18:19], 0, v[220:221]
	v_lshl_add_u64 v[220:221], v[170:171], 1, v[220:221]
	global_load_dwordx4 v[214:217], v[220:221], off
	global_load_dwordx4 v[218:221], v[220:221], off offset:256
	v_add_f32_e32 v104, v104, v105
	v_add_f32_e32 v109, v122, v104
	v_fma_f32 v104, v117, v106, v118
	v_fma_f32 v105, v117, v107, v118
	v_fma_f32 v106, v117, v110, v118
	v_fma_f32 v107, v117, v111, v118
	v_fma_f32 v104, v38, v104, v42
	v_fma_f32 v105, v39, v105, v43
	v_fma_f32 v106, v36, v106, v40
	v_fma_f32 v107, v37, v107, v41
	v_fma_f32 v104, v104, s10, v98
	v_fma_f32 v105, v105, s10, v99
	v_fma_f32 v98, v106, s10, v96
	v_fma_f32 v99, v107, s10, v97
	v_add_f32_e32 v97, v105, v104
	v_add_f32_e32 v96, v98, v99
	v_add_f32_e32 v96, v96, v97
	v_add_f32_e32 v106, v96, v108
	v_mul_f32_e32 v96, v99, v99
	v_mul_f32_e32 v97, v104, v104
	v_fmac_f32_e32 v96, v98, v98
	v_fmac_f32_e32 v97, v105, v105
	v_add_f32_e32 v96, v96, v97
	v_add_f32_e32 v107, v96, v109
	v_cvt_pk_bf16_f32 v96, v100, v101
	v_cvt_pk_bf16_f32 v97, v102, v103
	v_cvt_pk_bf16_f32 v98, v98, v99
	v_cvt_pk_bf16_f32 v99, v104, v105
	global_store_dwordx4 v[114:115], v[96:99], off offset:256
	ds_swizzle_b32 v96, v106 offset:swizzle(SWAP,16)
	ds_swizzle_b32 v97, v107 offset:swizzle(SWAP,16)
	s_waitcnt lgkmcnt(1)
	v_add_f32_e32 v96, v106, v96
	s_waitcnt lgkmcnt(0)
	v_add_f32_e32 v97, v107, v97
	v_mov_b32_e32 v98, v96
	v_mov_b32_e32 v99, v97
	s_nop 0
	v_permlane32_swap_b32_e32 v96, v98
	v_permlane32_swap_b32_e32 v97, v99
	s_and_saveexec_b64 s[4:5], s[44:45]
	s_cbranch_execz .LBB0_590
	v_add_f32_e64 v96, v96, v98
	v_add_f32_e64 v97, v97, v99
	v_lshlrev_b64 v[98:99], 7, v[112:113]
	v_lshl_add_u64 v[98:99], s[20:21], 0, v[98:99]
	v_lshl_add_u64 v[98:99], s[36:37], 2, v[98:99]
	global_store_dwordx2 v[98:99], v[96:97], off
; __device__ __forceinline__ unsigned pk(float lo, float hi) { return pg8::cvt_pk_bf16(lo, hi); }
; template <int O> __device__ __forceinline__ float swz_xor(float v) { return __int_as_float(__builtin_amdgcn_ds_swizzle(__float_as_int(v), (O << 10) | 0x1f)); }
;     __device__ __forceinline__ void operator()(pg8::f32x4 (&acc)[2][2][4][2], const pg8::Unit& u, int wr, int wc, int fr, int fq) const {
;     ...
;             for (int m = 0; m < 4; ++m) { const int rl = ai * 128 + wr * 64 + m * 16 + fr; const f2v st = T[rl]; const float r = st.y, rm = -st.x * st.y;
;                 const size_t off = (size_t)(u.pm * 256 + rl) * DM + cb; float s1 = 0.f, s2 = 0.f;
; #pragma unroll
;                 for (int bj = 0; bj < 2; ++bj) { f4 pre[2]; float xin[8]; unpack8(*(const u32x4*)(XB + off + 128 * bj), xin);
; #pragma unroll
;                     for (int n = 0; n < 2; ++n) { const f4 v = {xin[4 * n], xin[4 * n + 1], xin[4 * n + 2], xin[4 * n + 3]}; const f4 xr = (v * r + rm) * gv[bj][n] + bv[bj][n];
;                         pre[n] = xr * alpha + acc[ai][bj][m][n]; if (X) *(f4*)(X + off + 128 * bj + 4 * n) = pre[n];
;                         s1 += (pre[n][0] + pre[n][1]) + (pre[n][2] + pre[n][3]); s2 += (pre[n][0] * pre[n][0] + pre[n][1] * pre[n][1]) + (pre[n][2] * pre[n][2] + pre[n][3] * pre[n][3]); }
;                     u32x4 w; w.x = pk(pre[0][0], pre[0][1]); w.y = pk(pre[0][2], pre[0][3]); w.z = pk(pre[1][0], pre[1][1]); w.w = pk(pre[1][2], pre[1][3]);
;                     if (!X) *(u32x4*)(XB + off + 128 * bj) = w; }
;                 s1 += swz_xor<16>(s1); s2 += swz_xor<16>(s2);
;                 { auto r1 = __builtin_amdgcn_permlane32_swap(__float_as_uint(s1), __float_as_uint(s1), false, false); s1 = __uint_as_float(r1[0]) + __uint_as_float(r1[1]);
;                   auto r2 = __builtin_amdgcn_permlane32_swap(__float_as_uint(s2), __float_as_uint(s2), false, false); s2 = __uint_as_float(r2[0]) + __uint_as_float(r2[1]); }
;                 if (fq == 0) *(f2v*)(SPout + (size_t)(u.pm * 256 + rl) * 32 + (u.pn * 4 + wc) * 2) = (f2v){s1, s2};
.LBB0_590:
	s_or_b64 exec, exec, s[4:5]
	v_add_u32_e32 v96, s0, v186
	v_ashrrev_i32_e32 v97, 31, v96
	v_lshlrev_b64 v[98:99], 11, v[96:97]
	v_lshl_add_u64 v[98:99], s[18:19], 0, v[98:99]
	v_lshl_add_u64 v[98:99], v[170:171], 1, v[98:99]
	ds_read_b64 v[100:101], v201
	s_waitcnt lgkmcnt(0)
	v_mul_f32_e64 v102, v101, -v100
	s_waitcnt vmcnt(10)
	v_lshlrev_b32_e32 v108, 16, v222
	v_and_b32_e32 v109, 0xffff0000, v222
	v_lshlrev_b32_e32 v104, 16, v223
	v_and_b32_e32 v105, 0xffff0000, v223
	v_fma_f32 v104, v101, v104, v102
	v_fma_f32 v105, v101, v105, v102
	v_fma_f32 v108, v101, v108, v102
	v_fma_f32 v109, v101, v109, v102
	v_fma_f32 v104, v66, v104, v70
	v_fma_f32 v105, v67, v105, v71
	v_fma_f32 v108, v64, v108, v68
	v_fma_f32 v109, v65, v109, v69
	v_fma_f32 v94, v104, s10, v94
	v_fma_f32 v95, v105, s10, v95
	v_fma_f32 v92, v108, s10, v92
	v_fma_f32 v93, v109, s10, v93
	v_add_f32_e32 v104, v95, v94
	v_add_f32_e32 v103, v92, v93
	v_add_f32_e32 v103, v103, v104
	v_mul_f32_e32 v104, v93, v93
	v_mul_f32_e32 v105, v94, v94
	v_lshlrev_b32_e32 v110, 16, v224
	v_and_b32_e32 v111, 0xffff0000, v224
	v_lshlrev_b32_e32 v106, 16, v225
	v_and_b32_e32 v107, 0xffff0000, v225
	v_add_f32_e32 v103, 0, v103
	v_fmac_f32_e32 v104, v92, v92
	v_fmac_f32_e32 v105, v95, v95
	v_add_f32_e32 v108, v104, v105
	v_fma_f32 v104, v101, v106, v102
	v_fma_f32 v105, v101, v107, v102
	v_fma_f32 v106, v101, v110, v102
	v_fma_f32 v107, v101, v111, v102
	v_fma_f32 v104, v58, v104, v62
	v_fma_f32 v105, v59, v105, v63
	v_fma_f32 v106, v56, v106, v60
	v_fma_f32 v107, v57, v107, v61
	v_fma_f32 v104, v104, s10, v90
	v_fma_f32 v105, v105, s10, v91
	v_fma_f32 v90, v106, s10, v88
	v_fma_f32 v91, v107, s10, v89
	v_add_f32_e32 v89, v105, v104
	v_add_f32_e32 v88, v90, v91
	v_add_f32_e32 v88, v88, v89
	v_add_f32_e32 v103, v88, v103
	v_mul_f32_e32 v88, v91, v91
	v_mul_f32_e32 v89, v104, v104
	v_fmac_f32_e32 v88, v90, v90
	v_fmac_f32_e32 v89, v105, v105
	v_add_f32_e32 v88, v88, v89
	v_add_f32_e32 v106, v108, v88
	v_cvt_pk_bf16_f32 v88, v92, v93
	v_cvt_pk_bf16_f32 v89, v94, v95
	v_cvt_pk_bf16_f32 v90, v90, v91
	v_cvt_pk_bf16_f32 v91, v104, v105
	global_store_dwordx4 v[98:99], v[88:91], off
	s_waitcnt vmcnt(10)
	v_lshlrev_b32_e32 v92, 16, v226
	v_and_b32_e32 v93, 0xffff0000, v226
	v_lshlrev_b32_e32 v88, 16, v227
	v_and_b32_e32 v89, 0xffff0000, v227
	v_fma_f32 v88, v101, v88, v102
	v_fma_f32 v89, v101, v89, v102
	v_fma_f32 v92, v101, v92, v102
	v_fma_f32 v93, v101, v93, v102
	v_fma_f32 v88, v46, v88, v50
	v_fma_f32 v89, v47, v89, v51
	v_fma_f32 v92, v44, v92, v48
	v_fma_f32 v93, v45, v93, v49
	v_fma_f32 v86, v88, s10, v86
	v_fma_f32 v87, v89, s10, v87
	v_fma_f32 v84, v92, s10, v84
	v_fma_f32 v85, v93, s10, v85
	v_add_f32_e32 v89, v87, v86
	v_add_f32_e32 v88, v84, v85
	v_add_f32_e32 v88, v88, v89
	v_add_f32_e32 v92, v103, v88
	v_mul_f32_e32 v88, v85, v85
	v_mul_f32_e32 v89, v86, v86
	v_fmac_f32_e32 v88, v84, v84
	v_fmac_f32_e32 v89, v87, v87
	v_lshlrev_b32_e32 v94, 16, v228
	v_and_b32_e32 v95, 0xffff0000, v228
	v_lshlrev_b32_e32 v90, 16, v229
	v_and_b32_e32 v91, 0xffff0000, v229
	v_add_u32_e32 v226, s0, v195
	v_ashrrev_i32_e32 v227, 31, v226
	v_lshlrev_b64 v[228:229], 11, v[226:227]
	v_lshl_add_u64 v[228:229], s[18:19], 0, v[228:229]
	v_lshl_add_u64 v[228:229], v[170:171], 1, v[228:229]
	global_load_dwordx4 v[222:225], v[228:229], off
	global_load_dwordx4 v[226:229], v[228:229], off offset:256
	v_add_f32_e32 v88, v88, v89
	v_add_f32_e32 v93, v106, v88
	v_fma_f32 v88, v101, v90, v102
	v_fma_f32 v89, v101, v91, v102
	v_fma_f32 v90, v101, v94, v102
	v_fma_f32 v91, v101, v95, v102
	v_fma_f32 v88, v38, v88, v42
	v_fma_f32 v89, v39, v89, v43
	v_fma_f32 v90, v36, v90, v40
	v_fma_f32 v91, v37, v91, v41
	v_fma_f32 v88, v88, s10, v82
	v_fma_f32 v89, v89, s10, v83
	v_fma_f32 v82, v90, s10, v80
	v_fma_f32 v83, v91, s10, v81
	v_add_f32_e32 v81, v89, v88
	v_add_f32_e32 v80, v82, v83
	v_add_f32_e32 v80, v80, v81
	v_add_f32_e32 v90, v80, v92
	v_mul_f32_e32 v80, v83, v83
	v_mul_f32_e32 v81, v88, v88
	v_fmac_f32_e32 v80, v82, v82
	v_fmac_f32_e32 v81, v89, v89
	v_add_f32_e32 v80, v80, v81
	v_add_f32_e32 v91, v80, v93
	v_cvt_pk_bf16_f32 v80, v84, v85
	v_cvt_pk_bf16_f32 v81, v86, v87
	v_cvt_pk_bf16_f32 v82, v82, v83
	v_cvt_pk_bf16_f32 v83, v88, v89
	global_store_dwordx4 v[98:99], v[80:83], off offset:256
	ds_swizzle_b32 v80, v90 offset:swizzle(SWAP,16)
	ds_swizzle_b32 v81, v91 offset:swizzle(SWAP,16)
	s_waitcnt lgkmcnt(1)
	v_add_f32_e32 v80, v90, v80
	s_waitcnt lgkmcnt(0)
	v_add_f32_e32 v81, v91, v81
	v_mov_b32_e32 v82, v80
	v_mov_b32_e32 v83, v81
	s_nop 0
	v_permlane32_swap_b32_e32 v80, v82
	v_permlane32_swap_b32_e32 v81, v83
	s_and_saveexec_b64 s[4:5], s[44:45]
	s_cbranch_execz .LBB0_592
	v_add_f32_e64 v80, v80, v82
	v_add_f32_e64 v81, v81, v83
	v_lshlrev_b64 v[82:83], 7, v[96:97]
	v_lshl_add_u64 v[82:83], s[20:21], 0, v[82:83]
	v_lshl_add_u64 v[82:83], s[36:37], 2, v[82:83]
	global_store_dwordx2 v[82:83], v[80:81], off
; __device__ __forceinline__ unsigned pk(float lo, float hi) { return pg8::cvt_pk_bf16(lo, hi); }
; template <int O> __device__ __forceinline__ float swz_xor(float v) { return __int_as_float(__builtin_amdgcn_ds_swizzle(__float_as_int(v), (O << 10) | 0x1f)); }
;     __device__ __forceinline__ void operator()(pg8::f32x4 (&acc)[2][2][4][2], const pg8::Unit& u, int wr, int wc, int fr, int fq) const {
;     ...
;             for (int m = 0; m < 4; ++m) { const int rl = ai * 128 + wr * 64 + m * 16 + fr; const f2v st = T[rl]; const float r = st.y, rm = -st.x * st.y;
;                 const size_t off = (size_t)(u.pm * 256 + rl) * DM + cb; float s1 = 0.f, s2 = 0.f;
; #pragma unroll
;                 for (int bj = 0; bj < 2; ++bj) { f4 pre[2]; float xin[8]; unpack8(*(const u32x4*)(XB + off + 128 * bj), xin);
; #pragma unroll
;                     for (int n = 0; n < 2; ++n) { const f4 v = {xin[4 * n], xin[4 * n + 1], xin[4 * n + 2], xin[4 * n + 3]}; const f4 xr = (v * r + rm) * gv[bj][n] + bv[bj][n];
;                         pre[n] = xr * alpha + acc[ai][bj][m][n]; if (X) *(f4*)(X + off + 128 * bj + 4 * n) = pre[n];
;                         s1 += (pre[n][0] + pre[n][1]) + (pre[n][2] + pre[n][3]); s2 += (pre[n][0] * pre[n][0] + pre[n][1] * pre[n][1]) + (pre[n][2] * pre[n][2] + pre[n][3] * pre[n][3]); }
;                     u32x4 w; w.x = pk(pre[0][0], pre[0][1]); w.y = pk(pre[0][2], pre[0][3]); w.z = pk(pre[1][0], pre[1][1]); w.w = pk(pre[1][2], pre[1][3]);
;                     if (!X) *(u32x4*)(XB + off + 128 * bj) = w; }
;                 s1 += swz_xor<16>(s1); s2 += swz_xor<16>(s2);
;                 { auto r1 = __builtin_amdgcn_permlane32_swap(__float_as_uint(s1), __float_as_uint(s1), false, false); s1 = __uint_as_float(r1[0]) + __uint_as_float(r1[1]);
;                   auto r2 = __builtin_amdgcn_permlane32_swap(__float_as_uint(s2), __float_as_uint(s2), false, false); s2 = __uint_as_float(r2[0]) + __uint_as_float(r2[1]); }
;                 if (fq == 0) *(f2v*)(SPout + (size_t)(u.pm * 256 + rl) * 32 + (u.pn * 4 + wc) * 2) = (f2v){s1, s2};
.LBB0_592:
	s_or_b64 exec, exec, s[4:5]
	v_add_u32_e32 v80, s0, v187
	v_ashrrev_i32_e32 v81, 31, v80
	v_lshlrev_b64 v[82:83], 11, v[80:81]
	v_lshl_add_u64 v[82:83], s[18:19], 0, v[82:83]
	v_lshl_add_u64 v[82:83], v[170:171], 1, v[82:83]
	ds_read_b64 v[84:85], v202
	s_waitcnt lgkmcnt(0)
	v_mul_f32_e64 v86, v85, -v84
	s_waitcnt vmcnt(10)
	v_lshlrev_b32_e32 v92, 16, v238
	v_and_b32_e32 v93, 0xffff0000, v238
	v_lshlrev_b32_e32 v88, 16, v239
	v_and_b32_e32 v89, 0xffff0000, v239
	v_fma_f32 v88, v85, v88, v86
	v_fma_f32 v89, v85, v89, v86
	v_fma_f32 v92, v85, v92, v86
	v_fma_f32 v93, v85, v93, v86
	v_fma_f32 v88, v66, v88, v70
	v_fma_f32 v89, v67, v89, v71
	v_fma_f32 v92, v64, v92, v68
	v_fma_f32 v93, v65, v93, v69
	v_fma_f32 v78, v88, s10, v78
	v_fma_f32 v79, v89, s10, v79
	v_fma_f32 v76, v92, s10, v76
	v_fma_f32 v77, v93, s10, v77
	v_add_f32_e32 v88, v79, v78
	v_add_f32_e32 v87, v76, v77
	v_add_f32_e32 v87, v87, v88
	v_mul_f32_e32 v88, v77, v77
	v_mul_f32_e32 v89, v78, v78
	v_lshlrev_b32_e32 v94, 16, v240
	v_and_b32_e32 v95, 0xffff0000, v240
	v_lshlrev_b32_e32 v90, 16, v241
	v_and_b32_e32 v91, 0xffff0000, v241
	v_add_f32_e32 v87, 0, v87
	v_fmac_f32_e32 v88, v76, v76
	v_fmac_f32_e32 v89, v79, v79
	v_add_f32_e32 v92, v88, v89
	v_fma_f32 v88, v85, v90, v86
	v_fma_f32 v89, v85, v91, v86
	v_fma_f32 v90, v85, v94, v86
	v_fma_f32 v91, v85, v95, v86
	v_fma_f32 v88, v58, v88, v62
	v_fma_f32 v89, v59, v89, v63
	v_fma_f32 v90, v56, v90, v60
	v_fma_f32 v91, v57, v91, v61
	v_fma_f32 v88, v88, s10, v74
	v_fma_f32 v89, v89, s10, v75
	v_fma_f32 v74, v90, s10, v72
	v_fma_f32 v75, v91, s10, v73
	v_add_f32_e32 v73, v89, v88
	v_add_f32_e32 v72, v74, v75
	v_add_f32_e32 v72, v72, v73
	v_add_f32_e32 v87, v72, v87
	v_mul_f32_e32 v72, v75, v75
	v_mul_f32_e32 v73, v88, v88
	v_fmac_f32_e32 v72, v74, v74
	v_fmac_f32_e32 v73, v89, v89
	v_add_f32_e32 v72, v72, v73
	v_add_f32_e32 v90, v92, v72
	v_cvt_pk_bf16_f32 v72, v76, v77
	v_cvt_pk_bf16_f32 v73, v78, v79
	v_cvt_pk_bf16_f32 v74, v74, v75
	v_cvt_pk_bf16_f32 v75, v88, v89
	global_store_dwordx4 v[82:83], v[72:75], off
	s_waitcnt vmcnt(10)
	v_lshlrev_b32_e32 v76, 16, v242
	v_and_b32_e32 v77, 0xffff0000, v242
	v_lshlrev_b32_e32 v72, 16, v243
	v_and_b32_e32 v73, 0xffff0000, v243
	v_fma_f32 v72, v85, v72, v86
	v_fma_f32 v73, v85, v73, v86
	v_fma_f32 v76, v85, v76, v86
	v_fma_f32 v77, v85, v77, v86
	v_fma_f32 v72, v46, v72, v50
	v_fma_f32 v73, v47, v73, v51
	v_fma_f32 v76, v44, v76, v48
	v_fma_f32 v77, v45, v77, v49
	v_fma_f32 v54, v72, s10, v54
	v_fma_f32 v55, v73, s10, v55
	v_fma_f32 v52, v76, s10, v52
	v_fma_f32 v53, v77, s10, v53
	v_add_f32_e32 v73, v55, v54
	v_add_f32_e32 v72, v52, v53
	v_add_f32_e32 v72, v72, v73
	v_add_f32_e32 v76, v87, v72
	v_mul_f32_e32 v72, v53, v53
	v_mul_f32_e32 v73, v54, v54
	v_fmac_f32_e32 v72, v52, v52
	v_fmac_f32_e32 v73, v55, v55
	v_lshlrev_b32_e32 v78, 16, v244
	v_and_b32_e32 v79, 0xffff0000, v244
	v_lshlrev_b32_e32 v74, 16, v245
	v_and_b32_e32 v75, 0xffff0000, v245
	v_add_f32_e32 v72, v72, v73
	v_add_f32_e32 v77, v90, v72
	v_fma_f32 v72, v85, v74, v86
	v_fma_f32 v73, v85, v75, v86
	v_fma_f32 v74, v85, v78, v86
	v_fma_f32 v75, v85, v79, v86
	v_fma_f32 v72, v38, v72, v42
	v_fma_f32 v73, v39, v73, v43
	v_fma_f32 v74, v36, v74, v40
	v_fma_f32 v75, v37, v75, v41
	v_fma_f32 v72, v72, s10, v34
	v_fma_f32 v73, v73, s10, v35
	v_fma_f32 v34, v74, s10, v32
	v_fma_f32 v35, v75, s10, v33
	v_add_f32_e32 v33, v73, v72
	v_add_f32_e32 v32, v34, v35
	v_add_f32_e32 v32, v32, v33
	v_add_f32_e32 v74, v32, v76
	v_mul_f32_e32 v32, v35, v35
	v_mul_f32_e32 v33, v72, v72
	v_fmac_f32_e32 v32, v34, v34
	v_fmac_f32_e32 v33, v73, v73
	v_add_f32_e32 v32, v32, v33
	v_add_f32_e32 v75, v32, v77
	v_cvt_pk_bf16_f32 v32, v52, v53
	v_cvt_pk_bf16_f32 v33, v54, v55
	v_cvt_pk_bf16_f32 v34, v34, v35
	v_cvt_pk_bf16_f32 v35, v72, v73
	global_store_dwordx4 v[82:83], v[32:35], off offset:256
	ds_swizzle_b32 v32, v74 offset:swizzle(SWAP,16)
	ds_swizzle_b32 v33, v75 offset:swizzle(SWAP,16)
	s_waitcnt lgkmcnt(1)
	v_add_f32_e32 v32, v74, v32
	s_waitcnt lgkmcnt(0)
	v_add_f32_e32 v33, v75, v33
	v_mov_b32_e32 v34, v32
	v_mov_b32_e32 v35, v33
	s_nop 0
	v_permlane32_swap_b32_e32 v32, v34
	v_permlane32_swap_b32_e32 v33, v35
	s_and_saveexec_b64 s[4:5], s[44:45]
	s_cbranch_execz .LBB0_594
	v_add_f32_e64 v32, v32, v34
	v_add_f32_e64 v33, v33, v35
	v_lshlrev_b64 v[34:35], 7, v[80:81]
	v_lshl_add_u64 v[34:35], s[20:21], 0, v[34:35]
	v_lshl_add_u64 v[34:35], s[36:37], 2, v[34:35]
	global_store_dwordx2 v[34:35], v[32:33], off
; __device__ __forceinline__ unsigned pk(float lo, float hi) { return pg8::cvt_pk_bf16(lo, hi); }
; template <int O> __device__ __forceinline__ float swz_xor(float v) { return __int_as_float(__builtin_amdgcn_ds_swizzle(__float_as_int(v), (O << 10) | 0x1f)); }
;     __device__ __forceinline__ void operator()(pg8::f32x4 (&acc)[2][2][4][2], const pg8::Unit& u, int wr, int wc, int fr, int fq) const {
;     ...
;             for (int m = 0; m < 4; ++m) { const int rl = ai * 128 + wr * 64 + m * 16 + fr; const f2v st = T[rl]; const float r = st.y, rm = -st.x * st.y;
;                 const size_t off = (size_t)(u.pm * 256 + rl) * DM + cb; float s1 = 0.f, s2 = 0.f;
; #pragma unroll
;                 for (int bj = 0; bj < 2; ++bj) { f4 pre[2]; float xin[8]; unpack8(*(const u32x4*)(XB + off + 128 * bj), xin);
; #pragma unroll
;                     for (int n = 0; n < 2; ++n) { const f4 v = {xin[4 * n], xin[4 * n + 1], xin[4 * n + 2], xin[4 * n + 3]}; const f4 xr = (v * r + rm) * gv[bj][n] + bv[bj][n];
;                         pre[n] = xr * alpha + acc[ai][bj][m][n]; if (X) *(f4*)(X + off + 128 * bj + 4 * n) = pre[n];
;                         s1 += (pre[n][0] + pre[n][1]) + (pre[n][2] + pre[n][3]); s2 += (pre[n][0] * pre[n][0] + pre[n][1] * pre[n][1]) + (pre[n][2] * pre[n][2] + pre[n][3] * pre[n][3]); }
;                     u32x4 w; w.x = pk(pre[0][0], pre[0][1]); w.y = pk(pre[0][2], pre[0][3]); w.z = pk(pre[1][0], pre[1][1]); w.w = pk(pre[1][2], pre[1][3]);
;                     if (!X) *(u32x4*)(XB + off + 128 * bj) = w; }
;                 s1 += swz_xor<16>(s1); s2 += swz_xor<16>(s2);
;                 { auto r1 = __builtin_amdgcn_permlane32_swap(__float_as_uint(s1), __float_as_uint(s1), false, false); s1 = __uint_as_float(r1[0]) + __uint_as_float(r1[1]);
;                   auto r2 = __builtin_amdgcn_permlane32_swap(__float_as_uint(s2), __float_as_uint(s2), false, false); s2 = __uint_as_float(r2[0]) + __uint_as_float(r2[1]); }
;                 if (fq == 0) *(f2v*)(SPout + (size_t)(u.pm * 256 + rl) * 32 + (u.pn * 4 + wc) * 2) = (f2v){s1, s2};
.LBB0_594:
	s_or_b64 exec, exec, s[4:5]
	v_add_u32_e32 v32, s0, v194
	v_ashrrev_i32_e32 v33, 31, v32
	v_lshlrev_b64 v[34:35], 11, v[32:33]
	v_lshl_add_u64 v[34:35], s[18:19], 0, v[34:35]
	v_lshl_add_u64 v[34:35], v[170:171], 1, v[34:35]
	ds_read_b64 v[52:53], v203
	s_waitcnt lgkmcnt(0)
	v_mul_f32_e64 v54, v53, -v52
	s_waitcnt vmcnt(8)
	v_lshlrev_b32_e32 v76, 16, v214
	v_and_b32_e32 v77, 0xffff0000, v214
	v_lshlrev_b32_e32 v72, 16, v215
	v_and_b32_e32 v73, 0xffff0000, v215
	v_fma_f32 v72, v53, v72, v54
	v_fma_f32 v73, v53, v73, v54
	v_fma_f32 v76, v53, v76, v54
	v_fma_f32 v77, v53, v77, v54
	v_fma_f32 v72, v66, v72, v70
	v_fma_f32 v73, v67, v73, v71
	v_fma_f32 v76, v64, v76, v68
	v_fma_f32 v77, v65, v77, v69
	v_fma_f32 v30, v72, s10, v30
	v_fma_f32 v31, v73, s10, v31
	v_fma_f32 v28, v76, s10, v28
	v_fma_f32 v29, v77, s10, v29
	v_add_f32_e32 v72, v31, v30
	v_add_f32_e32 v55, v28, v29
	v_add_f32_e32 v55, v55, v72
	v_mul_f32_e32 v72, v29, v29
	v_mul_f32_e32 v73, v30, v30
	v_lshlrev_b32_e32 v78, 16, v216
	v_and_b32_e32 v79, 0xffff0000, v216
	v_lshlrev_b32_e32 v74, 16, v217
	v_and_b32_e32 v75, 0xffff0000, v217
	v_add_f32_e32 v55, 0, v55
	v_fmac_f32_e32 v72, v28, v28
	v_fmac_f32_e32 v73, v31, v31
	v_add_f32_e32 v76, v72, v73
	v_fma_f32 v72, v53, v74, v54
	v_fma_f32 v73, v53, v75, v54
	v_fma_f32 v74, v53, v78, v54
	v_fma_f32 v75, v53, v79, v54
	v_fma_f32 v72, v58, v72, v62
	v_fma_f32 v73, v59, v73, v63
	v_fma_f32 v74, v56, v74, v60
	v_fma_f32 v75, v57, v75, v61
	v_fma_f32 v72, v72, s10, v26
	v_fma_f32 v73, v73, s10, v27
	v_fma_f32 v26, v74, s10, v24
	v_fma_f32 v27, v75, s10, v25
	v_add_f32_e32 v25, v73, v72
	v_add_f32_e32 v24, v26, v27
	v_add_f32_e32 v24, v24, v25
	v_add_f32_e32 v55, v24, v55
	v_mul_f32_e32 v24, v27, v27
	v_mul_f32_e32 v25, v72, v72
	v_fmac_f32_e32 v24, v26, v26
	v_fmac_f32_e32 v25, v73, v73
	v_add_f32_e32 v24, v24, v25
	v_add_f32_e32 v74, v76, v24
	v_cvt_pk_bf16_f32 v24, v28, v29
	v_cvt_pk_bf16_f32 v25, v30, v31
	v_cvt_pk_bf16_f32 v26, v26, v27
	v_cvt_pk_bf16_f32 v27, v72, v73
	global_store_dwordx4 v[34:35], v[24:27], off
	s_waitcnt vmcnt(8)
	v_lshlrev_b32_e32 v28, 16, v218
	v_and_b32_e32 v29, 0xffff0000, v218
	v_lshlrev_b32_e32 v24, 16, v219
	v_and_b32_e32 v25, 0xffff0000, v219
	v_fma_f32 v24, v53, v24, v54
	v_fma_f32 v25, v53, v25, v54
	v_fma_f32 v28, v53, v28, v54
	v_fma_f32 v29, v53, v29, v54
	v_fma_f32 v24, v46, v24, v50
	v_fma_f32 v25, v47, v25, v51
	v_fma_f32 v28, v44, v28, v48
	v_fma_f32 v29, v45, v29, v49
	v_fma_f32 v22, v24, s10, v22
	v_fma_f32 v23, v25, s10, v23
	v_fma_f32 v20, v28, s10, v20
	v_fma_f32 v21, v29, s10, v21
	v_add_f32_e32 v25, v23, v22
	v_add_f32_e32 v24, v20, v21
	v_add_f32_e32 v24, v24, v25
	v_add_f32_e32 v28, v55, v24
	v_mul_f32_e32 v24, v21, v21
	v_mul_f32_e32 v25, v22, v22
	v_fmac_f32_e32 v24, v20, v20
	v_fmac_f32_e32 v25, v23, v23
	v_lshlrev_b32_e32 v30, 16, v220
	v_and_b32_e32 v31, 0xffff0000, v220
	v_lshlrev_b32_e32 v26, 16, v221
	v_and_b32_e32 v27, 0xffff0000, v221
	v_add_f32_e32 v24, v24, v25
	v_add_f32_e32 v29, v74, v24
	v_fma_f32 v24, v53, v26, v54
	v_fma_f32 v25, v53, v27, v54
	v_fma_f32 v26, v53, v30, v54
	v_fma_f32 v27, v53, v31, v54
	v_fma_f32 v24, v38, v24, v42
	v_fma_f32 v25, v39, v25, v43
	v_fma_f32 v26, v36, v26, v40
	v_fma_f32 v27, v37, v27, v41
	v_fma_f32 v24, v24, s10, v18
	v_fma_f32 v25, v25, s10, v19
	v_fma_f32 v18, v26, s10, v16
	v_fma_f32 v19, v27, s10, v17
	v_add_f32_e32 v17, v25, v24
	v_add_f32_e32 v16, v18, v19
	v_add_f32_e32 v16, v16, v17
	v_add_f32_e32 v26, v16, v28
	v_mul_f32_e32 v16, v19, v19
	v_mul_f32_e32 v17, v24, v24
	v_fmac_f32_e32 v16, v18, v18
	v_fmac_f32_e32 v17, v25, v25
	v_add_f32_e32 v16, v16, v17
	v_add_f32_e32 v27, v16, v29
	v_cvt_pk_bf16_f32 v16, v20, v21
	v_cvt_pk_bf16_f32 v17, v22, v23
	v_cvt_pk_bf16_f32 v18, v18, v19
	v_cvt_pk_bf16_f32 v19, v24, v25
	global_store_dwordx4 v[34:35], v[16:19], off offset:256
	ds_swizzle_b32 v16, v26 offset:swizzle(SWAP,16)
	ds_swizzle_b32 v17, v27 offset:swizzle(SWAP,16)
	s_waitcnt lgkmcnt(1)
	v_add_f32_e32 v16, v26, v16
	s_waitcnt lgkmcnt(0)
	v_add_f32_e32 v17, v27, v17
	v_mov_b32_e32 v18, v16
	v_mov_b32_e32 v19, v17
	s_nop 0
	v_permlane32_swap_b32_e32 v16, v18
	v_permlane32_swap_b32_e32 v17, v19
	s_and_saveexec_b64 s[4:5], s[44:45]
	s_cbranch_execz .LBB0_596
	v_add_f32_e64 v16, v16, v18
	v_add_f32_e64 v17, v17, v19
	v_lshlrev_b64 v[18:19], 7, v[32:33]
	v_lshl_add_u64 v[18:19], s[20:21], 0, v[18:19]
	v_lshl_add_u64 v[18:19], s[36:37], 2, v[18:19]
	global_store_dwordx2 v[18:19], v[16:17], off
; __device__ __forceinline__ unsigned pk(float lo, float hi) { return pg8::cvt_pk_bf16(lo, hi); }
; template <int O> __device__ __forceinline__ float swz_xor(float v) { return __int_as_float(__builtin_amdgcn_ds_swizzle(__float_as_int(v), (O << 10) | 0x1f)); }
;     __device__ __forceinline__ void operator()(pg8::f32x4 (&acc)[2][2][4][2], const pg8::Unit& u, int wr, int wc, int fr, int fq) const {
;     ...
;             for (int m = 0; m < 4; ++m) { const int rl = ai * 128 + wr * 64 + m * 16 + fr; const f2v st = T[rl]; const float r = st.y, rm = -st.x * st.y;
;                 const size_t off = (size_t)(u.pm * 256 + rl) * DM + cb; float s1 = 0.f, s2 = 0.f;
; #pragma unroll
;                 for (int bj = 0; bj < 2; ++bj) { f4 pre[2]; float xin[8]; unpack8(*(const u32x4*)(XB + off + 128 * bj), xin);
; #pragma unroll
;                     for (int n = 0; n < 2; ++n) { const f4 v = {xin[4 * n], xin[4 * n + 1], xin[4 * n + 2], xin[4 * n + 3]}; const f4 xr = (v * r + rm) * gv[bj][n] + bv[bj][n];
;                         pre[n] = xr * alpha + acc[ai][bj][m][n]; if (X) *(f4*)(X + off + 128 * bj + 4 * n) = pre[n];
;                         s1 += (pre[n][0] + pre[n][1]) + (pre[n][2] + pre[n][3]); s2 += (pre[n][0] * pre[n][0] + pre[n][1] * pre[n][1]) + (pre[n][2] * pre[n][2] + pre[n][3] * pre[n][3]); }
;                     u32x4 w; w.x = pk(pre[0][0], pre[0][1]); w.y = pk(pre[0][2], pre[0][3]); w.z = pk(pre[1][0], pre[1][1]); w.w = pk(pre[1][2], pre[1][3]);
;                     if (!X) *(u32x4*)(XB + off + 128 * bj) = w; }
;                 s1 += swz_xor<16>(s1); s2 += swz_xor<16>(s2);
;                 { auto r1 = __builtin_amdgcn_permlane32_swap(__float_as_uint(s1), __float_as_uint(s1), false, false); s1 = __uint_as_float(r1[0]) + __uint_as_float(r1[1]);
;                   auto r2 = __builtin_amdgcn_permlane32_swap(__float_as_uint(s2), __float_as_uint(s2), false, false); s2 = __uint_as_float(r2[0]) + __uint_as_float(r2[1]); }
;                 if (fq == 0) *(f2v*)(SPout + (size_t)(u.pm * 256 + rl) * 32 + (u.pn * 4 + wc) * 2) = (f2v){s1, s2};
.LBB0_596:
	s_or_b64 exec, exec, s[4:5]
	v_add_u32_e32 v16, s0, v195
	v_ashrrev_i32_e32 v17, 31, v16
	v_lshlrev_b64 v[18:19], 11, v[16:17]
	v_lshl_add_u64 v[18:19], s[18:19], 0, v[18:19]
	v_lshl_add_u64 v[22:23], v[170:171], 1, v[18:19]
	ds_read_b64 v[24:25], v204
	s_waitcnt lgkmcnt(0)
	v_mul_f32_e64 v26, v25, -v24
	s_waitcnt vmcnt(6)
	v_lshlrev_b32_e32 v28, 16, v222
	v_and_b32_e32 v29, 0xffff0000, v222
	v_lshlrev_b32_e32 v18, 16, v223
	v_and_b32_e32 v19, 0xffff0000, v223
	v_lshlrev_b32_e32 v30, 16, v224
	v_and_b32_e32 v31, 0xffff0000, v224
	v_lshlrev_b32_e32 v20, 16, v225
	v_and_b32_e32 v21, 0xffff0000, v225
	v_fma_f32 v18, v25, v18, v26
	v_fma_f32 v19, v25, v19, v26
	v_fma_f32 v28, v25, v28, v26
	v_fma_f32 v29, v25, v29, v26
	v_fma_f32 v20, v25, v20, v26
	v_fma_f32 v21, v25, v21, v26
	v_fma_f32 v30, v25, v30, v26
	v_fma_f32 v31, v25, v31, v26
	v_fma_f32 v28, v64, v28, v68
	v_fma_f32 v29, v65, v29, v69
	v_fma_f32 v18, v66, v18, v70
	v_fma_f32 v19, v67, v19, v71
	v_fma_f32 v30, v56, v30, v60
	v_fma_f32 v31, v57, v31, v61
	v_fma_f32 v20, v58, v20, v62
	v_fma_f32 v21, v59, v21, v63
	v_fma_f32 v18, v18, s10, v14
	v_fma_f32 v19, v19, s10, v15
	v_fma_f32 v28, v28, s10, v12
	v_fma_f32 v29, v29, s10, v13
	v_fma_f32 v20, v20, s10, v10
	v_fma_f32 v21, v21, s10, v11
	v_fma_f32 v30, v30, s10, v8
	v_fma_f32 v31, v31, s10, v9
	v_cvt_pk_bf16_f32 v8, v28, v29
	v_cvt_pk_bf16_f32 v9, v18, v19
	v_add_f32_e32 v27, v28, v29
	v_cvt_pk_bf16_f32 v10, v30, v31
	v_cvt_pk_bf16_f32 v11, v20, v21
	v_add_f32_e32 v32, v19, v18
	v_mul_f32_e32 v29, v29, v29
	v_mul_f32_e32 v18, v18, v18
	v_add_f32_e32 v33, v30, v31
	v_add_f32_e32 v34, v21, v20
	v_mul_f32_e32 v31, v31, v31
	v_mul_f32_e32 v20, v20, v20
	v_add_f32_e32 v27, v27, v32
	v_fmac_f32_e32 v29, v28, v28
	v_fmac_f32_e32 v18, v19, v19
	v_fmac_f32_e32 v31, v30, v30
	v_fmac_f32_e32 v20, v21, v21
	v_add_f32_e32 v19, v33, v34
	global_store_dwordx4 v[22:23], v[8:11], off
	s_nop 1
	v_add_f32_e32 v8, 0, v27
	v_add_f32_e32 v9, v29, v18
	v_add_f32_e32 v10, v31, v20
	v_add_f32_e32 v18, v19, v8
	v_add_f32_e32 v19, v9, v10
	s_waitcnt vmcnt(6)
	v_lshlrev_b32_e32 v8, 16, v226
	v_and_b32_e32 v9, 0xffff0000, v226
	v_lshlrev_b32_e32 v10, 16, v227
	v_and_b32_e32 v11, 0xffff0000, v227
	v_lshlrev_b32_e32 v12, 16, v228
	v_and_b32_e32 v13, 0xffff0000, v228
	v_lshlrev_b32_e32 v14, 16, v229
	v_and_b32_e32 v15, 0xffff0000, v229
	v_fma_f32 v10, v25, v10, v26
	v_fma_f32 v11, v25, v11, v26
	v_fma_f32 v8, v25, v8, v26
	v_fma_f32 v9, v25, v9, v26
	v_fma_f32 v14, v25, v14, v26
	v_fma_f32 v15, v25, v15, v26
	v_fma_f32 v12, v25, v12, v26
	v_fma_f32 v13, v25, v13, v26
	v_fma_f32 v8, v44, v8, v48
	v_fma_f32 v9, v45, v9, v49
	v_fma_f32 v10, v46, v10, v50
	v_fma_f32 v11, v47, v11, v51
	v_fma_f32 v12, v36, v12, v40
	v_fma_f32 v13, v37, v13, v41
	v_fma_f32 v14, v38, v14, v42
	v_fma_f32 v15, v39, v15, v43
	v_fma_f32 v6, v10, s10, v6
	v_fma_f32 v7, v11, s10, v7
	v_fma_f32 v4, v8, s10, v4
	v_fma_f32 v5, v9, s10, v5
	v_fma_f32 v8, v14, s10, v2
	v_fma_f32 v9, v15, s10, v3
	v_fma_f32 v2, v12, s10, v0
	v_fma_f32 v3, v13, s10, v1
	v_mul_f32_e32 v12, v5, v5
	v_mul_f32_e32 v13, v6, v6
	v_add_f32_e32 v10, v4, v5
	v_add_f32_e32 v11, v7, v6
	v_mul_f32_e32 v20, v3, v3
	v_mul_f32_e32 v21, v8, v8
	v_fmac_f32_e32 v12, v4, v4
	v_fmac_f32_e32 v13, v7, v7
	v_add_f32_e32 v14, v2, v3
	v_add_f32_e32 v15, v9, v8
	v_cvt_pk_bf16_f32 v0, v4, v5
	v_cvt_pk_bf16_f32 v1, v6, v7
	v_add_f32_e32 v5, v10, v11
	v_fmac_f32_e32 v20, v2, v2
	v_fmac_f32_e32 v21, v9, v9
	v_add_f32_e32 v6, v12, v13
	v_add_f32_e32 v4, v14, v15
	v_add_f32_e32 v5, v18, v5
	v_add_f32_e32 v7, v20, v21
	v_add_f32_e32 v6, v19, v6
	v_add_f32_e32 v4, v4, v5
	v_add_f32_e32 v5, v7, v6
	ds_swizzle_b32 v6, v4 offset:swizzle(SWAP,16)
	ds_swizzle_b32 v7, v5 offset:swizzle(SWAP,16)
	v_cvt_pk_bf16_f32 v2, v2, v3
	v_cvt_pk_bf16_f32 v3, v8, v9
	global_store_dwordx4 v[22:23], v[0:3], off offset:256
	s_waitcnt lgkmcnt(1)
	s_nop 0
	v_add_f32_e32 v0, v4, v6
	s_waitcnt lgkmcnt(0)
	v_add_f32_e32 v1, v5, v7
	v_mov_b32_e32 v2, v0
	v_mov_b32_e32 v3, v1
	s_nop 0
	v_permlane32_swap_b32_e32 v0, v2
	v_permlane32_swap_b32_e32 v1, v3
	s_and_saveexec_b64 s[4:5], s[44:45]
	s_cbranch_execz .LBB0_598
	v_add_f32_e64 v0, v0, v2
	v_add_f32_e64 v1, v1, v3
	v_lshlrev_b64 v[2:3], 7, v[16:17]
	v_lshl_add_u64 v[2:3], s[20:21], 0, v[2:3]
	v_lshl_add_u64 v[2:3], s[36:37], 2, v[2:3]
	global_store_dwordx2 v[2:3], v[0:1], off

; #define LAS __attribute__((address_space(3)))
; __device__ __forceinline__ void row_stats_to_lds(const float* SP, int pm, LAS f2v* T, int tid) {
;     if (tid < 256) { const f32x4* p = (const f32x4*)(SP + (size_t)(pm * 256 + tid) * 32); float s1 = 0.f, s2 = 0.f;
; #pragma unroll
;         for (int k = 0; k < 8; ++k) { const f32x4 v = p[k]; s1 += v.x + v.z; s2 += v.y + v.w; }
;         const float mu = s1 * (1.f / DM), var = s2 * (1.f / DM) - mu * mu;
;         T[tid] = (f2v){mu, 1.f / sqrtf(var + LN_EPS)}; }
;     asm volatile("s_waitcnt lgkmcnt(0)" ::: "memory"); __builtin_amdgcn_s_barrier(); asm volatile("" ::: "memory");
; }
;     __device__ __forceinline__ void operator()(pg8::f32x4 (&acc)[2][2][4][2], const pg8::Unit& u, int wr, int wc, int fr, int fq) const {
;     ...
;         row_stats_to_lds(SPin, u.pm, T, (wr * 4 + wc) * 64 + fq * 16 + fr);
;         const int cb = u.pn * 256 + wc * 32 + 8 * fq;
;         f4 gv[2][2], bv[2][2];
; #pragma unroll
;         for (int bj = 0; bj < 2; ++bj)
; #pragma unroll
;             for (int n = 0; n < 2; ++n) { gv[bj][n] = *(const f4*)(g + cb + 128 * bj + 4 * n); bv[bj][n] = *(const f4*)(b + cb + 128 * bj + 4 * n); }
; #pragma unroll
;         for (int ai = 0; ai < 2; ++ai)
; #pragma unroll
;             for (int m = 0; m < 4; ++m) { const int rl = ai * 128 + wr * 64 + m * 16 + fr; const f2v st = T[rl]; const float r = st.y, rm = -st.x * st.y;
;                 const size_t off = (size_t)(u.pm * 256 + rl) * DM + cb; float s1 = 0.f, s2 = 0.f;
; #pragma unroll
;                 for (int bj = 0; bj < 2; ++bj) { f4 pre[2]; float xin[8]; unpack8(*(const u32x4*)(XB + off + 128 * bj), xin);
; #pragma unroll
;                     for (int n = 0; n < 2; ++n) { const f4 v = {xin[4 * n], xin[4 * n + 1], xin[4 * n + 2], xin[4 * n + 3]}; const f4 xr = (v * r + rm) * gv[bj][n] + bv[bj][n];
;                         pre[n] = xr * alpha + acc[ai][bj][m][n]; if (X) *(f4*)(X + off + 128 * bj + 4 * n) = pre[n];
.LBB0_835:
	s_lshl_b32 s72, s72, 8
	s_and_saveexec_b64 s[36:37], s[40:41]
	s_cbranch_execz .LBB0_837
	v_add_u32_e32 v56, s72, v201
	v_ashrrev_i32_e32 v57, 31, v56
	v_lshlrev_b64 v[56:57], 7, v[56:57]
	v_lshl_add_u64 v[92:93], s[16:17], 0, v[56:57]
	global_load_dwordx4 v[56:59], v[92:93], off
	global_load_dwordx4 v[60:63], v[92:93], off offset:16
	global_load_dwordx4 v[64:67], v[92:93], off offset:32
	global_load_dwordx4 v[68:71], v[92:93], off offset:48
	global_load_dwordx4 v[76:79], v[92:93], off offset:64
	global_load_dwordx4 v[80:83], v[92:93], off offset:80
	global_load_dwordx4 v[88:91], v[92:93], off offset:96
	s_nop 0
	global_load_dwordx4 v[92:95], v[92:93], off offset:112
	s_mov_b32 s0, 0x3a800000
	s_waitcnt vmcnt(0)
	v_add_f32_e64 v56, v56, v58
	v_add_f32_e64 v57, v57, v59
	v_add_f32_e64 v58, v60, v62
	v_add_f32_e64 v59, v61, v63
	v_add_f32_e64 v56, v56, 0
	v_add_f32_e64 v57, v57, 0
	v_add_f32_e64 v60, v64, v66
	v_add_f32_e64 v61, v65, v67
	v_add_f32_e64 v56, v56, v58
	v_add_f32_e64 v57, v57, v59
	v_add_f32_e64 v62, v68, v70
	v_add_f32_e64 v63, v69, v71
	v_add_f32_e64 v56, v56, v60
	v_add_f32_e64 v57, v57, v61
	v_add_f32_e64 v64, v76, v78
	v_add_f32_e64 v65, v77, v79
	v_add_f32_e64 v56, v56, v62
	v_add_f32_e64 v57, v57, v63
	v_add_f32_e64 v66, v80, v82
	v_add_f32_e64 v67, v81, v83
	v_add_f32_e64 v56, v56, v64
	v_add_f32_e64 v57, v57, v65
	v_add_f32_e64 v68, v88, v90
	v_add_f32_e64 v69, v89, v91
	v_add_f32_e64 v56, v56, v66
	v_add_f32_e64 v57, v57, v67
	v_add_f32_e64 v70, v92, v94
	v_add_f32_e64 v71, v93, v95
	v_add_f32_e64 v56, v56, v68
	v_add_f32_e64 v57, v57, v69
	s_nop 0
	v_add_f32_e64 v56, v56, v70
	v_add_f32_e64 v57, v57, v71
	s_nop 0
	v_mul_f32_e64 v56, v56, s0
	v_mul_f32_e64 v57, v57, s0
	s_nop 0
	v_fma_f32 v57, -v56, v56, v57
	v_add_f32_e32 v57, 0x358637bd, v57
	v_mul_f32_e32 v58, 0x4f800000, v57
	v_cmp_gt_f32_e32 vcc, s11, v57
	s_nop 1
	v_cndmask_b32_e32 v57, v57, v58, vcc
	v_sqrt_f32_e32 v58, v57
	s_nop 0
	v_add_u32_e32 v59, -1, v58
	v_add_u32_e32 v60, 1, v58
	v_fma_f32 v61, -v59, v58, v57
	v_fma_f32 v62, -v60, v58, v57
	v_cmp_ge_f32_e64 s[46:47], 0, v61
	s_nop 1
	v_cndmask_b32_e64 v58, v58, v59, s[46:47]
	v_cmp_lt_f32_e64 s[46:47], 0, v62
	s_nop 1
	v_cndmask_b32_e64 v58, v58, v60, s[46:47]
	v_mul_f32_e32 v59, 0x37800000, v58
	v_cndmask_b32_e32 v58, v58, v59, vcc
	v_cmp_class_f32_e32 vcc, v57, v231
	s_nop 1
	v_cndmask_b32_e32 v57, v58, v57, vcc
	v_div_scale_f32 v58, s[0:1], v57, v57, 1.0
	v_rcp_f32_e32 v59, v58
	v_div_scale_f32 v60, vcc, 1.0, v57, 1.0
	v_fma_f32 v61, -v58, v59, 1.0
	v_fmac_f32_e32 v59, v61, v59
	v_mul_f32_e32 v61, v60, v59
	v_fma_f32 v62, -v58, v61, v60
	v_fmac_f32_e32 v61, v62, v59
	v_fma_f32 v58, -v58, v61, v60
	v_div_fmas_f32 v58, v58, v59, v61
	v_div_fixup_f32 v57, v58, v57, 1.0
	ds_write_b64 v209, v[56:57]
.LBB0_837:
	s_or_b64 exec, exec, s[36:37]
	v_add_u32_e32 v176, s72, v198
	v_lshl_or_b32 v174, s73, 8, v200
	v_ashrrev_i32_e32 v177, 31, v176
	v_ashrrev_i32_e32 v175, 31, v174
	v_lshlrev_b64 v[56:57], 10, v[176:177]
	v_lshl_add_u64 v[180:181], v[56:57], 0, v[174:175]
	s_waitcnt lgkmcnt(0)
	s_barrier
	v_lshl_add_u64 v[178:179], v[180:181], 1, s[14:15]
	v_add_u32_e32 v226, s72, v198
	v_ashrrev_i32_e32 v227, 31, v226
	v_lshlrev_b64 v[228:229], 10, v[226:227]
	v_lshl_add_u64 v[228:229], v[228:229], 0, v[174:175]
	v_lshl_add_u64 v[226:227], v[228:229], 1, s[14:15]
	global_load_dwordx4 v[222:225], v[226:227], off
	global_load_dwordx4 v[226:229], v[226:227], off offset:256
	v_add_u32_e32 v242, s72, v202
	v_ashrrev_i32_e32 v243, 31, v242
	v_lshlrev_b64 v[244:245], 10, v[242:243]
	v_lshl_add_u64 v[244:245], v[244:245], 0, v[174:175]
	v_lshl_add_u64 v[242:243], v[244:245], 1, s[14:15]
	global_load_dwordx4 v[238:241], v[242:243], off
	global_load_dwordx4 v[242:245], v[242:243], off offset:256
	v_lshlrev_b64 v[56:57], 2, v[174:175]
	v_lshl_add_u64 v[60:61], s[20:21], 0, v[56:57]
	v_lshl_add_u64 v[68:69], s[22:23], 0, v[56:57]
	global_load_dwordx4 v[76:79], v[60:61], off offset:16
	global_load_dwordx4 v[88:91], v[60:61], off
	global_load_dwordx4 v[92:95], v[68:69], off
	global_load_dwordx4 v[80:83], v[68:69], off offset:16
	global_load_dwordx4 v[56:59], v[60:61], off offset:528
	global_load_dwordx4 v[64:67], v[60:61], off offset:512
	s_nop 0
	global_load_dwordx4 v[60:63], v[68:69], off offset:528
	s_nop 0
	global_load_dwordx4 v[68:71], v[68:69], off offset:512
	ds_read_b64 v[182:183], v210
	v_cndmask_b32_e64 v184, 0, 1, s[28:29]
	v_cmp_ne_u32_e64 s[46:47], 1, v184
	s_mov_b64 s[36:37], 0
	s_andn2_b64 vcc, exec, s[28:29]
	s_waitcnt lgkmcnt(0)
	v_mul_f32_e64 v184, v183, -v182
	s_waitcnt vmcnt(0)
	v_lshlrev_b32_e32 v186, 16, v222
	v_and_b32_e32 v187, 0xffff0000, v222
	v_lshlrev_b32_e32 v160, 16, v223
	v_and_b32_e32 v161, 0xffff0000, v223
	v_fma_f32 v186, v183, v186, v184
	v_fma_f32 v187, v183, v187, v184
	v_fma_f32 v160, v183, v160, v184
	v_fma_f32 v161, v183, v161, v184
	v_fma_f32 v186, v88, v186, v92
	v_fma_f32 v187, v89, v187, v93
	v_fma_f32 v160, v90, v160, v94
	v_fma_f32 v161, v91, v161, v95
	v_fma_f32 v156, v186, s10, v156
	v_fma_f32 v157, v187, s10, v157
	v_fma_f32 v158, v160, s10, v158
	v_fma_f32 v159, v161, s10, v159
	v_lshl_add_u64 v[186:187], v[180:181], 2, s[52:53]
	s_cbranch_vccnz .LBB0_839
	s_mov_b64 s[36:37], s[52:53]
	global_store_dwordx4 v[186:187], v[156:159], off
.LBB0_839:
	v_mov_b32_e32 v182, v183
	v_mov_b32_e32 v185, v184
	v_lshlrev_b32_e32 v160, 16, v224
	v_and_b32_e32 v161, 0xffff0000, v224
	v_lshlrev_b32_e32 v162, 16, v225
	v_and_b32_e32 v163, 0xffff0000, v225
	v_mov_b32_e32 v194, v184
	v_mov_b32_e32 v195, v184
	v_mov_b32_e32 v196, v183
	v_mov_b32_e32 v197, v183
	v_fma_f32 v162, v196, v162, v194
	v_fma_f32 v163, v197, v163, v195
	v_fma_f32 v160, v182, v160, v184
	v_fma_f32 v161, v183, v161, v185
	v_fma_f32 v162, v78, v162, v82
	v_fma_f32 v163, v79, v163, v83
	v_fma_f32 v160, v76, v160, v80
	v_fma_f32 v161, v77, v161, v81
	v_fma_f32 v154, v162, s10, v154
	v_fma_f32 v155, v163, s10, v155
	s_cmp_eq_u64 s[36:37], 0
	v_fma_f32 v152, v160, s10, v152
	v_fma_f32 v153, v161, s10, v153
	s_cbranch_scc1 .LBB0_841
	v_lshl_add_u64 v[160:161], v[180:181], 2, s[36:37]
	global_store_dwordx4 v[160:161], v[152:155], off offset:16

;     __device__ __forceinline__ void operator()(pg8::f32x4 (&acc)[2][2][4][2], const pg8::Unit& u, int wr, int wc, int fr, int fq) const {
;     ...
;             for (int m = 0; m < 4; ++m) { const int rl = ai * 128 + wr * 64 + m * 16 + fr; const f2v st = T[rl]; const float r = st.y, rm = -st.x * st.y;
;                 const size_t off = (size_t)(u.pm * 256 + rl) * DM + cb; float s1 = 0.f, s2 = 0.f;
; #pragma unroll
;                 for (int bj = 0; bj < 2; ++bj) { f4 pre[2]; float xin[8]; unpack8(*(const u32x4*)(XB + off + 128 * bj), xin);
; #pragma unroll
;                     for (int n = 0; n < 2; ++n) { const f4 v = {xin[4 * n], xin[4 * n + 1], xin[4 * n + 2], xin[4 * n + 3]}; const f4 xr = (v * r + rm) * gv[bj][n] + bv[bj][n];
;                         pre[n] = xr * alpha + acc[ai][bj][m][n]; if (X) *(f4*)(X + off + 128 * bj + 4 * n) = pre[n];
;                         s1 += (pre[n][0] + pre[n][1]) + (pre[n][2] + pre[n][3]); s2 += (pre[n][0] * pre[n][0] + pre[n][1] * pre[n][1]) + (pre[n][2] * pre[n][2] + pre[n][3] * pre[n][3]); }
.LBB0_843:
	v_mov_b32_e32 v194, v184
	v_mov_b32_e32 v195, v184
	v_mov_b32_e32 v196, v183
	v_mov_b32_e32 v197, v183
	s_and_b64 vcc, exec, s[46:47]
	s_mov_b64 s[4:5], 0
	s_waitcnt vmcnt(11)
	v_lshlrev_b32_e32 v220, 16, v226
	v_and_b32_e32 v221, 0xffff0000, v226
	v_lshlrev_b32_e32 v160, 16, v227
	v_and_b32_e32 v161, 0xffff0000, v227
	v_fma_f32 v160, v196, v160, v194
	v_fma_f32 v161, v197, v161, v195
	v_fma_f32 v220, v182, v220, v184
	v_fma_f32 v221, v183, v221, v185
	v_fma_f32 v160, v66, v160, v70
	v_fma_f32 v161, v67, v161, v71
	v_fma_f32 v220, v64, v220, v68
	v_fma_f32 v221, v65, v221, v69
	v_fma_f32 v150, v160, s10, v150
	v_fma_f32 v151, v161, s10, v151
	v_fma_f32 v148, v220, s10, v148
	v_fma_f32 v149, v221, s10, v149
	s_cbranch_vccnz .LBB0_845
	s_mov_b64 s[4:5], s[52:53]
	global_store_dwordx4 v[186:187], v[148:151], off offset:512
.LBB0_845:
	v_lshlrev_b32_e32 v160, 16, v228
	v_and_b32_e32 v161, 0xffff0000, v228
	v_lshlrev_b32_e32 v162, 16, v229
	v_and_b32_e32 v163, 0xffff0000, v229
	v_add_u32_e32 v226, s72, v203
	v_ashrrev_i32_e32 v227, 31, v226
	v_lshlrev_b64 v[228:229], 10, v[226:227]
	v_lshl_add_u64 v[228:229], v[228:229], 0, v[174:175]
	v_lshl_add_u64 v[226:227], v[228:229], 1, s[14:15]
	global_load_dwordx4 v[222:225], v[226:227], off
	global_load_dwordx4 v[226:229], v[226:227], off offset:256
	v_fma_f32 v162, v196, v162, v194
	v_fma_f32 v163, v197, v163, v195
	v_fma_f32 v160, v182, v160, v184
	v_fma_f32 v161, v183, v161, v185
	v_fma_f32 v162, v58, v162, v62
	v_fma_f32 v163, v59, v163, v63
	v_fma_f32 v160, v56, v160, v60
	v_fma_f32 v161, v57, v161, v61
	v_fma_f32 v146, v162, s10, v146
	v_fma_f32 v147, v163, s10, v147
	s_cmp_eq_u64 s[4:5], 0
	v_fma_f32 v144, v160, s10, v144
	v_fma_f32 v145, v161, s10, v145
	s_cbranch_scc1 .LBB0_847
	v_lshl_add_u64 v[160:161], v[180:181], 2, s[4:5]
	global_store_dwordx4 v[160:161], v[144:147], off offset:528

; __device__ __forceinline__ unsigned pk(float lo, float hi) { return pg8::cvt_pk_bf16(lo, hi); }
; template <int O> __device__ __forceinline__ float swz_xor(float v) { return __int_as_float(__builtin_amdgcn_ds_swizzle(__float_as_int(v), (O << 10) | 0x1f)); }
;     __device__ __forceinline__ void operator()(pg8::f32x4 (&acc)[2][2][4][2], const pg8::Unit& u, int wr, int wc, int fr, int fq) const {
;     ...
;             for (int m = 0; m < 4; ++m) { const int rl = ai * 128 + wr * 64 + m * 16 + fr; const f2v st = T[rl]; const float r = st.y, rm = -st.x * st.y;
;                 const size_t off = (size_t)(u.pm * 256 + rl) * DM + cb; float s1 = 0.f, s2 = 0.f;
; #pragma unroll
;                 for (int bj = 0; bj < 2; ++bj) { f4 pre[2]; float xin[8]; unpack8(*(const u32x4*)(XB + off + 128 * bj), xin);
; #pragma unroll
;                     for (int n = 0; n < 2; ++n) { const f4 v = {xin[4 * n], xin[4 * n + 1], xin[4 * n + 2], xin[4 * n + 3]}; const f4 xr = (v * r + rm) * gv[bj][n] + bv[bj][n];
;                         pre[n] = xr * alpha + acc[ai][bj][m][n]; if (X) *(f4*)(X + off + 128 * bj + 4 * n) = pre[n];
;                         s1 += (pre[n][0] + pre[n][1]) + (pre[n][2] + pre[n][3]); s2 += (pre[n][0] * pre[n][0] + pre[n][1] * pre[n][1]) + (pre[n][2] * pre[n][2] + pre[n][3] * pre[n][3]); }
;                     u32x4 w; w.x = pk(pre[0][0], pre[0][1]); w.y = pk(pre[0][2], pre[0][3]); w.z = pk(pre[1][0], pre[1][1]); w.w = pk(pre[1][2], pre[1][3]);
;                     if (!X) *(u32x4*)(XB + off + 128 * bj) = w; }
;                 s1 += swz_xor<16>(s1); s2 += swz_xor<16>(s2);
;                 { auto r1 = __builtin_amdgcn_permlane32_swap(__float_as_uint(s1), __float_as_uint(s1), false, false); s1 = __uint_as_float(r1[0]) + __uint_as_float(r1[1]);
;                   auto r2 = __builtin_amdgcn_permlane32_swap(__float_as_uint(s2), __float_as_uint(s2), false, false); s2 = __uint_as_float(r2[0]) + __uint_as_float(r2[1]); }
;                 if (fq == 0) *(f2v*)(SPout + (size_t)(u.pm * 256 + rl) * 32 + (u.pn * 4 + wc) * 2) = (f2v){s1, s2};
.LBB0_849:
	s_nop 1
	v_add_f32_e32 v160, v156, v157
	v_mul_f32_e32 v157, v157, v157
	v_fmac_f32_e32 v157, v156, v156
	v_mul_f32_e32 v156, v158, v158
	v_fmac_f32_e32 v156, v159, v159
	v_add_f32_e32 v156, v157, v156
	v_add_f32_e32 v157, v152, v153
	v_mul_f32_e32 v153, v153, v153
	v_fmac_f32_e32 v153, v152, v152
	v_mul_f32_e32 v152, v154, v154
	v_fmac_f32_e32 v152, v155, v155
	v_add_f32_e32 v152, v153, v152
	v_add_f32_e32 v153, v148, v149
	v_mul_f32_e32 v149, v149, v149
	v_fmac_f32_e32 v149, v148, v148
	v_mul_f32_e32 v148, v150, v150
	v_add_f32_e32 v161, v159, v158
	v_fmac_f32_e32 v148, v151, v151
	v_add_f32_e32 v160, v160, v161
	v_add_f32_e32 v158, v155, v154
	v_add_f32_e32 v148, v149, v148
	v_add_f32_e32 v149, v144, v145
	v_mul_f32_e32 v145, v145, v145
	v_add_f32_e32 v160, 0, v160
	v_add_f32_e32 v157, v157, v158
	v_add_f32_e32 v154, v151, v150
	v_fmac_f32_e32 v145, v144, v144
	v_mul_f32_e32 v144, v146, v146
	v_add_f32_e32 v157, v157, v160
	v_add_f32_e32 v152, v156, v152
	v_add_f32_e32 v153, v153, v154
	v_add_f32_e32 v150, v147, v146
	v_fmac_f32_e32 v144, v147, v147
	v_add_f32_e32 v153, v157, v153
	v_add_f32_e32 v148, v152, v148
	v_add_f32_e32 v149, v149, v150
	v_add_f32_e32 v144, v145, v144
	v_add_f32_e32 v149, v149, v153
	v_add_f32_e32 v145, v144, v148
	ds_swizzle_b32 v144, v149 offset:swizzle(SWAP,16)
	ds_swizzle_b32 v146, v145 offset:swizzle(SWAP,16)
	s_lshl_b32 s0, s73, 3
	s_or_b32 s36, s0, s69
	s_ashr_i32 s37, s36, 31
	s_waitcnt lgkmcnt(1)
	v_add_f32_e32 v144, v149, v144
	s_waitcnt lgkmcnt(0)
	v_add_f32_e32 v145, v145, v146
	v_mov_b32_e32 v146, v144
	v_mov_b32_e32 v147, v145
	s_nop 0
	v_permlane32_swap_b32_e32 v144, v146
	v_permlane32_swap_b32_e32 v145, v147
	s_and_saveexec_b64 s[0:1], s[42:43]
	s_cbranch_execz .LBB0_851
	v_add_f32_e64 v144, v144, v146
	v_add_f32_e64 v145, v145, v147
	v_lshlrev_b64 v[146:147], 7, v[176:177]
	v_lshl_add_u64 v[146:147], s[18:19], 0, v[146:147]
	v_lshl_add_u64 v[146:147], s[36:37], 2, v[146:147]
	global_store_dwordx2 v[146:147], v[144:145], off
.LBB0_851:
	s_or_b64 exec, exec, s[0:1]
	v_add_u32_e32 v148, s72, v202
	v_ashrrev_i32_e32 v149, 31, v148
	v_lshlrev_b64 v[144:145], 10, v[148:149]
	v_lshl_add_u64 v[152:153], v[144:145], 0, v[174:175]
	v_lshl_add_u64 v[150:151], v[152:153], 1, s[14:15]
	ds_read_b64 v[154:155], v211
	s_mov_b64 s[38:39], 0
	s_and_b64 vcc, exec, s[46:47]
	s_waitcnt lgkmcnt(0)
	v_mul_f32_e64 v156, v155, -v154
	s_waitcnt vmcnt(13)
	v_lshlrev_b32_e32 v158, 16, v238
	v_and_b32_e32 v159, 0xffff0000, v238
	v_lshlrev_b32_e32 v144, 16, v239
	v_and_b32_e32 v145, 0xffff0000, v239
	v_fma_f32 v144, v155, v144, v156
	v_fma_f32 v145, v155, v145, v156
	v_fma_f32 v158, v155, v158, v156
	v_fma_f32 v159, v155, v159, v156
	v_fma_f32 v144, v90, v144, v94
	v_fma_f32 v145, v91, v145, v95
	v_fma_f32 v158, v88, v158, v92
	v_fma_f32 v159, v89, v159, v93
	v_fma_f32 v142, v144, s10, v142
	v_fma_f32 v143, v145, s10, v143
	v_fma_f32 v140, v158, s10, v140
	v_fma_f32 v141, v159, s10, v141
	v_lshl_add_u64 v[158:159], v[152:153], 2, s[52:53]
	s_cbranch_vccnz .LBB0_853
	s_mov_b64 s[38:39], s[52:53]
	global_store_dwordx4 v[158:159], v[140:143], off
.LBB0_853:
	v_mov_b32_e32 v154, v155
	v_mov_b32_e32 v157, v156
	v_lshlrev_b32_e32 v144, 16, v240
	v_and_b32_e32 v145, 0xffff0000, v240
	v_lshlrev_b32_e32 v146, 16, v241
	v_and_b32_e32 v147, 0xffff0000, v241
	v_mov_b32_e32 v160, v156
	v_mov_b32_e32 v161, v156
	v_mov_b32_e32 v162, v155
	v_mov_b32_e32 v163, v155
	v_fma_f32 v146, v162, v146, v160
	v_fma_f32 v147, v163, v147, v161
	v_fma_f32 v144, v154, v144, v156
	v_fma_f32 v145, v155, v145, v157
	v_fma_f32 v146, v78, v146, v82
	v_fma_f32 v147, v79, v147, v83
	v_fma_f32 v144, v76, v144, v80
	v_fma_f32 v145, v77, v145, v81
	v_fma_f32 v138, v146, s10, v138
	v_fma_f32 v139, v147, s10, v139
	s_cmp_eq_u64 s[38:39], 0
	v_fma_f32 v136, v144, s10, v136
	v_fma_f32 v137, v145, s10, v137
	s_cbranch_scc1 .LBB0_855
	v_lshl_add_u64 v[144:145], v[152:153], 2, s[38:39]
	global_store_dwordx4 v[144:145], v[136:139], off offset:16

;     __device__ __forceinline__ void operator()(pg8::f32x4 (&acc)[2][2][4][2], const pg8::Unit& u, int wr, int wc, int fr, int fq) const {
;     ...
;             for (int m = 0; m < 4; ++m) { const int rl = ai * 128 + wr * 64 + m * 16 + fr; const f2v st = T[rl]; const float r = st.y, rm = -st.x * st.y;
;                 const size_t off = (size_t)(u.pm * 256 + rl) * DM + cb; float s1 = 0.f, s2 = 0.f;
; #pragma unroll
;                 for (int bj = 0; bj < 2; ++bj) { f4 pre[2]; float xin[8]; unpack8(*(const u32x4*)(XB + off + 128 * bj), xin);
; #pragma unroll
;                     for (int n = 0; n < 2; ++n) { const f4 v = {xin[4 * n], xin[4 * n + 1], xin[4 * n + 2], xin[4 * n + 3]}; const f4 xr = (v * r + rm) * gv[bj][n] + bv[bj][n];
;                         pre[n] = xr * alpha + acc[ai][bj][m][n]; if (X) *(f4*)(X + off + 128 * bj + 4 * n) = pre[n];
;                         s1 += (pre[n][0] + pre[n][1]) + (pre[n][2] + pre[n][3]); s2 += (pre[n][0] * pre[n][0] + pre[n][1] * pre[n][1]) + (pre[n][2] * pre[n][2] + pre[n][3] * pre[n][3]); }
.LBB0_857:
	v_mov_b32_e32 v160, v156
	v_mov_b32_e32 v161, v156
	v_mov_b32_e32 v162, v155
	v_mov_b32_e32 v163, v155
	s_and_b64 vcc, exec, s[46:47]
	s_mov_b64 s[4:5], 0
	s_waitcnt vmcnt(13)
	v_lshlrev_b32_e32 v176, 16, v242
	v_and_b32_e32 v177, 0xffff0000, v242
	v_lshlrev_b32_e32 v144, 16, v243
	v_and_b32_e32 v145, 0xffff0000, v243
	v_fma_f32 v144, v162, v144, v160
	v_fma_f32 v145, v163, v145, v161
	v_fma_f32 v176, v154, v176, v156
	v_fma_f32 v177, v155, v177, v157
	v_fma_f32 v144, v66, v144, v70
	v_fma_f32 v145, v67, v145, v71
	v_fma_f32 v176, v64, v176, v68
	v_fma_f32 v177, v65, v177, v69
	v_fma_f32 v134, v144, s10, v134
	v_fma_f32 v135, v145, s10, v135
	v_fma_f32 v132, v176, s10, v132
	v_fma_f32 v133, v177, s10, v133
	s_cbranch_vccnz .LBB0_859
	s_mov_b64 s[4:5], s[52:53]
	global_store_dwordx4 v[158:159], v[132:135], off offset:512
.LBB0_859:
	v_lshlrev_b32_e32 v144, 16, v244
	v_and_b32_e32 v145, 0xffff0000, v244
	v_lshlrev_b32_e32 v146, 16, v245
	v_and_b32_e32 v147, 0xffff0000, v245
	v_add_u32_e32 v242, s72, v204
	v_ashrrev_i32_e32 v243, 31, v242
	v_lshlrev_b64 v[244:245], 10, v[242:243]
	v_lshl_add_u64 v[244:245], v[244:245], 0, v[174:175]
	v_lshl_add_u64 v[242:243], v[244:245], 1, s[14:15]
	global_load_dwordx4 v[238:241], v[242:243], off
	global_load_dwordx4 v[242:245], v[242:243], off offset:256
	v_fma_f32 v146, v162, v146, v160
	v_fma_f32 v147, v163, v147, v161
	v_fma_f32 v144, v154, v144, v156
	v_fma_f32 v145, v155, v145, v157
	v_fma_f32 v146, v58, v146, v62
	v_fma_f32 v147, v59, v147, v63
	v_fma_f32 v144, v56, v144, v60
	v_fma_f32 v145, v57, v145, v61
	v_fma_f32 v130, v146, s10, v130
	v_fma_f32 v131, v147, s10, v131
	s_cmp_eq_u64 s[4:5], 0
	v_fma_f32 v128, v144, s10, v128
	v_fma_f32 v129, v145, s10, v129
	s_cbranch_scc1 .LBB0_861
	v_lshl_add_u64 v[144:145], v[152:153], 2, s[4:5]
	global_store_dwordx4 v[144:145], v[128:131], off offset:528

; __device__ __forceinline__ unsigned pk(float lo, float hi) { return pg8::cvt_pk_bf16(lo, hi); }
; template <int O> __device__ __forceinline__ float swz_xor(float v) { return __int_as_float(__builtin_amdgcn_ds_swizzle(__float_as_int(v), (O << 10) | 0x1f)); }
;     __device__ __forceinline__ void operator()(pg8::f32x4 (&acc)[2][2][4][2], const pg8::Unit& u, int wr, int wc, int fr, int fq) const {
;     ...
;             for (int m = 0; m < 4; ++m) { const int rl = ai * 128 + wr * 64 + m * 16 + fr; const f2v st = T[rl]; const float r = st.y, rm = -st.x * st.y;
;                 const size_t off = (size_t)(u.pm * 256 + rl) * DM + cb; float s1 = 0.f, s2 = 0.f;
; #pragma unroll
;                 for (int bj = 0; bj < 2; ++bj) { f4 pre[2]; float xin[8]; unpack8(*(const u32x4*)(XB + off + 128 * bj), xin);
; #pragma unroll
;                     for (int n = 0; n < 2; ++n) { const f4 v = {xin[4 * n], xin[4 * n + 1], xin[4 * n + 2], xin[4 * n + 3]}; const f4 xr = (v * r + rm) * gv[bj][n] + bv[bj][n];
;                         pre[n] = xr * alpha + acc[ai][bj][m][n]; if (X) *(f4*)(X + off + 128 * bj + 4 * n) = pre[n];
;                         s1 += (pre[n][0] + pre[n][1]) + (pre[n][2] + pre[n][3]); s2 += (pre[n][0] * pre[n][0] + pre[n][1] * pre[n][1]) + (pre[n][2] * pre[n][2] + pre[n][3] * pre[n][3]); }
;                     u32x4 w; w.x = pk(pre[0][0], pre[0][1]); w.y = pk(pre[0][2], pre[0][3]); w.z = pk(pre[1][0], pre[1][1]); w.w = pk(pre[1][2], pre[1][3]);
;                     if (!X) *(u32x4*)(XB + off + 128 * bj) = w; }
;                 s1 += swz_xor<16>(s1); s2 += swz_xor<16>(s2);
;                 { auto r1 = __builtin_amdgcn_permlane32_swap(__float_as_uint(s1), __float_as_uint(s1), false, false); s1 = __uint_as_float(r1[0]) + __uint_as_float(r1[1]);
;                   auto r2 = __builtin_amdgcn_permlane32_swap(__float_as_uint(s2), __float_as_uint(s2), false, false); s2 = __uint_as_float(r2[0]) + __uint_as_float(r2[1]); }
;                 if (fq == 0) *(f2v*)(SPout + (size_t)(u.pm * 256 + rl) * 32 + (u.pn * 4 + wc) * 2) = (f2v){s1, s2};
.LBB0_863:
	s_nop 1
	v_add_f32_e32 v144, v140, v141
	v_mul_f32_e32 v141, v141, v141
	v_fmac_f32_e32 v141, v140, v140
	v_mul_f32_e32 v140, v142, v142
	v_fmac_f32_e32 v140, v143, v143
	v_add_f32_e32 v140, v141, v140
	v_add_f32_e32 v141, v136, v137
	v_mul_f32_e32 v137, v137, v137
	v_fmac_f32_e32 v137, v136, v136
	v_mul_f32_e32 v136, v138, v138
	v_fmac_f32_e32 v136, v139, v139
	v_add_f32_e32 v136, v137, v136
	v_add_f32_e32 v137, v132, v133
	v_mul_f32_e32 v133, v133, v133
	v_fmac_f32_e32 v133, v132, v132
	v_mul_f32_e32 v132, v134, v134
	v_add_f32_e32 v145, v143, v142
	v_fmac_f32_e32 v132, v135, v135
	v_add_f32_e32 v144, v144, v145
	v_add_f32_e32 v142, v139, v138
	v_add_f32_e32 v132, v133, v132
	v_add_f32_e32 v133, v128, v129
	v_mul_f32_e32 v129, v129, v129
	v_add_f32_e32 v144, 0, v144
	v_add_f32_e32 v141, v141, v142
	v_add_f32_e32 v138, v135, v134
	v_fmac_f32_e32 v129, v128, v128
	v_mul_f32_e32 v128, v130, v130
	v_add_f32_e32 v141, v141, v144
	v_add_f32_e32 v136, v140, v136
	v_add_f32_e32 v137, v137, v138
	v_add_f32_e32 v134, v131, v130
	v_fmac_f32_e32 v128, v131, v131
	v_add_f32_e32 v137, v141, v137
	v_add_f32_e32 v132, v136, v132
	v_add_f32_e32 v133, v133, v134
	v_add_f32_e32 v128, v129, v128
	v_add_f32_e32 v133, v133, v137
	v_add_f32_e32 v129, v128, v132
	ds_swizzle_b32 v128, v133 offset:swizzle(SWAP,16)
	ds_swizzle_b32 v130, v129 offset:swizzle(SWAP,16)
	s_waitcnt lgkmcnt(1)
	v_add_f32_e32 v128, v133, v128
	s_waitcnt lgkmcnt(0)
	v_add_f32_e32 v129, v129, v130
	v_mov_b32_e32 v130, v128
	v_mov_b32_e32 v131, v129
	s_nop 0
	v_permlane32_swap_b32_e32 v128, v130
	v_permlane32_swap_b32_e32 v129, v131
	s_and_saveexec_b64 s[0:1], s[42:43]
	s_cbranch_execz .LBB0_865
	v_add_f32_e64 v128, v128, v130
	v_add_f32_e64 v129, v129, v131
	v_lshlrev_b64 v[130:131], 7, v[148:149]
	v_lshl_add_u64 v[130:131], s[18:19], 0, v[130:131]
	v_lshl_add_u64 v[130:131], s[36:37], 2, v[130:131]
	global_store_dwordx2 v[130:131], v[128:129], off
.LBB0_865:
	s_or_b64 exec, exec, s[0:1]
	v_add_u32_e32 v132, s72, v203
	v_ashrrev_i32_e32 v133, 31, v132
	v_lshlrev_b64 v[128:129], 10, v[132:133]
	v_lshl_add_u64 v[136:137], v[128:129], 0, v[174:175]
	v_lshl_add_u64 v[134:135], v[136:137], 1, s[14:15]
	ds_read_b64 v[138:139], v212
	s_mov_b64 s[38:39], 0
	s_and_b64 vcc, exec, s[46:47]
	s_waitcnt lgkmcnt(0)
	v_mul_f32_e64 v140, v139, -v138
	s_waitcnt vmcnt(6)
	v_lshlrev_b32_e32 v142, 16, v222
	v_and_b32_e32 v143, 0xffff0000, v222
	v_lshlrev_b32_e32 v128, 16, v223
	v_and_b32_e32 v129, 0xffff0000, v223
	v_fma_f32 v128, v139, v128, v140
	v_fma_f32 v129, v139, v129, v140
	v_fma_f32 v142, v139, v142, v140
	v_fma_f32 v143, v139, v143, v140
	v_fma_f32 v128, v90, v128, v94
	v_fma_f32 v129, v91, v129, v95
	v_fma_f32 v142, v88, v142, v92
	v_fma_f32 v143, v89, v143, v93
	v_fma_f32 v126, v128, s10, v126
	v_fma_f32 v127, v129, s10, v127
	v_fma_f32 v124, v142, s10, v124
	v_fma_f32 v125, v143, s10, v125
	v_lshl_add_u64 v[142:143], v[136:137], 2, s[52:53]
	s_cbranch_vccnz .LBB0_867
	s_mov_b64 s[38:39], s[52:53]
	global_store_dwordx4 v[142:143], v[124:127], off
.LBB0_867:
	v_mov_b32_e32 v138, v139
	v_mov_b32_e32 v141, v140
	v_lshlrev_b32_e32 v128, 16, v224
	v_and_b32_e32 v129, 0xffff0000, v224
	v_lshlrev_b32_e32 v130, 16, v225
	v_and_b32_e32 v131, 0xffff0000, v225
	v_mov_b32_e32 v144, v140
	v_mov_b32_e32 v145, v140
	v_mov_b32_e32 v146, v139
	v_mov_b32_e32 v147, v139
	v_fma_f32 v130, v146, v130, v144
	v_fma_f32 v131, v147, v131, v145
	v_fma_f32 v128, v138, v128, v140
	v_fma_f32 v129, v139, v129, v141
	v_fma_f32 v130, v78, v130, v82
	v_fma_f32 v131, v79, v131, v83
	v_fma_f32 v128, v76, v128, v80
	v_fma_f32 v129, v77, v129, v81
	v_fma_f32 v122, v130, s10, v122
	v_fma_f32 v123, v131, s10, v123
	s_cmp_eq_u64 s[38:39], 0
	v_fma_f32 v120, v128, s10, v120
	v_fma_f32 v121, v129, s10, v121
	s_cbranch_scc1 .LBB0_869
	v_lshl_add_u64 v[128:129], v[136:137], 2, s[38:39]
	global_store_dwordx4 v[128:129], v[120:123], off offset:16

;     __device__ __forceinline__ void operator()(pg8::f32x4 (&acc)[2][2][4][2], const pg8::Unit& u, int wr, int wc, int fr, int fq) const {
;     ...
;             for (int m = 0; m < 4; ++m) { const int rl = ai * 128 + wr * 64 + m * 16 + fr; const f2v st = T[rl]; const float r = st.y, rm = -st.x * st.y;
;                 const size_t off = (size_t)(u.pm * 256 + rl) * DM + cb; float s1 = 0.f, s2 = 0.f;
; #pragma unroll
;                 for (int bj = 0; bj < 2; ++bj) { f4 pre[2]; float xin[8]; unpack8(*(const u32x4*)(XB + off + 128 * bj), xin);
; #pragma unroll
;                     for (int n = 0; n < 2; ++n) { const f4 v = {xin[4 * n], xin[4 * n + 1], xin[4 * n + 2], xin[4 * n + 3]}; const f4 xr = (v * r + rm) * gv[bj][n] + bv[bj][n];
;                         pre[n] = xr * alpha + acc[ai][bj][m][n]; if (X) *(f4*)(X + off + 128 * bj + 4 * n) = pre[n];
;                         s1 += (pre[n][0] + pre[n][1]) + (pre[n][2] + pre[n][3]); s2 += (pre[n][0] * pre[n][0] + pre[n][1] * pre[n][1]) + (pre[n][2] * pre[n][2] + pre[n][3] * pre[n][3]); }
.LBB0_871:
	v_mov_b32_e32 v144, v140
	v_mov_b32_e32 v145, v140
	v_mov_b32_e32 v146, v139
	v_mov_b32_e32 v147, v139
	s_and_b64 vcc, exec, s[46:47]
	s_mov_b64 s[4:5], 0
	s_waitcnt vmcnt(6)
	v_lshlrev_b32_e32 v148, 16, v226
	v_and_b32_e32 v149, 0xffff0000, v226
	v_lshlrev_b32_e32 v128, 16, v227
	v_and_b32_e32 v129, 0xffff0000, v227
	v_fma_f32 v128, v146, v128, v144
	v_fma_f32 v129, v147, v129, v145
	v_fma_f32 v148, v138, v148, v140
	v_fma_f32 v149, v139, v149, v141
	v_fma_f32 v128, v66, v128, v70
	v_fma_f32 v129, v67, v129, v71
	v_fma_f32 v148, v64, v148, v68
	v_fma_f32 v149, v65, v149, v69
	v_fma_f32 v118, v128, s10, v118
	v_fma_f32 v119, v129, s10, v119
	v_fma_f32 v116, v148, s10, v116
	v_fma_f32 v117, v149, s10, v117
	s_cbranch_vccnz .LBB0_873
	s_mov_b64 s[4:5], s[52:53]
	global_store_dwordx4 v[142:143], v[116:119], off offset:512
.LBB0_873:
	v_lshlrev_b32_e32 v128, 16, v228
	v_and_b32_e32 v129, 0xffff0000, v228
	v_lshlrev_b32_e32 v130, 16, v229
	v_and_b32_e32 v131, 0xffff0000, v229
	v_add_u32_e32 v226, s72, v205
	v_ashrrev_i32_e32 v227, 31, v226
	v_lshlrev_b64 v[228:229], 10, v[226:227]
	v_lshl_add_u64 v[228:229], v[228:229], 0, v[174:175]
	v_lshl_add_u64 v[226:227], v[228:229], 1, s[14:15]
	global_load_dwordx4 v[222:225], v[226:227], off
	global_load_dwordx4 v[226:229], v[226:227], off offset:256
	v_fma_f32 v130, v146, v130, v144
	v_fma_f32 v131, v147, v131, v145
	v_fma_f32 v128, v138, v128, v140
	v_fma_f32 v129, v139, v129, v141
	v_fma_f32 v130, v58, v130, v62
	v_fma_f32 v131, v59, v131, v63
	v_fma_f32 v128, v56, v128, v60
	v_fma_f32 v129, v57, v129, v61
	v_fma_f32 v114, v130, s10, v114
	v_fma_f32 v115, v131, s10, v115
	s_cmp_eq_u64 s[4:5], 0
	v_fma_f32 v112, v128, s10, v112
	v_fma_f32 v113, v129, s10, v113
	s_cbranch_scc1 .LBB0_875
	v_lshl_add_u64 v[128:129], v[136:137], 2, s[4:5]
	global_store_dwordx4 v[128:129], v[112:115], off offset:528

; __device__ __forceinline__ unsigned pk(float lo, float hi) { return pg8::cvt_pk_bf16(lo, hi); }
; template <int O> __device__ __forceinline__ float swz_xor(float v) { return __int_as_float(__builtin_amdgcn_ds_swizzle(__float_as_int(v), (O << 10) | 0x1f)); }
;     __device__ __forceinline__ void operator()(pg8::f32x4 (&acc)[2][2][4][2], const pg8::Unit& u, int wr, int wc, int fr, int fq) const {
;     ...
;             for (int m = 0; m < 4; ++m) { const int rl = ai * 128 + wr * 64 + m * 16 + fr; const f2v st = T[rl]; const float r = st.y, rm = -st.x * st.y;
;                 const size_t off = (size_t)(u.pm * 256 + rl) * DM + cb; float s1 = 0.f, s2 = 0.f;
; #pragma unroll
;                 for (int bj = 0; bj < 2; ++bj) { f4 pre[2]; float xin[8]; unpack8(*(const u32x4*)(XB + off + 128 * bj), xin);
; #pragma unroll
;                     for (int n = 0; n < 2; ++n) { const f4 v = {xin[4 * n], xin[4 * n + 1], xin[4 * n + 2], xin[4 * n + 3]}; const f4 xr = (v * r + rm) * gv[bj][n] + bv[bj][n];
;                         pre[n] = xr * alpha + acc[ai][bj][m][n]; if (X) *(f4*)(X + off + 128 * bj + 4 * n) = pre[n];
;                         s1 += (pre[n][0] + pre[n][1]) + (pre[n][2] + pre[n][3]); s2 += (pre[n][0] * pre[n][0] + pre[n][1] * pre[n][1]) + (pre[n][2] * pre[n][2] + pre[n][3] * pre[n][3]); }
;                     u32x4 w; w.x = pk(pre[0][0], pre[0][1]); w.y = pk(pre[0][2], pre[0][3]); w.z = pk(pre[1][0], pre[1][1]); w.w = pk(pre[1][2], pre[1][3]);
;                     if (!X) *(u32x4*)(XB + off + 128 * bj) = w; }
;                 s1 += swz_xor<16>(s1); s2 += swz_xor<16>(s2);
;                 { auto r1 = __builtin_amdgcn_permlane32_swap(__float_as_uint(s1), __float_as_uint(s1), false, false); s1 = __uint_as_float(r1[0]) + __uint_as_float(r1[1]);
;                   auto r2 = __builtin_amdgcn_permlane32_swap(__float_as_uint(s2), __float_as_uint(s2), false, false); s2 = __uint_as_float(r2[0]) + __uint_as_float(r2[1]); }
;                 if (fq == 0) *(f2v*)(SPout + (size_t)(u.pm * 256 + rl) * 32 + (u.pn * 4 + wc) * 2) = (f2v){s1, s2};
.LBB0_877:
	s_nop 1
	v_add_f32_e32 v128, v124, v125
	v_mul_f32_e32 v125, v125, v125
	v_fmac_f32_e32 v125, v124, v124
	v_mul_f32_e32 v124, v126, v126
	v_fmac_f32_e32 v124, v127, v127
	v_add_f32_e32 v124, v125, v124
	v_add_f32_e32 v125, v120, v121
	v_mul_f32_e32 v121, v121, v121
	v_fmac_f32_e32 v121, v120, v120
	v_mul_f32_e32 v120, v122, v122
	v_fmac_f32_e32 v120, v123, v123
	v_add_f32_e32 v120, v121, v120
	v_add_f32_e32 v121, v116, v117
	v_mul_f32_e32 v117, v117, v117
	v_fmac_f32_e32 v117, v116, v116
	v_mul_f32_e32 v116, v118, v118
	v_add_f32_e32 v129, v127, v126
	v_fmac_f32_e32 v116, v119, v119
	v_add_f32_e32 v128, v128, v129
	v_add_f32_e32 v126, v123, v122
	v_add_f32_e32 v116, v117, v116
	v_add_f32_e32 v117, v112, v113
	v_mul_f32_e32 v113, v113, v113
	v_add_f32_e32 v128, 0, v128
	v_add_f32_e32 v125, v125, v126
	v_add_f32_e32 v122, v119, v118
	v_fmac_f32_e32 v113, v112, v112
	v_mul_f32_e32 v112, v114, v114
	v_add_f32_e32 v125, v125, v128
	v_add_f32_e32 v120, v124, v120
	v_add_f32_e32 v121, v121, v122
	v_add_f32_e32 v118, v115, v114
	v_fmac_f32_e32 v112, v115, v115
	v_add_f32_e32 v121, v125, v121
	v_add_f32_e32 v116, v120, v116
	v_add_f32_e32 v117, v117, v118
	v_add_f32_e32 v112, v113, v112
	v_add_f32_e32 v117, v117, v121
	v_add_f32_e32 v113, v112, v116
	ds_swizzle_b32 v112, v117 offset:swizzle(SWAP,16)
	ds_swizzle_b32 v114, v113 offset:swizzle(SWAP,16)
	s_waitcnt lgkmcnt(1)
	v_add_f32_e32 v112, v117, v112
	s_waitcnt lgkmcnt(0)
	v_add_f32_e32 v113, v113, v114
	v_mov_b32_e32 v114, v112
	v_mov_b32_e32 v115, v113
	s_nop 0
	v_permlane32_swap_b32_e32 v112, v114
	v_permlane32_swap_b32_e32 v113, v115
	s_and_saveexec_b64 s[0:1], s[42:43]
	s_cbranch_execz .LBB0_879
	v_add_f32_e64 v112, v112, v114
	v_add_f32_e64 v113, v113, v115
	v_lshlrev_b64 v[114:115], 7, v[132:133]
	v_lshl_add_u64 v[114:115], s[18:19], 0, v[114:115]
	v_lshl_add_u64 v[114:115], s[36:37], 2, v[114:115]
	global_store_dwordx2 v[114:115], v[112:113], off
.LBB0_879:
	s_or_b64 exec, exec, s[0:1]
	v_add_u32_e32 v116, s72, v204
	v_ashrrev_i32_e32 v117, 31, v116
	v_lshlrev_b64 v[112:113], 10, v[116:117]
	v_lshl_add_u64 v[120:121], v[112:113], 0, v[174:175]
	v_lshl_add_u64 v[118:119], v[120:121], 1, s[14:15]
	ds_read_b64 v[122:123], v213
	s_mov_b64 s[38:39], 0
	s_and_b64 vcc, exec, s[46:47]
	s_waitcnt lgkmcnt(0)
	v_mul_f32_e64 v124, v123, -v122
	s_waitcnt vmcnt(6)
	v_lshlrev_b32_e32 v126, 16, v238
	v_and_b32_e32 v127, 0xffff0000, v238
	v_lshlrev_b32_e32 v112, 16, v239
	v_and_b32_e32 v113, 0xffff0000, v239
	v_fma_f32 v112, v123, v112, v124
	v_fma_f32 v113, v123, v113, v124
	v_fma_f32 v126, v123, v126, v124
	v_fma_f32 v127, v123, v127, v124
	v_fma_f32 v112, v90, v112, v94
	v_fma_f32 v113, v91, v113, v95
	v_fma_f32 v126, v88, v126, v92
	v_fma_f32 v127, v89, v127, v93
	v_fma_f32 v110, v112, s10, v110
	v_fma_f32 v111, v113, s10, v111
	v_fma_f32 v108, v126, s10, v108
	v_fma_f32 v109, v127, s10, v109
	v_lshl_add_u64 v[126:127], v[120:121], 2, s[52:53]
	s_cbranch_vccnz .LBB0_881
	s_mov_b64 s[38:39], s[52:53]
	global_store_dwordx4 v[126:127], v[108:111], off
.LBB0_881:
	v_mov_b32_e32 v122, v123
	v_mov_b32_e32 v125, v124
	v_lshlrev_b32_e32 v112, 16, v240
	v_and_b32_e32 v113, 0xffff0000, v240
	v_lshlrev_b32_e32 v114, 16, v241
	v_and_b32_e32 v115, 0xffff0000, v241
	v_mov_b32_e32 v128, v124
	v_mov_b32_e32 v129, v124
	v_mov_b32_e32 v130, v123
	v_mov_b32_e32 v131, v123
	v_fma_f32 v114, v130, v114, v128
	v_fma_f32 v115, v131, v115, v129
	v_fma_f32 v112, v122, v112, v124
	v_fma_f32 v113, v123, v113, v125
	v_fma_f32 v114, v78, v114, v82
	v_fma_f32 v115, v79, v115, v83
	v_fma_f32 v112, v76, v112, v80
	v_fma_f32 v113, v77, v113, v81
	v_fma_f32 v106, v114, s10, v106
	v_fma_f32 v107, v115, s10, v107
	s_cmp_eq_u64 s[38:39], 0
	v_fma_f32 v104, v112, s10, v104
	v_fma_f32 v105, v113, s10, v105
	s_cbranch_scc1 .LBB0_883
	v_lshl_add_u64 v[112:113], v[120:121], 2, s[38:39]
	global_store_dwordx4 v[112:113], v[104:107], off offset:16

;     __device__ __forceinline__ void operator()(pg8::f32x4 (&acc)[2][2][4][2], const pg8::Unit& u, int wr, int wc, int fr, int fq) const {
;     ...
;             for (int m = 0; m < 4; ++m) { const int rl = ai * 128 + wr * 64 + m * 16 + fr; const f2v st = T[rl]; const float r = st.y, rm = -st.x * st.y;
;                 const size_t off = (size_t)(u.pm * 256 + rl) * DM + cb; float s1 = 0.f, s2 = 0.f;
; #pragma unroll
;                 for (int bj = 0; bj < 2; ++bj) { f4 pre[2]; float xin[8]; unpack8(*(const u32x4*)(XB + off + 128 * bj), xin);
; #pragma unroll
;                     for (int n = 0; n < 2; ++n) { const f4 v = {xin[4 * n], xin[4 * n + 1], xin[4 * n + 2], xin[4 * n + 3]}; const f4 xr = (v * r + rm) * gv[bj][n] + bv[bj][n];
;                         pre[n] = xr * alpha + acc[ai][bj][m][n]; if (X) *(f4*)(X + off + 128 * bj + 4 * n) = pre[n];
;                         s1 += (pre[n][0] + pre[n][1]) + (pre[n][2] + pre[n][3]); s2 += (pre[n][0] * pre[n][0] + pre[n][1] * pre[n][1]) + (pre[n][2] * pre[n][2] + pre[n][3] * pre[n][3]); }
.LBB0_885:
	v_mov_b32_e32 v128, v124
	v_mov_b32_e32 v129, v124
	v_mov_b32_e32 v130, v123
	v_mov_b32_e32 v131, v123
	s_and_b64 vcc, exec, s[46:47]
	s_mov_b64 s[4:5], 0
	s_waitcnt vmcnt(6)
	v_lshlrev_b32_e32 v132, 16, v242
	v_and_b32_e32 v133, 0xffff0000, v242
	v_lshlrev_b32_e32 v112, 16, v243
	v_and_b32_e32 v113, 0xffff0000, v243
	v_fma_f32 v112, v130, v112, v128
	v_fma_f32 v113, v131, v113, v129
	v_fma_f32 v132, v122, v132, v124
	v_fma_f32 v133, v123, v133, v125
	v_fma_f32 v112, v66, v112, v70
	v_fma_f32 v113, v67, v113, v71
	v_fma_f32 v132, v64, v132, v68
	v_fma_f32 v133, v65, v133, v69
	v_fma_f32 v102, v112, s10, v102
	v_fma_f32 v103, v113, s10, v103
	v_fma_f32 v100, v132, s10, v100
	v_fma_f32 v101, v133, s10, v101
	s_cbranch_vccnz .LBB0_887
	s_mov_b64 s[4:5], s[52:53]
	global_store_dwordx4 v[126:127], v[100:103], off offset:512
.LBB0_887:
	v_lshlrev_b32_e32 v112, 16, v244
	v_and_b32_e32 v113, 0xffff0000, v244
	v_lshlrev_b32_e32 v114, 16, v245
	v_and_b32_e32 v115, 0xffff0000, v245
	v_add_u32_e32 v242, s72, v206
	v_ashrrev_i32_e32 v243, 31, v242
	v_lshlrev_b64 v[244:245], 10, v[242:243]
	v_lshl_add_u64 v[244:245], v[244:245], 0, v[174:175]
	v_lshl_add_u64 v[242:243], v[244:245], 1, s[14:15]
	global_load_dwordx4 v[238:241], v[242:243], off
	global_load_dwordx4 v[242:245], v[242:243], off offset:256
	v_fma_f32 v114, v130, v114, v128
	v_fma_f32 v115, v131, v115, v129
	v_fma_f32 v112, v122, v112, v124
	v_fma_f32 v113, v123, v113, v125
	v_fma_f32 v114, v58, v114, v62
	v_fma_f32 v115, v59, v115, v63
	v_fma_f32 v112, v56, v112, v60
	v_fma_f32 v113, v57, v113, v61
	v_fma_f32 v98, v114, s10, v98
	v_fma_f32 v99, v115, s10, v99
	s_cmp_eq_u64 s[4:5], 0
	v_fma_f32 v96, v112, s10, v96
	v_fma_f32 v97, v113, s10, v97
	s_cbranch_scc1 .LBB0_889
	v_lshl_add_u64 v[112:113], v[120:121], 2, s[4:5]
	global_store_dwordx4 v[112:113], v[96:99], off offset:528

; __device__ __forceinline__ unsigned pk(float lo, float hi) { return pg8::cvt_pk_bf16(lo, hi); }
; template <int O> __device__ __forceinline__ float swz_xor(float v) { return __int_as_float(__builtin_amdgcn_ds_swizzle(__float_as_int(v), (O << 10) | 0x1f)); }
;     __device__ __forceinline__ void operator()(pg8::f32x4 (&acc)[2][2][4][2], const pg8::Unit& u, int wr, int wc, int fr, int fq) const {
;     ...
;             for (int m = 0; m < 4; ++m) { const int rl = ai * 128 + wr * 64 + m * 16 + fr; const f2v st = T[rl]; const float r = st.y, rm = -st.x * st.y;
;                 const size_t off = (size_t)(u.pm * 256 + rl) * DM + cb; float s1 = 0.f, s2 = 0.f;
; #pragma unroll
;                 for (int bj = 0; bj < 2; ++bj) { f4 pre[2]; float xin[8]; unpack8(*(const u32x4*)(XB + off + 128 * bj), xin);
; #pragma unroll
;                     for (int n = 0; n < 2; ++n) { const f4 v = {xin[4 * n], xin[4 * n + 1], xin[4 * n + 2], xin[4 * n + 3]}; const f4 xr = (v * r + rm) * gv[bj][n] + bv[bj][n];
;                         pre[n] = xr * alpha + acc[ai][bj][m][n]; if (X) *(f4*)(X + off + 128 * bj + 4 * n) = pre[n];
;                         s1 += (pre[n][0] + pre[n][1]) + (pre[n][2] + pre[n][3]); s2 += (pre[n][0] * pre[n][0] + pre[n][1] * pre[n][1]) + (pre[n][2] * pre[n][2] + pre[n][3] * pre[n][3]); }
;                     u32x4 w; w.x = pk(pre[0][0], pre[0][1]); w.y = pk(pre[0][2], pre[0][3]); w.z = pk(pre[1][0], pre[1][1]); w.w = pk(pre[1][2], pre[1][3]);
;                     if (!X) *(u32x4*)(XB + off + 128 * bj) = w; }
;                 s1 += swz_xor<16>(s1); s2 += swz_xor<16>(s2);
;                 { auto r1 = __builtin_amdgcn_permlane32_swap(__float_as_uint(s1), __float_as_uint(s1), false, false); s1 = __uint_as_float(r1[0]) + __uint_as_float(r1[1]);
;                   auto r2 = __builtin_amdgcn_permlane32_swap(__float_as_uint(s2), __float_as_uint(s2), false, false); s2 = __uint_as_float(r2[0]) + __uint_as_float(r2[1]); }
;                 if (fq == 0) *(f2v*)(SPout + (size_t)(u.pm * 256 + rl) * 32 + (u.pn * 4 + wc) * 2) = (f2v){s1, s2};
.LBB0_891:
	s_nop 1
	v_add_f32_e32 v112, v108, v109
	v_mul_f32_e32 v109, v109, v109
	v_fmac_f32_e32 v109, v108, v108
	v_mul_f32_e32 v108, v110, v110
	v_fmac_f32_e32 v108, v111, v111
	v_add_f32_e32 v108, v109, v108
	v_add_f32_e32 v109, v104, v105
	v_mul_f32_e32 v105, v105, v105
	v_fmac_f32_e32 v105, v104, v104
	v_mul_f32_e32 v104, v106, v106
	v_fmac_f32_e32 v104, v107, v107
	v_add_f32_e32 v104, v105, v104
	v_add_f32_e32 v105, v100, v101
	v_mul_f32_e32 v101, v101, v101
	v_fmac_f32_e32 v101, v100, v100
	v_mul_f32_e32 v100, v102, v102
	v_add_f32_e32 v113, v111, v110
	v_fmac_f32_e32 v100, v103, v103
	v_add_f32_e32 v112, v112, v113
	v_add_f32_e32 v110, v107, v106
	v_add_f32_e32 v100, v101, v100
	v_add_f32_e32 v101, v96, v97
	v_mul_f32_e32 v97, v97, v97
	v_add_f32_e32 v112, 0, v112
	v_add_f32_e32 v109, v109, v110
	v_add_f32_e32 v106, v103, v102
	v_fmac_f32_e32 v97, v96, v96
	v_mul_f32_e32 v96, v98, v98
	v_add_f32_e32 v109, v109, v112
	v_add_f32_e32 v104, v108, v104
	v_add_f32_e32 v105, v105, v106
	v_add_f32_e32 v102, v99, v98
	v_fmac_f32_e32 v96, v99, v99
	v_add_f32_e32 v105, v109, v105
	v_add_f32_e32 v100, v104, v100
	v_add_f32_e32 v101, v101, v102
	v_add_f32_e32 v96, v97, v96
	v_add_f32_e32 v101, v101, v105
	v_add_f32_e32 v97, v96, v100
	ds_swizzle_b32 v96, v101 offset:swizzle(SWAP,16)
	ds_swizzle_b32 v98, v97 offset:swizzle(SWAP,16)
	s_waitcnt lgkmcnt(1)
	v_add_f32_e32 v96, v101, v96
	s_waitcnt lgkmcnt(0)
	v_add_f32_e32 v97, v97, v98
	v_mov_b32_e32 v98, v96
	v_mov_b32_e32 v99, v97
	s_nop 0
	v_permlane32_swap_b32_e32 v96, v98
	v_permlane32_swap_b32_e32 v97, v99
	s_and_saveexec_b64 s[0:1], s[42:43]
	s_cbranch_execz .LBB0_893
	v_add_f32_e64 v96, v96, v98
	v_add_f32_e64 v97, v97, v99
	v_lshlrev_b64 v[98:99], 7, v[116:117]
	v_lshl_add_u64 v[98:99], s[18:19], 0, v[98:99]
	v_lshl_add_u64 v[98:99], s[36:37], 2, v[98:99]
	global_store_dwordx2 v[98:99], v[96:97], off
.LBB0_893:
	s_or_b64 exec, exec, s[0:1]
	v_add_u32_e32 v100, s72, v205
	v_ashrrev_i32_e32 v101, 31, v100
	v_lshlrev_b64 v[96:97], 10, v[100:101]
	v_lshl_add_u64 v[104:105], v[96:97], 0, v[174:175]
	v_lshl_add_u64 v[102:103], v[104:105], 1, s[14:15]
	ds_read_b64 v[106:107], v214
	s_mov_b64 s[38:39], 0
	s_and_b64 vcc, exec, s[46:47]
	s_waitcnt lgkmcnt(0)
	v_mul_f32_e64 v108, v107, -v106
	s_waitcnt vmcnt(6)
	v_lshlrev_b32_e32 v110, 16, v222
	v_and_b32_e32 v111, 0xffff0000, v222
	v_lshlrev_b32_e32 v96, 16, v223
	v_and_b32_e32 v97, 0xffff0000, v223
	v_fma_f32 v96, v107, v96, v108
	v_fma_f32 v97, v107, v97, v108
	v_fma_f32 v110, v107, v110, v108
	v_fma_f32 v111, v107, v111, v108
	v_fma_f32 v96, v90, v96, v94
	v_fma_f32 v97, v91, v97, v95
	v_fma_f32 v110, v88, v110, v92
	v_fma_f32 v111, v89, v111, v93
	v_fma_f32 v86, v96, s10, v86
	v_fma_f32 v87, v97, s10, v87
	v_fma_f32 v84, v110, s10, v84
	v_fma_f32 v85, v111, s10, v85
	v_lshl_add_u64 v[110:111], v[104:105], 2, s[52:53]
	s_cbranch_vccnz .LBB0_895
	s_mov_b64 s[38:39], s[52:53]
	global_store_dwordx4 v[110:111], v[84:87], off
.LBB0_895:
	v_mov_b32_e32 v106, v107
	v_mov_b32_e32 v109, v108
	v_lshlrev_b32_e32 v96, 16, v224
	v_and_b32_e32 v97, 0xffff0000, v224
	v_lshlrev_b32_e32 v98, 16, v225
	v_and_b32_e32 v99, 0xffff0000, v225
	v_mov_b32_e32 v112, v108
	v_mov_b32_e32 v113, v108
	v_mov_b32_e32 v114, v107
	v_mov_b32_e32 v115, v107
	v_fma_f32 v98, v114, v98, v112
	v_fma_f32 v99, v115, v99, v113
	v_fma_f32 v96, v106, v96, v108
	v_fma_f32 v97, v107, v97, v109
	v_fma_f32 v98, v78, v98, v82
	v_fma_f32 v99, v79, v99, v83
	v_fma_f32 v96, v76, v96, v80
	v_fma_f32 v97, v77, v97, v81
	v_fma_f32 v74, v98, s10, v74
	v_fma_f32 v75, v99, s10, v75
	s_cmp_eq_u64 s[38:39], 0
	v_fma_f32 v72, v96, s10, v72
	v_fma_f32 v73, v97, s10, v73
	s_cbranch_scc1 .LBB0_897
	v_lshl_add_u64 v[96:97], v[104:105], 2, s[38:39]
	global_store_dwordx4 v[96:97], v[72:75], off offset:16

;     __device__ __forceinline__ void operator()(pg8::f32x4 (&acc)[2][2][4][2], const pg8::Unit& u, int wr, int wc, int fr, int fq) const {
;     ...
;             for (int m = 0; m < 4; ++m) { const int rl = ai * 128 + wr * 64 + m * 16 + fr; const f2v st = T[rl]; const float r = st.y, rm = -st.x * st.y;
;                 const size_t off = (size_t)(u.pm * 256 + rl) * DM + cb; float s1 = 0.f, s2 = 0.f;
; #pragma unroll
;                 for (int bj = 0; bj < 2; ++bj) { f4 pre[2]; float xin[8]; unpack8(*(const u32x4*)(XB + off + 128 * bj), xin);
; #pragma unroll
;                     for (int n = 0; n < 2; ++n) { const f4 v = {xin[4 * n], xin[4 * n + 1], xin[4 * n + 2], xin[4 * n + 3]}; const f4 xr = (v * r + rm) * gv[bj][n] + bv[bj][n];
;                         pre[n] = xr * alpha + acc[ai][bj][m][n]; if (X) *(f4*)(X + off + 128 * bj + 4 * n) = pre[n];
;                         s1 += (pre[n][0] + pre[n][1]) + (pre[n][2] + pre[n][3]); s2 += (pre[n][0] * pre[n][0] + pre[n][1] * pre[n][1]) + (pre[n][2] * pre[n][2] + pre[n][3] * pre[n][3]); }
.LBB0_899:
	v_mov_b32_e32 v112, v108
	v_mov_b32_e32 v113, v108
	v_mov_b32_e32 v114, v107
	v_mov_b32_e32 v115, v107
	s_and_b64 vcc, exec, s[46:47]
	s_mov_b64 s[4:5], 0
	s_waitcnt vmcnt(6)
	v_lshlrev_b32_e32 v116, 16, v226
	v_and_b32_e32 v117, 0xffff0000, v226
	v_lshlrev_b32_e32 v96, 16, v227
	v_and_b32_e32 v97, 0xffff0000, v227
	v_fma_f32 v96, v114, v96, v112
	v_fma_f32 v97, v115, v97, v113
	v_fma_f32 v116, v106, v116, v108
	v_fma_f32 v117, v107, v117, v109
	v_fma_f32 v96, v66, v96, v70
	v_fma_f32 v97, v67, v97, v71
	v_fma_f32 v116, v64, v116, v68
	v_fma_f32 v117, v65, v117, v69
	v_fma_f32 v54, v96, s10, v54
	v_fma_f32 v55, v97, s10, v55
	v_fma_f32 v52, v116, s10, v52
	v_fma_f32 v53, v117, s10, v53
	s_cbranch_vccnz .LBB0_901
	s_mov_b64 s[4:5], s[52:53]
	global_store_dwordx4 v[110:111], v[52:55], off offset:512
.LBB0_901:
	v_lshlrev_b32_e32 v96, 16, v228
	v_and_b32_e32 v97, 0xffff0000, v228
	v_lshlrev_b32_e32 v98, 16, v229
	v_and_b32_e32 v99, 0xffff0000, v229
	v_add_u32_e32 v226, s72, v207
	v_ashrrev_i32_e32 v227, 31, v226
	v_lshlrev_b64 v[228:229], 10, v[226:227]
	v_lshl_add_u64 v[228:229], v[228:229], 0, v[174:175]
	v_lshl_add_u64 v[226:227], v[228:229], 1, s[14:15]
	global_load_dwordx4 v[222:225], v[226:227], off
	global_load_dwordx4 v[226:229], v[226:227], off offset:256
	v_fma_f32 v98, v114, v98, v112
	v_fma_f32 v99, v115, v99, v113
	v_fma_f32 v96, v106, v96, v108
	v_fma_f32 v97, v107, v97, v109
	v_fma_f32 v98, v58, v98, v62
	v_fma_f32 v99, v59, v99, v63
	v_fma_f32 v96, v56, v96, v60
	v_fma_f32 v97, v57, v97, v61
	v_fma_f32 v50, v98, s10, v50
	v_fma_f32 v51, v99, s10, v51
	s_cmp_eq_u64 s[4:5], 0
	v_fma_f32 v48, v96, s10, v48
	v_fma_f32 v49, v97, s10, v49
	s_cbranch_scc1 .LBB0_903
	v_lshl_add_u64 v[96:97], v[104:105], 2, s[4:5]
	global_store_dwordx4 v[96:97], v[48:51], off offset:528

; __device__ __forceinline__ unsigned pk(float lo, float hi) { return pg8::cvt_pk_bf16(lo, hi); }
; template <int O> __device__ __forceinline__ float swz_xor(float v) { return __int_as_float(__builtin_amdgcn_ds_swizzle(__float_as_int(v), (O << 10) | 0x1f)); }
;     __device__ __forceinline__ void operator()(pg8::f32x4 (&acc)[2][2][4][2], const pg8::Unit& u, int wr, int wc, int fr, int fq) const {
;     ...
;             for (int m = 0; m < 4; ++m) { const int rl = ai * 128 + wr * 64 + m * 16 + fr; const f2v st = T[rl]; const float r = st.y, rm = -st.x * st.y;
;                 const size_t off = (size_t)(u.pm * 256 + rl) * DM + cb; float s1 = 0.f, s2 = 0.f;
; #pragma unroll
;                 for (int bj = 0; bj < 2; ++bj) { f4 pre[2]; float xin[8]; unpack8(*(const u32x4*)(XB + off + 128 * bj), xin);
; #pragma unroll
;                     for (int n = 0; n < 2; ++n) { const f4 v = {xin[4 * n], xin[4 * n + 1], xin[4 * n + 2], xin[4 * n + 3]}; const f4 xr = (v * r + rm) * gv[bj][n] + bv[bj][n];
;                         pre[n] = xr * alpha + acc[ai][bj][m][n]; if (X) *(f4*)(X + off + 128 * bj + 4 * n) = pre[n];
;                         s1 += (pre[n][0] + pre[n][1]) + (pre[n][2] + pre[n][3]); s2 += (pre[n][0] * pre[n][0] + pre[n][1] * pre[n][1]) + (pre[n][2] * pre[n][2] + pre[n][3] * pre[n][3]); }
;                     u32x4 w; w.x = pk(pre[0][0], pre[0][1]); w.y = pk(pre[0][2], pre[0][3]); w.z = pk(pre[1][0], pre[1][1]); w.w = pk(pre[1][2], pre[1][3]);
;                     if (!X) *(u32x4*)(XB + off + 128 * bj) = w; }
;                 s1 += swz_xor<16>(s1); s2 += swz_xor<16>(s2);
;                 { auto r1 = __builtin_amdgcn_permlane32_swap(__float_as_uint(s1), __float_as_uint(s1), false, false); s1 = __uint_as_float(r1[0]) + __uint_as_float(r1[1]);
;                   auto r2 = __builtin_amdgcn_permlane32_swap(__float_as_uint(s2), __float_as_uint(s2), false, false); s2 = __uint_as_float(r2[0]) + __uint_as_float(r2[1]); }
;                 if (fq == 0) *(f2v*)(SPout + (size_t)(u.pm * 256 + rl) * 32 + (u.pn * 4 + wc) * 2) = (f2v){s1, s2};
.LBB0_905:
	s_nop 1
	v_add_f32_e32 v96, v84, v85
	v_mul_f32_e32 v85, v85, v85
	v_fmac_f32_e32 v85, v84, v84
	v_mul_f32_e32 v84, v86, v86
	v_fmac_f32_e32 v84, v87, v87
	v_add_f32_e32 v84, v85, v84
	v_add_f32_e32 v85, v72, v73
	v_mul_f32_e32 v73, v73, v73
	v_fmac_f32_e32 v73, v72, v72
	v_mul_f32_e32 v72, v74, v74
	v_fmac_f32_e32 v72, v75, v75
	v_add_f32_e32 v72, v73, v72
	v_add_f32_e32 v73, v52, v53
	v_mul_f32_e32 v53, v53, v53
	v_fmac_f32_e32 v53, v52, v52
	v_mul_f32_e32 v52, v54, v54
	v_add_f32_e32 v97, v87, v86
	v_fmac_f32_e32 v52, v55, v55
	v_add_f32_e32 v96, v96, v97
	v_add_f32_e32 v86, v75, v74
	v_add_f32_e32 v52, v53, v52
	v_add_f32_e32 v53, v48, v49
	v_mul_f32_e32 v49, v49, v49
	v_add_f32_e32 v96, 0, v96
	v_add_f32_e32 v85, v85, v86
	v_add_f32_e32 v74, v55, v54
	v_fmac_f32_e32 v49, v48, v48
	v_mul_f32_e32 v48, v50, v50
	v_add_f32_e32 v85, v85, v96
	v_add_f32_e32 v72, v84, v72
	v_add_f32_e32 v73, v73, v74
	v_add_f32_e32 v54, v51, v50
	v_fmac_f32_e32 v48, v51, v51
	v_add_f32_e32 v73, v85, v73
	v_add_f32_e32 v52, v72, v52
	v_add_f32_e32 v53, v53, v54
	v_add_f32_e32 v48, v49, v48
	v_add_f32_e32 v53, v53, v73
	v_add_f32_e32 v49, v48, v52
	ds_swizzle_b32 v48, v53 offset:swizzle(SWAP,16)
	ds_swizzle_b32 v50, v49 offset:swizzle(SWAP,16)
	s_waitcnt lgkmcnt(1)
	v_add_f32_e32 v48, v53, v48
	s_waitcnt lgkmcnt(0)
	v_add_f32_e32 v49, v49, v50
	v_mov_b32_e32 v50, v48
	v_mov_b32_e32 v51, v49
	s_nop 0
	v_permlane32_swap_b32_e32 v48, v50
	v_permlane32_swap_b32_e32 v49, v51
	s_and_saveexec_b64 s[0:1], s[42:43]
	s_cbranch_execz .LBB0_907
	v_add_f32_e64 v48, v48, v50
	v_add_f32_e64 v49, v49, v51
	v_lshlrev_b64 v[50:51], 7, v[100:101]
	v_lshl_add_u64 v[50:51], s[18:19], 0, v[50:51]
	v_lshl_add_u64 v[50:51], s[36:37], 2, v[50:51]
	global_store_dwordx2 v[50:51], v[48:49], off
.LBB0_907:
	s_or_b64 exec, exec, s[0:1]
	v_add_u32_e32 v52, s72, v206
	v_ashrrev_i32_e32 v53, 31, v52
	v_lshlrev_b64 v[48:49], 10, v[52:53]
	v_lshl_add_u64 v[72:73], v[48:49], 0, v[174:175]
	v_lshl_add_u64 v[54:55], v[72:73], 1, s[14:15]
	ds_read_b64 v[74:75], v215
	s_mov_b64 s[38:39], 0
	s_and_b64 vcc, exec, s[46:47]
	s_waitcnt lgkmcnt(0)
	v_mul_f32_e64 v84, v75, -v74
	s_waitcnt vmcnt(6)
	v_lshlrev_b32_e32 v86, 16, v238
	v_and_b32_e32 v87, 0xffff0000, v238
	v_lshlrev_b32_e32 v48, 16, v239
	v_and_b32_e32 v49, 0xffff0000, v239
	v_fma_f32 v48, v75, v48, v84
	v_fma_f32 v49, v75, v49, v84
	v_fma_f32 v86, v75, v86, v84
	v_fma_f32 v87, v75, v87, v84
	v_fma_f32 v48, v90, v48, v94
	v_fma_f32 v49, v91, v49, v95
	v_fma_f32 v86, v88, v86, v92
	v_fma_f32 v87, v89, v87, v93
	v_fma_f32 v46, v48, s10, v46
	v_fma_f32 v47, v49, s10, v47
	v_fma_f32 v44, v86, s10, v44
	v_fma_f32 v45, v87, s10, v45
	v_lshl_add_u64 v[86:87], v[72:73], 2, s[52:53]
	s_cbranch_vccnz .LBB0_909
	s_mov_b64 s[38:39], s[52:53]
	global_store_dwordx4 v[86:87], v[44:47], off
.LBB0_909:
	v_mov_b32_e32 v74, v75
	v_mov_b32_e32 v85, v84
	v_lshlrev_b32_e32 v48, 16, v240
	v_and_b32_e32 v49, 0xffff0000, v240
	v_lshlrev_b32_e32 v50, 16, v241
	v_and_b32_e32 v51, 0xffff0000, v241
	v_mov_b32_e32 v96, v84
	v_mov_b32_e32 v97, v84
	v_mov_b32_e32 v98, v75
	v_mov_b32_e32 v99, v75
	v_fma_f32 v50, v98, v50, v96
	v_fma_f32 v51, v99, v51, v97
	v_fma_f32 v48, v74, v48, v84
	v_fma_f32 v49, v75, v49, v85
	v_fma_f32 v50, v78, v50, v82
	v_fma_f32 v51, v79, v51, v83
	v_fma_f32 v48, v76, v48, v80
	v_fma_f32 v49, v77, v49, v81
	v_fma_f32 v42, v50, s10, v42
	v_fma_f32 v43, v51, s10, v43
	s_cmp_eq_u64 s[38:39], 0
	v_fma_f32 v40, v48, s10, v40
	v_fma_f32 v41, v49, s10, v41
	s_cbranch_scc1 .LBB0_911
	v_lshl_add_u64 v[48:49], v[72:73], 2, s[38:39]
	global_store_dwordx4 v[48:49], v[40:43], off offset:16

;     __device__ __forceinline__ void operator()(pg8::f32x4 (&acc)[2][2][4][2], const pg8::Unit& u, int wr, int wc, int fr, int fq) const {
;     ...
;             for (int m = 0; m < 4; ++m) { const int rl = ai * 128 + wr * 64 + m * 16 + fr; const f2v st = T[rl]; const float r = st.y, rm = -st.x * st.y;
;                 const size_t off = (size_t)(u.pm * 256 + rl) * DM + cb; float s1 = 0.f, s2 = 0.f;
; #pragma unroll
;                 for (int bj = 0; bj < 2; ++bj) { f4 pre[2]; float xin[8]; unpack8(*(const u32x4*)(XB + off + 128 * bj), xin);
; #pragma unroll
;                     for (int n = 0; n < 2; ++n) { const f4 v = {xin[4 * n], xin[4 * n + 1], xin[4 * n + 2], xin[4 * n + 3]}; const f4 xr = (v * r + rm) * gv[bj][n] + bv[bj][n];
;                         pre[n] = xr * alpha + acc[ai][bj][m][n]; if (X) *(f4*)(X + off + 128 * bj + 4 * n) = pre[n];
;                         s1 += (pre[n][0] + pre[n][1]) + (pre[n][2] + pre[n][3]); s2 += (pre[n][0] * pre[n][0] + pre[n][1] * pre[n][1]) + (pre[n][2] * pre[n][2] + pre[n][3] * pre[n][3]); }
.LBB0_913:
	v_mov_b32_e32 v96, v84
	v_mov_b32_e32 v97, v84
	v_mov_b32_e32 v98, v75
	v_mov_b32_e32 v99, v75
	s_and_b64 vcc, exec, s[46:47]
	s_mov_b64 s[4:5], 0
	s_waitcnt vmcnt(6)
	v_lshlrev_b32_e32 v100, 16, v242
	v_and_b32_e32 v101, 0xffff0000, v242
	v_lshlrev_b32_e32 v48, 16, v243
	v_and_b32_e32 v49, 0xffff0000, v243
	v_fma_f32 v48, v98, v48, v96
	v_fma_f32 v49, v99, v49, v97
	v_fma_f32 v100, v74, v100, v84
	v_fma_f32 v101, v75, v101, v85
	v_fma_f32 v48, v66, v48, v70
	v_fma_f32 v49, v67, v49, v71
	v_fma_f32 v100, v64, v100, v68
	v_fma_f32 v101, v65, v101, v69
	v_fma_f32 v38, v48, s10, v38
	v_fma_f32 v39, v49, s10, v39
	v_fma_f32 v36, v100, s10, v36
	v_fma_f32 v37, v101, s10, v37
	s_cbranch_vccnz .LBB0_915
	s_mov_b64 s[4:5], s[52:53]
	global_store_dwordx4 v[86:87], v[36:39], off offset:512
.LBB0_915:
	v_lshlrev_b32_e32 v48, 16, v244
	v_and_b32_e32 v49, 0xffff0000, v244
	v_lshlrev_b32_e32 v50, 16, v245
	v_and_b32_e32 v51, 0xffff0000, v245
	v_add_u32_e32 v242, s72, v208
	v_ashrrev_i32_e32 v243, 31, v242
	v_lshlrev_b64 v[244:245], 10, v[242:243]
	v_lshl_add_u64 v[244:245], v[244:245], 0, v[174:175]
	v_lshl_add_u64 v[242:243], v[244:245], 1, s[14:15]
	global_load_dwordx4 v[238:241], v[242:243], off
	global_load_dwordx4 v[242:245], v[242:243], off offset:256
	v_fma_f32 v50, v98, v50, v96
	v_fma_f32 v51, v99, v51, v97
	v_fma_f32 v48, v74, v48, v84
	v_fma_f32 v49, v75, v49, v85
	v_fma_f32 v50, v58, v50, v62
	v_fma_f32 v51, v59, v51, v63
	v_fma_f32 v48, v56, v48, v60
	v_fma_f32 v49, v57, v49, v61
	v_fma_f32 v34, v50, s10, v34
	v_fma_f32 v35, v51, s10, v35
	s_cmp_eq_u64 s[4:5], 0
	v_fma_f32 v32, v48, s10, v32
	v_fma_f32 v33, v49, s10, v33
	s_cbranch_scc1 .LBB0_917
	v_lshl_add_u64 v[48:49], v[72:73], 2, s[4:5]
	global_store_dwordx4 v[48:49], v[32:35], off offset:528

; __device__ __forceinline__ unsigned pk(float lo, float hi) { return pg8::cvt_pk_bf16(lo, hi); }
; template <int O> __device__ __forceinline__ float swz_xor(float v) { return __int_as_float(__builtin_amdgcn_ds_swizzle(__float_as_int(v), (O << 10) | 0x1f)); }
;     __device__ __forceinline__ void operator()(pg8::f32x4 (&acc)[2][2][4][2], const pg8::Unit& u, int wr, int wc, int fr, int fq) const {
;     ...
;             for (int m = 0; m < 4; ++m) { const int rl = ai * 128 + wr * 64 + m * 16 + fr; const f2v st = T[rl]; const float r = st.y, rm = -st.x * st.y;
;                 const size_t off = (size_t)(u.pm * 256 + rl) * DM + cb; float s1 = 0.f, s2 = 0.f;
; #pragma unroll
;                 for (int bj = 0; bj < 2; ++bj) { f4 pre[2]; float xin[8]; unpack8(*(const u32x4*)(XB + off + 128 * bj), xin);
; #pragma unroll
;                     for (int n = 0; n < 2; ++n) { const f4 v = {xin[4 * n], xin[4 * n + 1], xin[4 * n + 2], xin[4 * n + 3]}; const f4 xr = (v * r + rm) * gv[bj][n] + bv[bj][n];
;                         pre[n] = xr * alpha + acc[ai][bj][m][n]; if (X) *(f4*)(X + off + 128 * bj + 4 * n) = pre[n];
;                         s1 += (pre[n][0] + pre[n][1]) + (pre[n][2] + pre[n][3]); s2 += (pre[n][0] * pre[n][0] + pre[n][1] * pre[n][1]) + (pre[n][2] * pre[n][2] + pre[n][3] * pre[n][3]); }
;                     u32x4 w; w.x = pk(pre[0][0], pre[0][1]); w.y = pk(pre[0][2], pre[0][3]); w.z = pk(pre[1][0], pre[1][1]); w.w = pk(pre[1][2], pre[1][3]);
;                     if (!X) *(u32x4*)(XB + off + 128 * bj) = w; }
;                 s1 += swz_xor<16>(s1); s2 += swz_xor<16>(s2);
;                 { auto r1 = __builtin_amdgcn_permlane32_swap(__float_as_uint(s1), __float_as_uint(s1), false, false); s1 = __uint_as_float(r1[0]) + __uint_as_float(r1[1]);
;                   auto r2 = __builtin_amdgcn_permlane32_swap(__float_as_uint(s2), __float_as_uint(s2), false, false); s2 = __uint_as_float(r2[0]) + __uint_as_float(r2[1]); }
;                 if (fq == 0) *(f2v*)(SPout + (size_t)(u.pm * 256 + rl) * 32 + (u.pn * 4 + wc) * 2) = (f2v){s1, s2};
.LBB0_919:
	s_nop 1
	v_add_f32_e32 v48, v44, v45
	v_mul_f32_e32 v45, v45, v45
	v_fmac_f32_e32 v45, v44, v44
	v_mul_f32_e32 v44, v46, v46
	v_fmac_f32_e32 v44, v47, v47
	v_add_f32_e32 v44, v45, v44
	v_add_f32_e32 v45, v40, v41
	v_mul_f32_e32 v41, v41, v41
	v_fmac_f32_e32 v41, v40, v40
	v_mul_f32_e32 v40, v42, v42
	v_fmac_f32_e32 v40, v43, v43
	v_add_f32_e32 v40, v41, v40
	v_add_f32_e32 v41, v36, v37
	v_mul_f32_e32 v37, v37, v37
	v_fmac_f32_e32 v37, v36, v36
	v_mul_f32_e32 v36, v38, v38
	v_add_f32_e32 v49, v47, v46
	v_fmac_f32_e32 v36, v39, v39
	v_add_f32_e32 v48, v48, v49
	v_add_f32_e32 v46, v43, v42
	v_add_f32_e32 v36, v37, v36
	v_add_f32_e32 v37, v32, v33
	v_mul_f32_e32 v33, v33, v33
	v_add_f32_e32 v48, 0, v48
	v_add_f32_e32 v45, v45, v46
	v_add_f32_e32 v42, v39, v38
	v_fmac_f32_e32 v33, v32, v32
	v_mul_f32_e32 v32, v34, v34
	v_add_f32_e32 v45, v45, v48
	v_add_f32_e32 v40, v44, v40
	v_add_f32_e32 v41, v41, v42
	v_add_f32_e32 v38, v35, v34
	v_fmac_f32_e32 v32, v35, v35
	v_add_f32_e32 v41, v45, v41
	v_add_f32_e32 v36, v40, v36
	v_add_f32_e32 v37, v37, v38
	v_add_f32_e32 v32, v33, v32
	v_add_f32_e32 v37, v37, v41
	v_add_f32_e32 v33, v32, v36
	ds_swizzle_b32 v32, v37 offset:swizzle(SWAP,16)
	ds_swizzle_b32 v34, v33 offset:swizzle(SWAP,16)
	s_waitcnt lgkmcnt(1)
	v_add_f32_e32 v32, v37, v32
	s_waitcnt lgkmcnt(0)
	v_add_f32_e32 v33, v33, v34
	v_mov_b32_e32 v34, v32
	v_mov_b32_e32 v35, v33
	s_nop 0
	v_permlane32_swap_b32_e32 v32, v34
	v_permlane32_swap_b32_e32 v33, v35
	s_and_saveexec_b64 s[0:1], s[42:43]
	s_cbranch_execz .LBB0_921
	v_add_f32_e64 v32, v32, v34
	v_add_f32_e64 v33, v33, v35
	v_lshlrev_b64 v[34:35], 7, v[52:53]
	v_lshl_add_u64 v[34:35], s[18:19], 0, v[34:35]
	v_lshl_add_u64 v[34:35], s[36:37], 2, v[34:35]
	global_store_dwordx2 v[34:35], v[32:33], off
.LBB0_921:
	s_or_b64 exec, exec, s[0:1]
	v_add_u32_e32 v36, s72, v207
	v_ashrrev_i32_e32 v37, 31, v36
	v_lshlrev_b64 v[32:33], 10, v[36:37]
	v_lshl_add_u64 v[40:41], v[32:33], 0, v[174:175]
	v_lshl_add_u64 v[38:39], v[40:41], 1, s[14:15]
	ds_read_b64 v[42:43], v216
	s_mov_b64 s[38:39], 0
	s_and_b64 vcc, exec, s[46:47]
	s_waitcnt lgkmcnt(0)
	v_mul_f32_e64 v44, v43, -v42
	s_waitcnt vmcnt(6)
	v_lshlrev_b32_e32 v46, 16, v222
	v_and_b32_e32 v47, 0xffff0000, v222
	v_lshlrev_b32_e32 v32, 16, v223
	v_and_b32_e32 v33, 0xffff0000, v223
	v_fma_f32 v32, v43, v32, v44
	v_fma_f32 v33, v43, v33, v44
	v_fma_f32 v46, v43, v46, v44
	v_fma_f32 v47, v43, v47, v44
	v_fma_f32 v32, v90, v32, v94
	v_fma_f32 v33, v91, v33, v95
	v_fma_f32 v46, v88, v46, v92
	v_fma_f32 v47, v89, v47, v93
	v_fma_f32 v30, v32, s10, v30
	v_fma_f32 v31, v33, s10, v31
	v_fma_f32 v28, v46, s10, v28
	v_fma_f32 v29, v47, s10, v29
	v_lshl_add_u64 v[46:47], v[40:41], 2, s[52:53]
	s_cbranch_vccnz .LBB0_923
	s_mov_b64 s[38:39], s[52:53]
	global_store_dwordx4 v[46:47], v[28:31], off
.LBB0_923:
	v_mov_b32_e32 v42, v43
	v_mov_b32_e32 v45, v44
	v_lshlrev_b32_e32 v32, 16, v224
	v_and_b32_e32 v33, 0xffff0000, v224
	v_lshlrev_b32_e32 v34, 16, v225
	v_and_b32_e32 v35, 0xffff0000, v225
	v_mov_b32_e32 v48, v44
	v_mov_b32_e32 v49, v44
	v_mov_b32_e32 v50, v43
	v_mov_b32_e32 v51, v43
	v_fma_f32 v34, v50, v34, v48
	v_fma_f32 v35, v51, v35, v49
	v_fma_f32 v32, v42, v32, v44
	v_fma_f32 v33, v43, v33, v45
	v_fma_f32 v34, v78, v34, v82
	v_fma_f32 v35, v79, v35, v83
	v_fma_f32 v32, v76, v32, v80
	v_fma_f32 v33, v77, v33, v81
	v_fma_f32 v26, v34, s10, v26
	v_fma_f32 v27, v35, s10, v27
	s_cmp_eq_u64 s[38:39], 0
	v_fma_f32 v24, v32, s10, v24
	v_fma_f32 v25, v33, s10, v25
	s_cbranch_scc1 .LBB0_925
	v_lshl_add_u64 v[32:33], v[40:41], 2, s[38:39]
	global_store_dwordx4 v[32:33], v[24:27], off offset:16

;     __device__ __forceinline__ void operator()(pg8::f32x4 (&acc)[2][2][4][2], const pg8::Unit& u, int wr, int wc, int fr, int fq) const {
;     ...
;             for (int m = 0; m < 4; ++m) { const int rl = ai * 128 + wr * 64 + m * 16 + fr; const f2v st = T[rl]; const float r = st.y, rm = -st.x * st.y;
;                 const size_t off = (size_t)(u.pm * 256 + rl) * DM + cb; float s1 = 0.f, s2 = 0.f;
; #pragma unroll
;                 for (int bj = 0; bj < 2; ++bj) { f4 pre[2]; float xin[8]; unpack8(*(const u32x4*)(XB + off + 128 * bj), xin);
; #pragma unroll
;                     for (int n = 0; n < 2; ++n) { const f4 v = {xin[4 * n], xin[4 * n + 1], xin[4 * n + 2], xin[4 * n + 3]}; const f4 xr = (v * r + rm) * gv[bj][n] + bv[bj][n];
;                         pre[n] = xr * alpha + acc[ai][bj][m][n]; if (X) *(f4*)(X + off + 128 * bj + 4 * n) = pre[n];
;                         s1 += (pre[n][0] + pre[n][1]) + (pre[n][2] + pre[n][3]); s2 += (pre[n][0] * pre[n][0] + pre[n][1] * pre[n][1]) + (pre[n][2] * pre[n][2] + pre[n][3] * pre[n][3]); }
.LBB0_927:
	v_mov_b32_e32 v48, v44
	v_mov_b32_e32 v49, v44
	v_mov_b32_e32 v50, v43
	v_mov_b32_e32 v51, v43
	s_and_b64 vcc, exec, s[46:47]
	s_mov_b64 s[4:5], 0
	s_waitcnt vmcnt(6)
	v_lshlrev_b32_e32 v52, 16, v226
	v_and_b32_e32 v53, 0xffff0000, v226
	v_lshlrev_b32_e32 v32, 16, v227
	v_and_b32_e32 v33, 0xffff0000, v227
	v_fma_f32 v32, v50, v32, v48
	v_fma_f32 v33, v51, v33, v49
	v_fma_f32 v52, v42, v52, v44
	v_fma_f32 v53, v43, v53, v45
	v_fma_f32 v32, v66, v32, v70
	v_fma_f32 v33, v67, v33, v71
	v_fma_f32 v52, v64, v52, v68
	v_fma_f32 v53, v65, v53, v69
	v_fma_f32 v22, v32, s10, v22
	v_fma_f32 v23, v33, s10, v23
	v_fma_f32 v20, v52, s10, v20
	v_fma_f32 v21, v53, s10, v21
	s_cbranch_vccnz .LBB0_929
	s_mov_b64 s[4:5], s[52:53]
	global_store_dwordx4 v[46:47], v[20:23], off offset:512
.LBB0_929:
	v_lshlrev_b32_e32 v32, 16, v228
	v_and_b32_e32 v33, 0xffff0000, v228
	v_lshlrev_b32_e32 v34, 16, v229
	v_and_b32_e32 v35, 0xffff0000, v229
	v_fma_f32 v34, v50, v34, v48
	v_fma_f32 v35, v51, v35, v49
	v_fma_f32 v32, v42, v32, v44
	v_fma_f32 v33, v43, v33, v45
	v_fma_f32 v34, v58, v34, v62
	v_fma_f32 v35, v59, v35, v63
	v_fma_f32 v32, v56, v32, v60
	v_fma_f32 v33, v57, v33, v61
	v_fma_f32 v18, v34, s10, v18
	v_fma_f32 v19, v35, s10, v19
	s_cmp_eq_u64 s[4:5], 0
	v_fma_f32 v16, v32, s10, v16
	v_fma_f32 v17, v33, s10, v17
	s_cbranch_scc1 .LBB0_931
	v_lshl_add_u64 v[32:33], v[40:41], 2, s[4:5]
	global_store_dwordx4 v[32:33], v[16:19], off offset:528

; __device__ __forceinline__ unsigned pk(float lo, float hi) { return pg8::cvt_pk_bf16(lo, hi); }
; template <int O> __device__ __forceinline__ float swz_xor(float v) { return __int_as_float(__builtin_amdgcn_ds_swizzle(__float_as_int(v), (O << 10) | 0x1f)); }
;     __device__ __forceinline__ void operator()(pg8::f32x4 (&acc)[2][2][4][2], const pg8::Unit& u, int wr, int wc, int fr, int fq) const {
;     ...
;             for (int m = 0; m < 4; ++m) { const int rl = ai * 128 + wr * 64 + m * 16 + fr; const f2v st = T[rl]; const float r = st.y, rm = -st.x * st.y;
;                 const size_t off = (size_t)(u.pm * 256 + rl) * DM + cb; float s1 = 0.f, s2 = 0.f;
; #pragma unroll
;                 for (int bj = 0; bj < 2; ++bj) { f4 pre[2]; float xin[8]; unpack8(*(const u32x4*)(XB + off + 128 * bj), xin);
; #pragma unroll
;                     for (int n = 0; n < 2; ++n) { const f4 v = {xin[4 * n], xin[4 * n + 1], xin[4 * n + 2], xin[4 * n + 3]}; const f4 xr = (v * r + rm) * gv[bj][n] + bv[bj][n];
;                         pre[n] = xr * alpha + acc[ai][bj][m][n]; if (X) *(f4*)(X + off + 128 * bj + 4 * n) = pre[n];
;                         s1 += (pre[n][0] + pre[n][1]) + (pre[n][2] + pre[n][3]); s2 += (pre[n][0] * pre[n][0] + pre[n][1] * pre[n][1]) + (pre[n][2] * pre[n][2] + pre[n][3] * pre[n][3]); }
;                     u32x4 w; w.x = pk(pre[0][0], pre[0][1]); w.y = pk(pre[0][2], pre[0][3]); w.z = pk(pre[1][0], pre[1][1]); w.w = pk(pre[1][2], pre[1][3]);
;                     if (!X) *(u32x4*)(XB + off + 128 * bj) = w; }
;                 s1 += swz_xor<16>(s1); s2 += swz_xor<16>(s2);
;                 { auto r1 = __builtin_amdgcn_permlane32_swap(__float_as_uint(s1), __float_as_uint(s1), false, false); s1 = __uint_as_float(r1[0]) + __uint_as_float(r1[1]);
;                   auto r2 = __builtin_amdgcn_permlane32_swap(__float_as_uint(s2), __float_as_uint(s2), false, false); s2 = __uint_as_float(r2[0]) + __uint_as_float(r2[1]); }
;                 if (fq == 0) *(f2v*)(SPout + (size_t)(u.pm * 256 + rl) * 32 + (u.pn * 4 + wc) * 2) = (f2v){s1, s2};
.LBB0_933:
	s_nop 1
	v_add_f32_e32 v32, v28, v29
	v_mul_f32_e32 v29, v29, v29
	v_fmac_f32_e32 v29, v28, v28
	v_mul_f32_e32 v28, v30, v30
	v_fmac_f32_e32 v28, v31, v31
	v_add_f32_e32 v28, v29, v28
	v_add_f32_e32 v29, v24, v25
	v_mul_f32_e32 v25, v25, v25
	v_fmac_f32_e32 v25, v24, v24
	v_mul_f32_e32 v24, v26, v26
	v_fmac_f32_e32 v24, v27, v27
	v_add_f32_e32 v24, v25, v24
	v_add_f32_e32 v25, v20, v21
	v_mul_f32_e32 v21, v21, v21
	v_fmac_f32_e32 v21, v20, v20
	v_mul_f32_e32 v20, v22, v22
	v_add_f32_e32 v33, v31, v30
	v_fmac_f32_e32 v20, v23, v23
	v_add_f32_e32 v32, v32, v33
	v_add_f32_e32 v30, v27, v26
	v_add_f32_e32 v20, v21, v20
	v_add_f32_e32 v21, v16, v17
	v_mul_f32_e32 v17, v17, v17
	v_add_f32_e32 v32, 0, v32
	v_add_f32_e32 v29, v29, v30
	v_add_f32_e32 v26, v23, v22
	v_fmac_f32_e32 v17, v16, v16
	v_mul_f32_e32 v16, v18, v18
	v_add_f32_e32 v29, v29, v32
	v_add_f32_e32 v24, v28, v24
	v_add_f32_e32 v25, v25, v26
	v_add_f32_e32 v22, v19, v18
	v_fmac_f32_e32 v16, v19, v19
	v_add_f32_e32 v25, v29, v25
	v_add_f32_e32 v20, v24, v20
	v_add_f32_e32 v21, v21, v22
	v_add_f32_e32 v16, v17, v16
	v_add_f32_e32 v21, v21, v25
	v_add_f32_e32 v17, v16, v20
	ds_swizzle_b32 v16, v21 offset:swizzle(SWAP,16)
	ds_swizzle_b32 v18, v17 offset:swizzle(SWAP,16)
	s_waitcnt lgkmcnt(1)
	v_add_f32_e32 v16, v21, v16
	s_waitcnt lgkmcnt(0)
	v_add_f32_e32 v17, v17, v18
	v_mov_b32_e32 v18, v16
	v_mov_b32_e32 v19, v17
	s_nop 0
	v_permlane32_swap_b32_e32 v16, v18
	v_permlane32_swap_b32_e32 v17, v19
	s_and_saveexec_b64 s[0:1], s[42:43]
	s_cbranch_execz .LBB0_935
	v_add_f32_e64 v16, v16, v18
	v_add_f32_e64 v17, v17, v19
	v_lshlrev_b64 v[18:19], 7, v[36:37]
	v_lshl_add_u64 v[18:19], s[18:19], 0, v[18:19]
	v_lshl_add_u64 v[18:19], s[36:37], 2, v[18:19]
	global_store_dwordx2 v[18:19], v[16:17], off
.LBB0_935:
	s_or_b64 exec, exec, s[0:1]
	v_add_u32_e32 v20, s72, v208
	v_ashrrev_i32_e32 v21, 31, v20
	v_lshlrev_b64 v[16:17], 10, v[20:21]
	v_lshl_add_u64 v[24:25], v[16:17], 0, v[174:175]
	v_lshl_add_u64 v[22:23], v[24:25], 1, s[14:15]
	ds_read_b64 v[26:27], v217
	s_mov_b64 s[38:39], 0
	s_and_b64 vcc, exec, s[46:47]
	s_waitcnt lgkmcnt(0)
	v_mul_f32_e64 v28, v27, -v26
	s_waitcnt vmcnt(4)
	v_lshlrev_b32_e32 v30, 16, v238
	v_and_b32_e32 v31, 0xffff0000, v238
	v_lshlrev_b32_e32 v16, 16, v239
	v_and_b32_e32 v17, 0xffff0000, v239
	v_fma_f32 v16, v27, v16, v28
	v_fma_f32 v17, v27, v17, v28
	v_fma_f32 v30, v27, v30, v28
	v_fma_f32 v31, v27, v31, v28
	v_fma_f32 v16, v90, v16, v94
	v_fma_f32 v17, v91, v17, v95
	v_fma_f32 v30, v88, v30, v92
	v_fma_f32 v31, v89, v31, v93
	v_fma_f32 v14, v16, s10, v14
	v_fma_f32 v15, v17, s10, v15
	v_fma_f32 v12, v30, s10, v12
	v_fma_f32 v13, v31, s10, v13
	v_lshl_add_u64 v[30:31], v[24:25], 2, s[52:53]
	s_cbranch_vccnz .LBB0_937
	s_mov_b64 s[38:39], s[52:53]
	global_store_dwordx4 v[30:31], v[12:15], off
.LBB0_937:
	v_mov_b32_e32 v26, v27
	v_mov_b32_e32 v29, v28
	v_lshlrev_b32_e32 v16, 16, v240
	v_and_b32_e32 v17, 0xffff0000, v240
	v_lshlrev_b32_e32 v18, 16, v241
	v_and_b32_e32 v19, 0xffff0000, v241
	v_mov_b32_e32 v32, v28
	v_mov_b32_e32 v33, v28
	v_mov_b32_e32 v34, v27
	v_mov_b32_e32 v35, v27
	v_fma_f32 v18, v34, v18, v32
	v_fma_f32 v19, v35, v19, v33
	v_fma_f32 v16, v26, v16, v28
	v_fma_f32 v17, v27, v17, v29
	v_fma_f32 v18, v78, v18, v82
	v_fma_f32 v19, v79, v19, v83
	v_fma_f32 v16, v76, v16, v80
	v_fma_f32 v17, v77, v17, v81
	v_fma_f32 v10, v18, s10, v10
	v_fma_f32 v11, v19, s10, v11
	s_cmp_eq_u64 s[38:39], 0
	v_fma_f32 v8, v16, s10, v8
	v_fma_f32 v9, v17, s10, v9
	s_cbranch_scc1 .LBB0_939
	v_lshl_add_u64 v[16:17], v[24:25], 2, s[38:39]
	global_store_dwordx4 v[16:17], v[8:11], off offset:16

;     __device__ __forceinline__ void operator()(pg8::f32x4 (&acc)[2][2][4][2], const pg8::Unit& u, int wr, int wc, int fr, int fq) const {
;     ...
;                 for (int bj = 0; bj < 2; ++bj) { f4 pre[2]; float xin[8]; unpack8(*(const u32x4*)(XB + off + 128 * bj), xin);
; #pragma unroll
;                     for (int n = 0; n < 2; ++n) { const f4 v = {xin[4 * n], xin[4 * n + 1], xin[4 * n + 2], xin[4 * n + 3]}; const f4 xr = (v * r + rm) * gv[bj][n] + bv[bj][n];
;                         pre[n] = xr * alpha + acc[ai][bj][m][n]; if (X) *(f4*)(X + off + 128 * bj + 4 * n) = pre[n];
;                         s1 += (pre[n][0] + pre[n][1]) + (pre[n][2] + pre[n][3]); s2 += (pre[n][0] * pre[n][0] + pre[n][1] * pre[n][1]) + (pre[n][2] * pre[n][2] + pre[n][3] * pre[n][3]); }
.LBB0_941:
	v_mov_b32_e32 v32, v28
	v_mov_b32_e32 v33, v28
	v_mov_b32_e32 v34, v27
	v_mov_b32_e32 v35, v27
	s_and_b64 vcc, exec, s[46:47]
	s_mov_b64 s[4:5], 0
	s_waitcnt vmcnt(4)
	v_lshlrev_b32_e32 v36, 16, v242
	v_and_b32_e32 v37, 0xffff0000, v242
	v_lshlrev_b32_e32 v16, 16, v243
	v_and_b32_e32 v17, 0xffff0000, v243
	v_fma_f32 v16, v34, v16, v32
	v_fma_f32 v17, v35, v17, v33
	v_fma_f32 v36, v26, v36, v28
	v_fma_f32 v37, v27, v37, v29
	v_fma_f32 v16, v66, v16, v70
	v_fma_f32 v17, v67, v17, v71
	v_fma_f32 v36, v64, v36, v68
	v_fma_f32 v37, v65, v37, v69
	v_fma_f32 v6, v16, s10, v6
	v_fma_f32 v7, v17, s10, v7
	v_fma_f32 v4, v36, s10, v4
	v_fma_f32 v5, v37, s10, v5
	s_cbranch_vccnz .LBB0_943
	s_mov_b64 s[4:5], s[52:53]
	global_store_dwordx4 v[30:31], v[4:7], off offset:512
.LBB0_943:
	v_lshlrev_b32_e32 v16, 16, v244
	v_and_b32_e32 v17, 0xffff0000, v244
	v_lshlrev_b32_e32 v18, 16, v245
	v_and_b32_e32 v19, 0xffff0000, v245
	v_fma_f32 v18, v34, v18, v32
	v_fma_f32 v19, v35, v19, v33
	v_fma_f32 v16, v26, v16, v28
	v_fma_f32 v17, v27, v17, v29
	v_fma_f32 v18, v58, v18, v62
	v_fma_f32 v19, v59, v19, v63
	v_fma_f32 v16, v56, v16, v60
	v_fma_f32 v17, v57, v17, v61
	v_fma_f32 v2, v18, s10, v2
	v_fma_f32 v3, v19, s10, v3
	s_cmp_eq_u64 s[4:5], 0
	v_fma_f32 v0, v16, s10, v0
	v_fma_f32 v1, v17, s10, v1
	s_cbranch_scc1 .LBB0_945
	v_lshl_add_u64 v[16:17], v[24:25], 2, s[4:5]
	global_store_dwordx4 v[16:17], v[0:3], off offset:528

; __device__ __forceinline__ unsigned pk(float lo, float hi) { return pg8::cvt_pk_bf16(lo, hi); }
; template <int O> __device__ __forceinline__ float swz_xor(float v) { return __int_as_float(__builtin_amdgcn_ds_swizzle(__float_as_int(v), (O << 10) | 0x1f)); }
;     __device__ __forceinline__ void operator()(pg8::f32x4 (&acc)[2][2][4][2], const pg8::Unit& u, int wr, int wc, int fr, int fq) const {
;     ...
;                         s1 += (pre[n][0] + pre[n][1]) + (pre[n][2] + pre[n][3]); s2 += (pre[n][0] * pre[n][0] + pre[n][1] * pre[n][1]) + (pre[n][2] * pre[n][2] + pre[n][3] * pre[n][3]); }
;                     u32x4 w; w.x = pk(pre[0][0], pre[0][1]); w.y = pk(pre[0][2], pre[0][3]); w.z = pk(pre[1][0], pre[1][1]); w.w = pk(pre[1][2], pre[1][3]);
;                     if (!X) *(u32x4*)(XB + off + 128 * bj) = w; }
;                 s1 += swz_xor<16>(s1); s2 += swz_xor<16>(s2);
;                 { auto r1 = __builtin_amdgcn_permlane32_swap(__float_as_uint(s1), __float_as_uint(s1), false, false); s1 = __uint_as_float(r1[0]) + __uint_as_float(r1[1]);
;                   auto r2 = __builtin_amdgcn_permlane32_swap(__float_as_uint(s2), __float_as_uint(s2), false, false); s2 = __uint_as_float(r2[0]) + __uint_as_float(r2[1]); }
;                 if (fq == 0) *(f2v*)(SPout + (size_t)(u.pm * 256 + rl) * 32 + (u.pn * 4 + wc) * 2) = (f2v){s1, s2};
.LBB0_947:
	s_nop 1
	v_add_f32_e32 v16, v12, v13
	v_mul_f32_e32 v13, v13, v13
	v_fmac_f32_e32 v13, v12, v12
	v_mul_f32_e32 v12, v14, v14
	v_fmac_f32_e32 v12, v15, v15
	v_add_f32_e32 v12, v13, v12
	v_add_f32_e32 v13, v8, v9
	v_mul_f32_e32 v9, v9, v9
	v_fmac_f32_e32 v9, v8, v8
	v_mul_f32_e32 v8, v10, v10
	v_fmac_f32_e32 v8, v11, v11
	v_add_f32_e32 v8, v9, v8
	v_add_f32_e32 v9, v4, v5
	v_mul_f32_e32 v5, v5, v5
	v_fmac_f32_e32 v5, v4, v4
	v_mul_f32_e32 v4, v6, v6
	v_add_f32_e32 v17, v15, v14
	v_fmac_f32_e32 v4, v7, v7
	v_add_f32_e32 v16, v16, v17
	v_add_f32_e32 v14, v11, v10
	v_add_f32_e32 v4, v5, v4
	v_add_f32_e32 v5, v0, v1
	v_mul_f32_e32 v1, v1, v1
	v_add_f32_e32 v16, 0, v16
	v_add_f32_e32 v13, v13, v14
	v_add_f32_e32 v10, v7, v6
	v_fmac_f32_e32 v1, v0, v0
	v_mul_f32_e32 v0, v2, v2
	v_add_f32_e32 v13, v13, v16
	v_add_f32_e32 v8, v12, v8
	v_add_f32_e32 v9, v9, v10
	v_add_f32_e32 v6, v3, v2
	v_fmac_f32_e32 v0, v3, v3
	v_add_f32_e32 v9, v13, v9
	v_add_f32_e32 v4, v8, v4
	v_add_f32_e32 v5, v5, v6
	v_add_f32_e32 v0, v1, v0
	v_add_f32_e32 v5, v5, v9
	v_add_f32_e32 v1, v0, v4
	ds_swizzle_b32 v0, v5 offset:swizzle(SWAP,16)
	ds_swizzle_b32 v2, v1 offset:swizzle(SWAP,16)
	s_waitcnt lgkmcnt(1)
	v_add_f32_e32 v0, v5, v0
	s_waitcnt lgkmcnt(0)
	v_add_f32_e32 v1, v1, v2
	v_mov_b32_e32 v2, v0
	v_mov_b32_e32 v3, v1
	s_nop 0
	v_permlane32_swap_b32_e32 v0, v2
	v_permlane32_swap_b32_e32 v1, v3
	s_and_saveexec_b64 s[0:1], s[42:43]
	s_cbranch_execz .LBB0_949
	v_add_f32_e64 v0, v0, v2
	v_add_f32_e64 v1, v1, v3
	v_lshlrev_b64 v[2:3], 7, v[20:21]
	v_lshl_add_u64 v[2:3], s[18:19], 0, v[2:3]
	v_lshl_add_u64 v[2:3], s[36:37], 2, v[2:3]
	global_store_dwordx2 v[2:3], v[0:1], off
